# waitcnt lever on GEMM MFMA head: 32 redundant post-barrier lgkmcnt(0) removed (already drained by the pre-barrier wait), on top of noprio+nonop
# speedup vs baseline: 1.0126x; 1.0126x over previous
; #define PG8_STAGE(bufoff, gbase, voff) do { _Pragma("unroll") for (int _i = 0; _i < 2; ++_i) \
;         __builtin_amdgcn_global_load_lds((const unsigned*)((const char*)(gbase) + (voff)[_i]), (LAS unsigned*)(lds + (bufoff) + ldsw + _i * 8192), 16, 0, 0); } while (0)
; #define PG8_LDA(dst, b, h) do { _Pragma("unroll") for (int m = 0; m < 4; ++m) _Pragma("unroll") for (int k = 0; k < 2; ++k) dst[m][k] = *(const LAS bf16x8*)(lds + PG8_SA(b, h) + aoff + m * 2048 + k * 1024); } while (0)
; #define PG8_LDB(dst, b, h) do { _Pragma("unroll") for (int n = 0; n < 2; ++n) _Pragma("unroll") for (int k = 0; k < 2; ++k) dst[n][k] = *(const LAS bf16x8*)(lds + PG8_SB(b, h) + boff + n * 2048 + k * 1024); } while (0)
; #define PG8_MMA(ai, bj, At, Bt) do { __builtin_amdgcn_s_setprio(1); _Pragma("unroll") for (int m = 0; m < 4; ++m) _Pragma("unroll") for (int n = 0; n < 2; ++n) _Pragma("unroll") for (int k = 0; k < 2; ++k) \
;         acc[ai][bj][m][n] = __builtin_amdgcn_mfma_f32_16x16x32_bf16(Bt[n][k], At[m][k], acc[ai][bj][m][n], 0, 0, 0); __builtin_amdgcn_s_setprio(0); } while (0)
; #define PG8_WAIT_V(n) asm volatile("s_waitcnt vmcnt(" #n ")" ::: "memory")
; #define PG8_WAIT_L(n) asm volatile("s_waitcnt lgkmcnt(" #n ")" ::: "memory")
; #define PG8_BAR __builtin_amdgcn_s_barrier()
; #define PG8_SCHED __builtin_amdgcn_sched_barrier(0)
; template <class Epi, class Sched, bool ALIGN_EPI = true>
; __device__ __forceinline__ void gemm_phase(LAS unsigned char* lds, const Gemm g, const Sched& S, const Epi& E) {
;     ...
;             const char* a1 = cA + (size_t)(t + 1) * kstep;
;             const char* a2 = last ? nA : cA + (size_t)(t + 2) * kstep; const char* b2 = last ? nB : cB + (size_t)(t + 2) * kstep;
;             const char* a3 = a2 + kstep; const char* b3 = b2 + kstep;
;             PG8_LDB(B0, 0, 0); PG8_LDB(B1, 0, 1); PG8_SCHED; PG8_LDA(At, 0, 0); PG8_STAGE(PG8_SA(1, 1), a1 + hstep, voffA);
;             PG8_WAIT_V(8); PG8_WAIT_L(0); PG8_BAR; PG8_MMA(0, 0, At, B0); PG8_MMA(0, 1, At, B1); PG8_BAR; PG8_SCHED;
;             PG8_LDA(At, 0, 1); PG8_STAGE(PG8_SB(0, 0), b2, voffB); PG8_STAGE(PG8_SB(0, 1), b2 + hstep, voffB); PG8_STAGE(PG8_SA(0, 0), a2, voffA);
.LBB0_195:
	v_add_u32_e32 v136, s78, v169
	ds_read_b128 v[172:175], v136
	ds_read_b128 v[180:183], v136 offset:1024
	ds_read_b128 v[184:187], v136 offset:2048
	ds_read_b128 v[188:191], v136 offset:3072
	v_add_u32_e32 v136, s79, v169
	ds_read_b128 v[192:195], v136
	ds_read_b128 v[196:199], v136 offset:1024
	ds_read_b128 v[204:207], v136 offset:2048
	ds_read_b128 v[208:211], v136 offset:3072
	s_add_u32 s36, s34, 0xfff80080
	s_addc_u32 s37, s35, -1
	s_cmp_eq_u32 s89, 28
	s_cselect_b32 s39, s84, s37
	s_cselect_b32 s38, s85, s36
	s_cselect_b32 s37, s9, s88
	s_cselect_b32 s36, s86, s87
	v_lshl_add_u64 v[164:165], s[34:35], 0, v[160:161]
	s_add_i32 m0, s44, 0xc000
	ds_read_b128 v[212:215], v171
	ds_read_b128 v[216:219], v171 offset:1024
	ds_read_b128 v[220:223], v171 offset:2048
	ds_read_b128 v[224:227], v171 offset:3072
	ds_read_b128 v[228:231], v171 offset:4096
	ds_read_b128 v[232:235], v171 offset:5120
	ds_read_b128 v[236:239], v171 offset:6144
	ds_read_b128 v[240:243], v171 offset:7168
	global_load_lds_dwordx4 v[164:165], off
	s_add_i32 m0, s44, 0xe000
	v_lshl_add_u64 v[164:165], s[34:35], 0, v[162:163]
	global_load_lds_dwordx4 v[164:165], off
	s_waitcnt vmcnt(8)
	s_waitcnt lgkmcnt(0)
	s_barrier
	v_mfma_f32_16x16x32_bf16 v[124:127], v[172:175], v[212:215], v[124:127]
	v_mfma_f32_16x16x32_bf16 v[120:123], v[184:187], v[212:215], v[120:123]
	v_mfma_f32_16x16x32_bf16 v[108:111], v[172:175], v[220:223], v[108:111]
	v_mfma_f32_16x16x32_bf16 v[104:107], v[184:187], v[220:223], v[104:107]
	v_mfma_f32_16x16x32_bf16 v[92:95], v[172:175], v[228:231], v[92:95]
	v_mfma_f32_16x16x32_bf16 v[88:91], v[184:187], v[228:231], v[88:91]
	v_mfma_f32_16x16x32_bf16 v[76:79], v[172:175], v[236:239], v[76:79]
	v_mfma_f32_16x16x32_bf16 v[72:75], v[184:187], v[236:239], v[72:75]
	v_mfma_f32_16x16x32_bf16 v[124:127], v[180:183], v[216:219], v[124:127]
	v_mfma_f32_16x16x32_bf16 v[120:123], v[188:191], v[216:219], v[120:123]
	v_mfma_f32_16x16x32_bf16 v[108:111], v[180:183], v[224:227], v[108:111]
	v_mfma_f32_16x16x32_bf16 v[104:107], v[188:191], v[224:227], v[104:107]
	v_mfma_f32_16x16x32_bf16 v[92:95], v[180:183], v[232:235], v[92:95]
	v_mfma_f32_16x16x32_bf16 v[88:91], v[188:191], v[232:235], v[88:91]
	v_mfma_f32_16x16x32_bf16 v[76:79], v[180:183], v[240:243], v[76:79]
	v_mfma_f32_16x16x32_bf16 v[72:75], v[188:191], v[240:243], v[72:75]
	v_mfma_f32_16x16x32_bf16 v[116:119], v[192:195], v[212:215], v[116:119]
	v_mfma_f32_16x16x32_bf16 v[112:115], v[204:207], v[212:215], v[112:115]
	v_mfma_f32_16x16x32_bf16 v[100:103], v[192:195], v[220:223], v[100:103]
	v_mfma_f32_16x16x32_bf16 v[96:99], v[204:207], v[220:223], v[96:99]
	v_mfma_f32_16x16x32_bf16 v[84:87], v[192:195], v[228:231], v[84:87]
	v_mfma_f32_16x16x32_bf16 v[80:83], v[204:207], v[228:231], v[80:83]
	v_mfma_f32_16x16x32_bf16 v[68:71], v[192:195], v[236:239], v[68:71]
	v_mfma_f32_16x16x32_bf16 v[64:67], v[204:207], v[236:239], v[64:67]
	v_mfma_f32_16x16x32_bf16 v[116:119], v[196:199], v[216:219], v[116:119]
	v_mfma_f32_16x16x32_bf16 v[112:115], v[208:211], v[216:219], v[112:115]
	v_mfma_f32_16x16x32_bf16 v[100:103], v[196:199], v[224:227], v[100:103]
	v_mfma_f32_16x16x32_bf16 v[96:99], v[208:211], v[224:227], v[96:99]
	v_mfma_f32_16x16x32_bf16 v[84:87], v[196:199], v[232:235], v[84:87]
	v_mfma_f32_16x16x32_bf16 v[80:83], v[208:211], v[232:235], v[80:83]
	v_mfma_f32_16x16x32_bf16 v[68:71], v[196:199], v[240:243], v[68:71]
	v_mfma_f32_16x16x32_bf16 v[64:67], v[208:211], v[240:243], v[64:67]
	s_barrier
	s_add_i32 s46, s78, s42
	v_lshl_add_u64 v[164:165], s[36:37], 0, v[130:131]
	s_mov_b32 m0, s46
	ds_read_b128 v[212:215], v171 offset:16384
	ds_read_b128 v[216:219], v171 offset:17408
	ds_read_b128 v[220:223], v171 offset:18432
	ds_read_b128 v[224:227], v171 offset:19456
	ds_read_b128 v[228:231], v171 offset:20480
	ds_read_b128 v[232:235], v171 offset:21504
	ds_read_b128 v[236:239], v171 offset:22528
	ds_read_b128 v[240:243], v171 offset:23552
	global_load_lds_dwordx4 v[164:165], off
	s_add_i32 m0, s46, 0x2000
	s_add_u32 s90, s36, 0x80000
	v_lshl_add_u64 v[176:177], s[36:37], 0, v[134:135]
	s_addc_u32 s91, s37, 0
	s_add_i32 s46, s79, s42
	global_load_lds_dwordx4 v[176:177], off
	v_lshl_add_u64 v[200:201], s[90:91], 0, v[130:131]
	s_mov_b32 m0, s46
	v_lshl_add_u64 v[244:245], s[38:39], 0, v[132:133]
	global_load_lds_dwordx4 v[200:201], off
	s_add_i32 m0, s46, 0x2000
	v_lshl_add_u64 v[200:201], s[90:91], 0, v[134:135]
	global_load_lds_dwordx4 v[200:201], off
	s_mov_b32 m0, s44
	v_lshl_add_u64 v[200:201], s[38:39], 0, v[128:129]
	global_load_lds_dwordx4 v[200:201], off
	s_mov_b32 m0, s50
	s_nop 0
	global_load_lds_dwordx4 v[244:245], off
	s_waitcnt vmcnt(8)
	s_waitcnt lgkmcnt(0)
	s_barrier
; #define PG8_STAGE(bufoff, gbase, voff) do { _Pragma("unroll") for (int _i = 0; _i < 2; ++_i) \
;         __builtin_amdgcn_global_load_lds((const unsigned*)((const char*)(gbase) + (voff)[_i]), (LAS unsigned*)(lds + (bufoff) + ldsw + _i * 8192), 16, 0, 0); } while (0)
; #define PG8_LDA(dst, b, h) do { _Pragma("unroll") for (int m = 0; m < 4; ++m) _Pragma("unroll") for (int k = 0; k < 2; ++k) dst[m][k] = *(const LAS bf16x8*)(lds + PG8_SA(b, h) + aoff + m * 2048 + k * 1024); } while (0)
; #define PG8_LDB(dst, b, h) do { _Pragma("unroll") for (int n = 0; n < 2; ++n) _Pragma("unroll") for (int k = 0; k < 2; ++k) dst[n][k] = *(const LAS bf16x8*)(lds + PG8_SB(b, h) + boff + n * 2048 + k * 1024); } while (0)
; #define PG8_MMA(ai, bj, At, Bt) do { __builtin_amdgcn_s_setprio(1); _Pragma("unroll") for (int m = 0; m < 4; ++m) _Pragma("unroll") for (int n = 0; n < 2; ++n) _Pragma("unroll") for (int k = 0; k < 2; ++k) \
;         acc[ai][bj][m][n] = __builtin_amdgcn_mfma_f32_16x16x32_bf16(Bt[n][k], At[m][k], acc[ai][bj][m][n], 0, 0, 0); __builtin_amdgcn_s_setprio(0); } while (0)
; #define PG8_WAIT_V(n) asm volatile("s_waitcnt vmcnt(" #n ")" ::: "memory")
; #define PG8_WAIT_L(n) asm volatile("s_waitcnt lgkmcnt(" #n ")" ::: "memory")
; #define PG8_BAR __builtin_amdgcn_s_barrier()
; #define PG8_SCHED __builtin_amdgcn_sched_barrier(0)
; template <class Epi, class Sched, bool ALIGN_EPI = true>
; __device__ __forceinline__ void gemm_phase(LAS unsigned char* lds, const Gemm g, const Sched& S, const Epi& E) {
;     ...
;             PG8_WAIT_V(8); PG8_WAIT_L(0); PG8_BAR; PG8_MMA(1, 0, At, B0); PG8_MMA(1, 1, At, B1); PG8_BAR; PG8_SCHED;
;             PG8_LDB(B0, 1, 0); PG8_LDB(B1, 1, 1); PG8_SCHED; PG8_LDA(At, 1, 0); PG8_STAGE(PG8_SA(0, 1), a2 + hstep, voffA);
;             PG8_WAIT_V(8); PG8_WAIT_L(0); PG8_BAR; PG8_MMA(0, 0, At, B0); PG8_MMA(0, 1, At, B1); PG8_BAR; PG8_SCHED;
;             PG8_LDA(At, 1, 1); PG8_STAGE(PG8_SB(1, 0), b3, voffB); PG8_STAGE(PG8_SB(1, 1), b3 + hstep, voffB); PG8_STAGE(PG8_SA(1, 0), a3, voffA);
	v_mfma_f32_16x16x32_bf16 v[60:63], v[172:175], v[212:215], v[60:63]
	v_mfma_f32_16x16x32_bf16 v[56:59], v[184:187], v[212:215], v[56:59]
	v_mfma_f32_16x16x32_bf16 v[44:47], v[172:175], v[220:223], v[44:47]
	v_mfma_f32_16x16x32_bf16 v[40:43], v[184:187], v[220:223], v[40:43]
	v_mfma_f32_16x16x32_bf16 v[28:31], v[172:175], v[228:231], v[28:31]
	v_mfma_f32_16x16x32_bf16 v[24:27], v[184:187], v[228:231], v[24:27]
	v_mfma_f32_16x16x32_bf16 v[12:15], v[172:175], v[236:239], v[12:15]
	v_mfma_f32_16x16x32_bf16 v[8:11], v[184:187], v[236:239], v[8:11]
	v_mfma_f32_16x16x32_bf16 v[60:63], v[180:183], v[216:219], v[60:63]
	v_mfma_f32_16x16x32_bf16 v[56:59], v[188:191], v[216:219], v[56:59]
	v_mfma_f32_16x16x32_bf16 v[44:47], v[180:183], v[224:227], v[44:47]
	v_mfma_f32_16x16x32_bf16 v[40:43], v[188:191], v[224:227], v[40:43]
	v_mfma_f32_16x16x32_bf16 v[28:31], v[180:183], v[232:235], v[28:31]
	v_mfma_f32_16x16x32_bf16 v[24:27], v[188:191], v[232:235], v[24:27]
	v_mfma_f32_16x16x32_bf16 v[12:15], v[180:183], v[240:243], v[12:15]
	v_mfma_f32_16x16x32_bf16 v[8:11], v[188:191], v[240:243], v[8:11]
	v_mfma_f32_16x16x32_bf16 v[52:55], v[192:195], v[212:215], v[52:55]
	v_mfma_f32_16x16x32_bf16 v[48:51], v[204:207], v[212:215], v[48:51]
	v_mfma_f32_16x16x32_bf16 v[36:39], v[192:195], v[220:223], v[36:39]
	v_mfma_f32_16x16x32_bf16 v[32:35], v[204:207], v[220:223], v[32:35]
	v_mfma_f32_16x16x32_bf16 v[20:23], v[192:195], v[228:231], v[20:23]
	v_mfma_f32_16x16x32_bf16 v[16:19], v[204:207], v[228:231], v[16:19]
	v_mfma_f32_16x16x32_bf16 v[4:7], v[192:195], v[236:239], v[4:7]
	v_mfma_f32_16x16x32_bf16 v[0:3], v[204:207], v[236:239], v[0:3]
	v_mfma_f32_16x16x32_bf16 v[52:55], v[196:199], v[216:219], v[52:55]
	v_mfma_f32_16x16x32_bf16 v[48:51], v[208:211], v[216:219], v[48:51]
	v_mfma_f32_16x16x32_bf16 v[36:39], v[196:199], v[224:227], v[36:39]
	v_mfma_f32_16x16x32_bf16 v[32:35], v[208:211], v[224:227], v[32:35]
	v_mfma_f32_16x16x32_bf16 v[20:23], v[196:199], v[232:235], v[20:23]
	v_mfma_f32_16x16x32_bf16 v[16:19], v[208:211], v[232:235], v[16:19]
	v_mfma_f32_16x16x32_bf16 v[4:7], v[196:199], v[240:243], v[4:7]
	v_mfma_f32_16x16x32_bf16 v[0:3], v[208:211], v[240:243], v[0:3]
	s_barrier
	s_add_i32 s46, 0, 0x18000
	v_add_u32_e32 v136, s46, v169
	s_add_i32 s47, 0, 0x1c000
	ds_read_b128 v[172:175], v136
	ds_read_b128 v[180:183], v136 offset:1024
	ds_read_b128 v[184:187], v136 offset:2048
	ds_read_b128 v[188:191], v136 offset:3072
	v_add_u32_e32 v136, s47, v169
	ds_read_b128 v[192:195], v136
	ds_read_b128 v[196:199], v136 offset:1024
	ds_read_b128 v[204:207], v136 offset:2048
	ds_read_b128 v[208:211], v136 offset:3072
	s_add_u32 s38, s38, 0x80000
	s_addc_u32 s39, s39, 0
	s_mov_b32 m0, s52
	v_lshl_add_u64 v[246:247], s[38:39], 0, v[128:129]
	ds_read_b128 v[212:215], v171 offset:32768
	ds_read_b128 v[216:219], v171 offset:33792
	ds_read_b128 v[220:223], v171 offset:34816
	ds_read_b128 v[224:227], v171 offset:35840
	ds_read_b128 v[228:231], v171 offset:36864
	ds_read_b128 v[232:235], v171 offset:37888
	ds_read_b128 v[236:239], v171 offset:38912
	ds_read_b128 v[240:243], v171 offset:39936
	global_load_lds_dwordx4 v[246:247], off
	s_mov_b32 m0, s53
	v_lshl_add_u64 v[246:247], s[38:39], 0, v[132:133]
	global_load_lds_dwordx4 v[246:247], off
	s_waitcnt vmcnt(8)
	s_waitcnt lgkmcnt(0)
	s_barrier
	v_mfma_f32_16x16x32_bf16 v[124:127], v[172:175], v[212:215], v[124:127]
	v_mfma_f32_16x16x32_bf16 v[120:123], v[184:187], v[212:215], v[120:123]
	v_mfma_f32_16x16x32_bf16 v[108:111], v[172:175], v[220:223], v[108:111]
	v_mfma_f32_16x16x32_bf16 v[104:107], v[184:187], v[220:223], v[104:107]
	v_mfma_f32_16x16x32_bf16 v[92:95], v[172:175], v[228:231], v[92:95]
	v_mfma_f32_16x16x32_bf16 v[88:91], v[184:187], v[228:231], v[88:91]
	v_mfma_f32_16x16x32_bf16 v[76:79], v[172:175], v[236:239], v[76:79]
	v_mfma_f32_16x16x32_bf16 v[72:75], v[184:187], v[236:239], v[72:75]
	v_mfma_f32_16x16x32_bf16 v[124:127], v[180:183], v[216:219], v[124:127]
	v_mfma_f32_16x16x32_bf16 v[120:123], v[188:191], v[216:219], v[120:123]
	v_mfma_f32_16x16x32_bf16 v[108:111], v[180:183], v[224:227], v[108:111]
	v_mfma_f32_16x16x32_bf16 v[104:107], v[188:191], v[224:227], v[104:107]
	v_mfma_f32_16x16x32_bf16 v[92:95], v[180:183], v[232:235], v[92:95]
	v_mfma_f32_16x16x32_bf16 v[88:91], v[188:191], v[232:235], v[88:91]
	v_mfma_f32_16x16x32_bf16 v[76:79], v[180:183], v[240:243], v[76:79]
	v_mfma_f32_16x16x32_bf16 v[72:75], v[188:191], v[240:243], v[72:75]
	v_mfma_f32_16x16x32_bf16 v[116:119], v[192:195], v[212:215], v[116:119]
	v_mfma_f32_16x16x32_bf16 v[112:115], v[204:207], v[212:215], v[112:115]
	v_mfma_f32_16x16x32_bf16 v[100:103], v[192:195], v[220:223], v[100:103]
	v_mfma_f32_16x16x32_bf16 v[96:99], v[204:207], v[220:223], v[96:99]
	v_mfma_f32_16x16x32_bf16 v[84:87], v[192:195], v[228:231], v[84:87]
	v_mfma_f32_16x16x32_bf16 v[80:83], v[204:207], v[228:231], v[80:83]
	v_mfma_f32_16x16x32_bf16 v[68:71], v[192:195], v[236:239], v[68:71]
	v_mfma_f32_16x16x32_bf16 v[64:67], v[204:207], v[236:239], v[64:67]
	v_mfma_f32_16x16x32_bf16 v[116:119], v[196:199], v[216:219], v[116:119]
	v_mfma_f32_16x16x32_bf16 v[112:115], v[208:211], v[216:219], v[112:115]
	v_mfma_f32_16x16x32_bf16 v[100:103], v[196:199], v[224:227], v[100:103]
	v_mfma_f32_16x16x32_bf16 v[96:99], v[208:211], v[224:227], v[96:99]
	v_mfma_f32_16x16x32_bf16 v[84:87], v[196:199], v[232:235], v[84:87]
	v_mfma_f32_16x16x32_bf16 v[80:83], v[208:211], v[232:235], v[80:83]
	v_mfma_f32_16x16x32_bf16 v[68:71], v[196:199], v[240:243], v[68:71]
	v_mfma_f32_16x16x32_bf16 v[64:67], v[208:211], v[240:243], v[64:67]
	s_barrier
; #define PG8_STAGE(bufoff, gbase, voff) do { _Pragma("unroll") for (int _i = 0; _i < 2; ++_i) \
;         __builtin_amdgcn_global_load_lds((const unsigned*)((const char*)(gbase) + (voff)[_i]), (LAS unsigned*)(lds + (bufoff) + ldsw + _i * 8192), 16, 0, 0); } while (0)
; #define PG8_LDA(dst, b, h) do { _Pragma("unroll") for (int m = 0; m < 4; ++m) _Pragma("unroll") for (int k = 0; k < 2; ++k) dst[m][k] = *(const LAS bf16x8*)(lds + PG8_SA(b, h) + aoff + m * 2048 + k * 1024); } while (0)
; #define PG8_MMA(ai, bj, At, Bt) do { __builtin_amdgcn_s_setprio(1); _Pragma("unroll") for (int m = 0; m < 4; ++m) _Pragma("unroll") for (int n = 0; n < 2; ++n) _Pragma("unroll") for (int k = 0; k < 2; ++k) \
;         acc[ai][bj][m][n] = __builtin_amdgcn_mfma_f32_16x16x32_bf16(Bt[n][k], At[m][k], acc[ai][bj][m][n], 0, 0, 0); __builtin_amdgcn_s_setprio(0); } while (0)
; #define PG8_WAIT_V(n) asm volatile("s_waitcnt vmcnt(" #n ")" ::: "memory")
; #define PG8_WAIT_L(n) asm volatile("s_waitcnt lgkmcnt(" #n ")" ::: "memory")
; #define PG8_BAR __builtin_amdgcn_s_barrier()
; #define PG8_SCHED __builtin_amdgcn_sched_barrier(0)
; template <class Epi, class Sched, bool ALIGN_EPI = true>
; __device__ __forceinline__ void gemm_phase(LAS unsigned char* lds, const Gemm g, const Sched& S, const Epi& E) {
;     ...
;             PG8_LDA(At, 1, 1); PG8_STAGE(PG8_SB(1, 0), b3, voffB); PG8_STAGE(PG8_SB(1, 1), b3 + hstep, voffB); PG8_STAGE(PG8_SA(1, 0), a3, voffA);
;             PG8_WAIT_V(8); PG8_WAIT_L(0); PG8_BAR; PG8_MMA(1, 0, At, B0); PG8_MMA(1, 1, At, B1); PG8_BAR; PG8_SCHED;
;         }
;         if constexpr (ALIGN_EPI) { if (wr == 0) PG8_BAR; }
;         E(acc, cur, wr, wc, fr, fq);
;         if (!has_next) break;
	s_add_i32 s38, s46, s42
	v_lshl_add_u64 v[164:165], v[164:165], 0, s[22:23]
	s_mov_b32 m0, s38
	ds_read_b128 v[212:215], v171 offset:49152
	ds_read_b128 v[216:219], v171 offset:50176
	ds_read_b128 v[220:223], v171 offset:51200
	ds_read_b128 v[224:227], v171 offset:52224
	ds_read_b128 v[228:231], v171 offset:53248
	ds_read_b128 v[232:235], v171 offset:54272
	ds_read_b128 v[236:239], v171 offset:55296
	ds_read_b128 v[240:243], v171 offset:56320
	global_load_lds_dwordx4 v[164:165], off
	s_add_i32 m0, s38, 0x2000
	s_add_u32 s36, s36, 0x80080
	v_lshl_add_u64 v[164:165], v[176:177], 0, s[22:23]
	s_addc_u32 s37, s37, 0
	s_add_i32 s38, s47, s42
	global_load_lds_dwordx4 v[164:165], off
	s_mov_b32 m0, s38
	v_lshl_add_u64 v[164:165], s[36:37], 0, v[130:131]
	global_load_lds_dwordx4 v[164:165], off
	s_add_i32 m0, s38, 0x2000
	v_lshl_add_u64 v[164:165], s[36:37], 0, v[134:135]
	global_load_lds_dwordx4 v[164:165], off
	s_mov_b32 m0, s54
	v_lshl_add_u64 v[164:165], v[200:201], 0, s[22:23]
	global_load_lds_dwordx4 v[164:165], off
	s_mov_b32 m0, s55
	v_lshl_add_u64 v[164:165], v[244:245], 0, s[22:23]
	global_load_lds_dwordx4 v[164:165], off
	s_waitcnt vmcnt(8)
	s_waitcnt lgkmcnt(0)
	s_barrier
	v_mfma_f32_16x16x32_bf16 v[60:63], v[172:175], v[212:215], v[60:63]
	v_mfma_f32_16x16x32_bf16 v[56:59], v[184:187], v[212:215], v[56:59]
	v_mfma_f32_16x16x32_bf16 v[44:47], v[172:175], v[220:223], v[44:47]
	v_mfma_f32_16x16x32_bf16 v[40:43], v[184:187], v[220:223], v[40:43]
	v_mfma_f32_16x16x32_bf16 v[28:31], v[172:175], v[228:231], v[28:31]
	v_mfma_f32_16x16x32_bf16 v[24:27], v[184:187], v[228:231], v[24:27]
	v_mfma_f32_16x16x32_bf16 v[12:15], v[172:175], v[236:239], v[12:15]
	v_mfma_f32_16x16x32_bf16 v[8:11], v[184:187], v[236:239], v[8:11]
	v_mfma_f32_16x16x32_bf16 v[60:63], v[180:183], v[216:219], v[60:63]
	v_mfma_f32_16x16x32_bf16 v[56:59], v[188:191], v[216:219], v[56:59]
	v_mfma_f32_16x16x32_bf16 v[44:47], v[180:183], v[224:227], v[44:47]
	v_mfma_f32_16x16x32_bf16 v[40:43], v[188:191], v[224:227], v[40:43]
	v_mfma_f32_16x16x32_bf16 v[28:31], v[180:183], v[232:235], v[28:31]
	v_mfma_f32_16x16x32_bf16 v[24:27], v[188:191], v[232:235], v[24:27]
	v_mfma_f32_16x16x32_bf16 v[12:15], v[180:183], v[240:243], v[12:15]
	v_mfma_f32_16x16x32_bf16 v[8:11], v[188:191], v[240:243], v[8:11]
	v_mfma_f32_16x16x32_bf16 v[52:55], v[192:195], v[212:215], v[52:55]
	v_mfma_f32_16x16x32_bf16 v[48:51], v[204:207], v[212:215], v[48:51]
	v_mfma_f32_16x16x32_bf16 v[36:39], v[192:195], v[220:223], v[36:39]
	v_mfma_f32_16x16x32_bf16 v[32:35], v[204:207], v[220:223], v[32:35]
	v_mfma_f32_16x16x32_bf16 v[20:23], v[192:195], v[228:231], v[20:23]
	v_mfma_f32_16x16x32_bf16 v[16:19], v[204:207], v[228:231], v[16:19]
	v_mfma_f32_16x16x32_bf16 v[4:7], v[192:195], v[236:239], v[4:7]
	v_mfma_f32_16x16x32_bf16 v[0:3], v[204:207], v[236:239], v[0:3]
	v_mfma_f32_16x16x32_bf16 v[52:55], v[196:199], v[216:219], v[52:55]
	v_mfma_f32_16x16x32_bf16 v[48:51], v[208:211], v[216:219], v[48:51]
	v_mfma_f32_16x16x32_bf16 v[36:39], v[196:199], v[224:227], v[36:39]
	v_mfma_f32_16x16x32_bf16 v[32:35], v[208:211], v[224:227], v[32:35]
	v_mfma_f32_16x16x32_bf16 v[20:23], v[196:199], v[232:235], v[20:23]
	v_mfma_f32_16x16x32_bf16 v[16:19], v[208:211], v[232:235], v[16:19]
	v_mfma_f32_16x16x32_bf16 v[4:7], v[196:199], v[240:243], v[4:7]
	v_mfma_f32_16x16x32_bf16 v[0:3], v[208:211], v[240:243], v[0:3]
	s_barrier
	s_add_i32 s89, s89, 2
	s_add_u32 s34, s34, 0x100
	s_addc_u32 s35, s35, 0
	s_add_u32 s87, s87, 0x100
	s_addc_u32 s88, s88, 0
	s_cmp_gt_u32 s89, 29
	s_cbranch_scc0 .LBB0_195
	s_and_b64 vcc, exec, s[24:25]
	s_cbranch_vccnz .LBB0_202
	s_lshr_b32 s9, s81, 2
	s_cmp_lt_i32 s9, 1
	s_mov_b64 s[34:35], -1
	s_cbranch_scc0 .LBB0_203

; #define PG8_STAGE(bufoff, gbase, voff) do { _Pragma("unroll") for (int _i = 0; _i < 2; ++_i) \
;         __builtin_amdgcn_global_load_lds((const unsigned*)((const char*)(gbase) + (voff)[_i]), (LAS unsigned*)(lds + (bufoff) + ldsw + _i * 8192), 16, 0, 0); } while (0)
; #define PG8_LDA(dst, b, h) do { _Pragma("unroll") for (int m = 0; m < 4; ++m) _Pragma("unroll") for (int k = 0; k < 2; ++k) dst[m][k] = *(const LAS bf16x8*)(lds + PG8_SA(b, h) + aoff + m * 2048 + k * 1024); } while (0)
; #define PG8_LDB(dst, b, h) do { _Pragma("unroll") for (int n = 0; n < 2; ++n) _Pragma("unroll") for (int k = 0; k < 2; ++k) dst[n][k] = *(const LAS bf16x8*)(lds + PG8_SB(b, h) + boff + n * 2048 + k * 1024); } while (0)
; #define PG8_MMA(ai, bj, At, Bt) do { __builtin_amdgcn_s_setprio(1); _Pragma("unroll") for (int m = 0; m < 4; ++m) _Pragma("unroll") for (int n = 0; n < 2; ++n) _Pragma("unroll") for (int k = 0; k < 2; ++k) \
;         acc[ai][bj][m][n] = __builtin_amdgcn_mfma_f32_16x16x32_bf16(Bt[n][k], At[m][k], acc[ai][bj][m][n], 0, 0, 0); __builtin_amdgcn_s_setprio(0); } while (0)
; #define PG8_WAIT_V(n) asm volatile("s_waitcnt vmcnt(" #n ")" ::: "memory")
; #define PG8_WAIT_L(n) asm volatile("s_waitcnt lgkmcnt(" #n ")" ::: "memory")
; #define PG8_BAR __builtin_amdgcn_s_barrier()
; #define PG8_SCHED __builtin_amdgcn_sched_barrier(0)
; template <class Epi, class Sched, bool ALIGN_EPI = true>
; __device__ __forceinline__ void gemm_phase(LAS unsigned char* lds, const Gemm g, const Sched& S, const Epi& E) {
;     ...
;             const char* a1 = cA + (size_t)(t + 1) * kstep;
;             const char* a2 = last ? nA : cA + (size_t)(t + 2) * kstep; const char* b2 = last ? nB : cB + (size_t)(t + 2) * kstep;
;             const char* a3 = a2 + kstep; const char* b3 = b2 + kstep;
;             PG8_LDB(B0, 0, 0); PG8_LDB(B1, 0, 1); PG8_SCHED; PG8_LDA(At, 0, 0); PG8_STAGE(PG8_SA(1, 1), a1 + hstep, voffA);
;             PG8_WAIT_V(8); PG8_WAIT_L(0); PG8_BAR; PG8_MMA(0, 0, At, B0); PG8_MMA(0, 1, At, B1); PG8_BAR; PG8_SCHED;
;             PG8_LDA(At, 0, 1); PG8_STAGE(PG8_SB(0, 0), b2, voffB); PG8_STAGE(PG8_SB(0, 1), b2 + hstep, voffB); PG8_STAGE(PG8_SA(0, 0), a2, voffA);
.LBB0_223:
	ds_read_b128 v[128:131], v203
	s_waitcnt lgkmcnt(0)
	ds_read_b128 v[132:135], v203 offset:1024
	ds_read_b128 v[136:139], v203 offset:2048
	ds_read_b128 v[140:143], v203 offset:3072
	ds_read_b128 v[176:179], v204
	ds_read_b128 v[180:183], v204 offset:1024
	ds_read_b128 v[184:187], v204 offset:2048
	ds_read_b128 v[188:191], v204 offset:3072
	s_add_u32 s46, s76, 0xfff80080
	s_addc_u32 s47, s77, -1
	s_cmp_eq_u32 vcc_hi, 28
	s_cselect_b32 s81, s9, s47
	s_cselect_b32 s80, s30, s46
	s_cselect_b32 s79, s11, vcc_lo
	s_cselect_b32 s78, s96, s97
	v_lshl_add_u64 v[200:201], s[76:77], 0, v[164:165]
	s_add_i32 m0, s55, 0xc000
	ds_read_b128 v[192:195], v205
	ds_read_b128 v[196:199], v205 offset:1024
	ds_read_b128 v[208:211], v205 offset:2048
	ds_read_b128 v[212:215], v205 offset:3072
	ds_read_b128 v[216:219], v205 offset:4096
	ds_read_b128 v[220:223], v205 offset:5120
	ds_read_b128 v[224:227], v205 offset:6144
	ds_read_b128 v[228:231], v205 offset:7168
	global_load_lds_dwordx4 v[200:201], off
	s_add_i32 m0, s55, 0xe000
	v_lshl_add_u64 v[200:201], s[76:77], 0, v[166:167]
	global_load_lds_dwordx4 v[200:201], off
	s_waitcnt vmcnt(8)
	s_waitcnt lgkmcnt(0)
	s_barrier
	v_mfma_f32_16x16x32_bf16 v[124:127], v[128:131], v[192:195], v[124:127]
	v_mfma_f32_16x16x32_bf16 v[120:123], v[136:139], v[192:195], v[120:123]
	v_mfma_f32_16x16x32_bf16 v[108:111], v[128:131], v[208:211], v[108:111]
	v_mfma_f32_16x16x32_bf16 v[104:107], v[136:139], v[208:211], v[104:107]
	v_mfma_f32_16x16x32_bf16 v[92:95], v[128:131], v[216:219], v[92:95]
	v_mfma_f32_16x16x32_bf16 v[88:91], v[136:139], v[216:219], v[88:91]
	v_mfma_f32_16x16x32_bf16 v[76:79], v[128:131], v[224:227], v[76:79]
	v_mfma_f32_16x16x32_bf16 v[72:75], v[136:139], v[224:227], v[72:75]
	v_mfma_f32_16x16x32_bf16 v[124:127], v[132:135], v[196:199], v[124:127]
	v_mfma_f32_16x16x32_bf16 v[120:123], v[140:143], v[196:199], v[120:123]
	v_mfma_f32_16x16x32_bf16 v[108:111], v[132:135], v[212:215], v[108:111]
	v_mfma_f32_16x16x32_bf16 v[104:107], v[140:143], v[212:215], v[104:107]
	v_mfma_f32_16x16x32_bf16 v[92:95], v[132:135], v[220:223], v[92:95]
	v_mfma_f32_16x16x32_bf16 v[88:91], v[140:143], v[220:223], v[88:91]
	v_mfma_f32_16x16x32_bf16 v[76:79], v[132:135], v[228:231], v[76:79]
	v_mfma_f32_16x16x32_bf16 v[72:75], v[140:143], v[228:231], v[72:75]
	v_mfma_f32_16x16x32_bf16 v[116:119], v[176:179], v[192:195], v[116:119]
	v_mfma_f32_16x16x32_bf16 v[112:115], v[184:187], v[192:195], v[112:115]
	v_mfma_f32_16x16x32_bf16 v[100:103], v[176:179], v[208:211], v[100:103]
	v_mfma_f32_16x16x32_bf16 v[96:99], v[184:187], v[208:211], v[96:99]
	v_mfma_f32_16x16x32_bf16 v[84:87], v[176:179], v[216:219], v[84:87]
	v_mfma_f32_16x16x32_bf16 v[80:83], v[184:187], v[216:219], v[80:83]
	v_mfma_f32_16x16x32_bf16 v[68:71], v[176:179], v[224:227], v[68:71]
	v_mfma_f32_16x16x32_bf16 v[64:67], v[184:187], v[224:227], v[64:67]
	v_mfma_f32_16x16x32_bf16 v[116:119], v[180:183], v[196:199], v[116:119]
	v_mfma_f32_16x16x32_bf16 v[112:115], v[188:191], v[196:199], v[112:115]
	v_mfma_f32_16x16x32_bf16 v[100:103], v[180:183], v[212:215], v[100:103]
	v_mfma_f32_16x16x32_bf16 v[96:99], v[188:191], v[212:215], v[96:99]
	v_mfma_f32_16x16x32_bf16 v[84:87], v[180:183], v[220:223], v[84:87]
	v_mfma_f32_16x16x32_bf16 v[80:83], v[188:191], v[220:223], v[80:83]
	v_mfma_f32_16x16x32_bf16 v[68:71], v[180:183], v[228:231], v[68:71]
	v_mfma_f32_16x16x32_bf16 v[64:67], v[188:191], v[228:231], v[64:67]
	s_barrier
	s_add_i32 s46, s90, s53
	v_lshl_add_u64 v[200:201], s[78:79], 0, v[146:147]
	s_mov_b32 m0, s46
	ds_read_b128 v[192:195], v205 offset:16384
	ds_read_b128 v[196:199], v205 offset:17408
	ds_read_b128 v[208:211], v205 offset:18432
	ds_read_b128 v[212:215], v205 offset:19456
	ds_read_b128 v[216:219], v205 offset:20480
	ds_read_b128 v[220:223], v205 offset:21504
	ds_read_b128 v[224:227], v205 offset:22528
	ds_read_b128 v[228:231], v205 offset:23552
	global_load_lds_dwordx4 v[200:201], off
	s_add_i32 m0, s46, 0x2000
	s_add_u32 s46, s78, 0x80000
	v_lshl_add_u64 v[232:233], s[78:79], 0, v[150:151]
	s_addc_u32 s47, s79, 0
	s_add_i32 s82, s91, s53
	global_load_lds_dwordx4 v[232:233], off
	v_lshl_add_u64 v[234:235], s[46:47], 0, v[146:147]
	s_mov_b32 m0, s82
	v_lshl_add_u64 v[236:237], s[80:81], 0, v[148:149]
	global_load_lds_dwordx4 v[234:235], off
	s_add_i32 m0, s82, 0x2000
	v_lshl_add_u64 v[234:235], s[46:47], 0, v[150:151]
	global_load_lds_dwordx4 v[234:235], off
	s_mov_b32 m0, s55
	v_lshl_add_u64 v[234:235], s[80:81], 0, v[144:145]
	global_load_lds_dwordx4 v[234:235], off
	s_mov_b32 m0, s57
	s_nop 0
	global_load_lds_dwordx4 v[236:237], off
	s_waitcnt vmcnt(8)
	s_waitcnt lgkmcnt(0)
	s_barrier
; #define PG8_STAGE(bufoff, gbase, voff) do { _Pragma("unroll") for (int _i = 0; _i < 2; ++_i) \
;         __builtin_amdgcn_global_load_lds((const unsigned*)((const char*)(gbase) + (voff)[_i]), (LAS unsigned*)(lds + (bufoff) + ldsw + _i * 8192), 16, 0, 0); } while (0)
; #define PG8_LDA(dst, b, h) do { _Pragma("unroll") for (int m = 0; m < 4; ++m) _Pragma("unroll") for (int k = 0; k < 2; ++k) dst[m][k] = *(const LAS bf16x8*)(lds + PG8_SA(b, h) + aoff + m * 2048 + k * 1024); } while (0)
; #define PG8_LDB(dst, b, h) do { _Pragma("unroll") for (int n = 0; n < 2; ++n) _Pragma("unroll") for (int k = 0; k < 2; ++k) dst[n][k] = *(const LAS bf16x8*)(lds + PG8_SB(b, h) + boff + n * 2048 + k * 1024); } while (0)
; #define PG8_MMA(ai, bj, At, Bt) do { __builtin_amdgcn_s_setprio(1); _Pragma("unroll") for (int m = 0; m < 4; ++m) _Pragma("unroll") for (int n = 0; n < 2; ++n) _Pragma("unroll") for (int k = 0; k < 2; ++k) \
;         acc[ai][bj][m][n] = __builtin_amdgcn_mfma_f32_16x16x32_bf16(Bt[n][k], At[m][k], acc[ai][bj][m][n], 0, 0, 0); __builtin_amdgcn_s_setprio(0); } while (0)
; #define PG8_WAIT_V(n) asm volatile("s_waitcnt vmcnt(" #n ")" ::: "memory")
; #define PG8_WAIT_L(n) asm volatile("s_waitcnt lgkmcnt(" #n ")" ::: "memory")
; #define PG8_BAR __builtin_amdgcn_s_barrier()
; #define PG8_SCHED __builtin_amdgcn_sched_barrier(0)
; template <class Epi, class Sched, bool ALIGN_EPI = true>
; __device__ __forceinline__ void gemm_phase(LAS unsigned char* lds, const Gemm g, const Sched& S, const Epi& E) {
;     ...
;             PG8_WAIT_V(8); PG8_WAIT_L(0); PG8_BAR; PG8_MMA(1, 0, At, B0); PG8_MMA(1, 1, At, B1); PG8_BAR; PG8_SCHED;
;             PG8_LDB(B0, 1, 0); PG8_LDB(B1, 1, 1); PG8_SCHED; PG8_LDA(At, 1, 0); PG8_STAGE(PG8_SA(0, 1), a2 + hstep, voffA);
;             PG8_WAIT_V(8); PG8_WAIT_L(0); PG8_BAR; PG8_MMA(0, 0, At, B0); PG8_MMA(0, 1, At, B1); PG8_BAR; PG8_SCHED;
;             PG8_LDA(At, 1, 1); PG8_STAGE(PG8_SB(1, 0), b3, voffB); PG8_STAGE(PG8_SB(1, 1), b3 + hstep, voffB); PG8_STAGE(PG8_SA(1, 0), a3, voffA);
	v_mfma_f32_16x16x32_bf16 v[60:63], v[128:131], v[192:195], v[60:63]
	v_mfma_f32_16x16x32_bf16 v[56:59], v[136:139], v[192:195], v[56:59]
	v_mfma_f32_16x16x32_bf16 v[44:47], v[128:131], v[208:211], v[44:47]
	v_mfma_f32_16x16x32_bf16 v[40:43], v[136:139], v[208:211], v[40:43]
	v_mfma_f32_16x16x32_bf16 v[28:31], v[128:131], v[216:219], v[28:31]
	v_mfma_f32_16x16x32_bf16 v[24:27], v[136:139], v[216:219], v[24:27]
	v_mfma_f32_16x16x32_bf16 v[12:15], v[128:131], v[224:227], v[12:15]
	v_mfma_f32_16x16x32_bf16 v[8:11], v[136:139], v[224:227], v[8:11]
	v_mfma_f32_16x16x32_bf16 v[60:63], v[132:135], v[196:199], v[60:63]
	v_mfma_f32_16x16x32_bf16 v[56:59], v[140:143], v[196:199], v[56:59]
	v_mfma_f32_16x16x32_bf16 v[44:47], v[132:135], v[212:215], v[44:47]
	v_mfma_f32_16x16x32_bf16 v[40:43], v[140:143], v[212:215], v[40:43]
	v_mfma_f32_16x16x32_bf16 v[28:31], v[132:135], v[220:223], v[28:31]
	v_mfma_f32_16x16x32_bf16 v[24:27], v[140:143], v[220:223], v[24:27]
	v_mfma_f32_16x16x32_bf16 v[12:15], v[132:135], v[228:231], v[12:15]
	v_mfma_f32_16x16x32_bf16 v[8:11], v[140:143], v[228:231], v[8:11]
	v_mfma_f32_16x16x32_bf16 v[52:55], v[176:179], v[192:195], v[52:55]
	v_mfma_f32_16x16x32_bf16 v[48:51], v[184:187], v[192:195], v[48:51]
	v_mfma_f32_16x16x32_bf16 v[36:39], v[176:179], v[208:211], v[36:39]
	v_mfma_f32_16x16x32_bf16 v[32:35], v[184:187], v[208:211], v[32:35]
	v_mfma_f32_16x16x32_bf16 v[20:23], v[176:179], v[216:219], v[20:23]
	v_mfma_f32_16x16x32_bf16 v[16:19], v[184:187], v[216:219], v[16:19]
	v_mfma_f32_16x16x32_bf16 v[4:7], v[176:179], v[224:227], v[4:7]
	v_mfma_f32_16x16x32_bf16 v[0:3], v[184:187], v[224:227], v[0:3]
	v_mfma_f32_16x16x32_bf16 v[52:55], v[180:183], v[196:199], v[52:55]
	v_mfma_f32_16x16x32_bf16 v[48:51], v[188:191], v[196:199], v[48:51]
	v_mfma_f32_16x16x32_bf16 v[36:39], v[180:183], v[212:215], v[36:39]
	v_mfma_f32_16x16x32_bf16 v[32:35], v[188:191], v[212:215], v[32:35]
	v_mfma_f32_16x16x32_bf16 v[20:23], v[180:183], v[220:223], v[20:23]
	v_mfma_f32_16x16x32_bf16 v[16:19], v[188:191], v[220:223], v[16:19]
	v_mfma_f32_16x16x32_bf16 v[4:7], v[180:183], v[228:231], v[4:7]
	v_mfma_f32_16x16x32_bf16 v[0:3], v[188:191], v[228:231], v[0:3]
	s_barrier
	s_add_i32 s82, 0, 0x18000
	s_add_i32 s92, 0, 0x1c000
	v_add_u32_e32 v140, s82, v161
	v_add_u32_e32 v152, s92, v161
	ds_read_b128 v[128:131], v140
	ds_read_b128 v[132:135], v140 offset:1024
	ds_read_b128 v[136:139], v140 offset:2048
	ds_read_b128 v[140:143], v140 offset:3072
	ds_read_b128 v[176:179], v152
	ds_read_b128 v[180:183], v152 offset:1024
	ds_read_b128 v[184:187], v152 offset:2048
	ds_read_b128 v[188:191], v152 offset:3072
	s_add_u32 s46, s80, 0x80000
	s_addc_u32 s47, s81, 0
	s_mov_b32 m0, s83
	v_lshl_add_u64 v[238:239], s[46:47], 0, v[144:145]
	ds_read_b128 v[192:195], v205 offset:32768
	ds_read_b128 v[196:199], v205 offset:33792
	ds_read_b128 v[208:211], v205 offset:34816
	ds_read_b128 v[212:215], v205 offset:35840
	ds_read_b128 v[216:219], v205 offset:36864
	ds_read_b128 v[220:223], v205 offset:37888
	ds_read_b128 v[224:227], v205 offset:38912
	ds_read_b128 v[228:231], v205 offset:39936
	global_load_lds_dwordx4 v[238:239], off
	s_mov_b32 m0, s84
	v_lshl_add_u64 v[238:239], s[46:47], 0, v[148:149]
	global_load_lds_dwordx4 v[238:239], off
	s_waitcnt vmcnt(8)
	s_waitcnt lgkmcnt(0)
	s_barrier
	v_mfma_f32_16x16x32_bf16 v[124:127], v[128:131], v[192:195], v[124:127]
	v_mfma_f32_16x16x32_bf16 v[120:123], v[136:139], v[192:195], v[120:123]
	v_mfma_f32_16x16x32_bf16 v[108:111], v[128:131], v[208:211], v[108:111]
	v_mfma_f32_16x16x32_bf16 v[104:107], v[136:139], v[208:211], v[104:107]
	v_mfma_f32_16x16x32_bf16 v[92:95], v[128:131], v[216:219], v[92:95]
	v_mfma_f32_16x16x32_bf16 v[88:91], v[136:139], v[216:219], v[88:91]
	v_mfma_f32_16x16x32_bf16 v[76:79], v[128:131], v[224:227], v[76:79]
	v_mfma_f32_16x16x32_bf16 v[72:75], v[136:139], v[224:227], v[72:75]
	v_mfma_f32_16x16x32_bf16 v[124:127], v[132:135], v[196:199], v[124:127]
	v_mfma_f32_16x16x32_bf16 v[120:123], v[140:143], v[196:199], v[120:123]
	v_mfma_f32_16x16x32_bf16 v[108:111], v[132:135], v[212:215], v[108:111]
	v_mfma_f32_16x16x32_bf16 v[104:107], v[140:143], v[212:215], v[104:107]
	v_mfma_f32_16x16x32_bf16 v[92:95], v[132:135], v[220:223], v[92:95]
	v_mfma_f32_16x16x32_bf16 v[88:91], v[140:143], v[220:223], v[88:91]
	v_mfma_f32_16x16x32_bf16 v[76:79], v[132:135], v[228:231], v[76:79]
	v_mfma_f32_16x16x32_bf16 v[72:75], v[140:143], v[228:231], v[72:75]
	v_mfma_f32_16x16x32_bf16 v[116:119], v[176:179], v[192:195], v[116:119]
	v_mfma_f32_16x16x32_bf16 v[112:115], v[184:187], v[192:195], v[112:115]
	v_mfma_f32_16x16x32_bf16 v[100:103], v[176:179], v[208:211], v[100:103]
	v_mfma_f32_16x16x32_bf16 v[96:99], v[184:187], v[208:211], v[96:99]
	v_mfma_f32_16x16x32_bf16 v[84:87], v[176:179], v[216:219], v[84:87]
	v_mfma_f32_16x16x32_bf16 v[80:83], v[184:187], v[216:219], v[80:83]
	v_mfma_f32_16x16x32_bf16 v[68:71], v[176:179], v[224:227], v[68:71]
	v_mfma_f32_16x16x32_bf16 v[64:67], v[184:187], v[224:227], v[64:67]
	v_mfma_f32_16x16x32_bf16 v[116:119], v[180:183], v[196:199], v[116:119]
	v_mfma_f32_16x16x32_bf16 v[112:115], v[188:191], v[196:199], v[112:115]
	v_mfma_f32_16x16x32_bf16 v[100:103], v[180:183], v[212:215], v[100:103]
	v_mfma_f32_16x16x32_bf16 v[96:99], v[188:191], v[212:215], v[96:99]
	v_mfma_f32_16x16x32_bf16 v[84:87], v[180:183], v[220:223], v[84:87]
	v_mfma_f32_16x16x32_bf16 v[80:83], v[188:191], v[220:223], v[80:83]
	v_mfma_f32_16x16x32_bf16 v[68:71], v[180:183], v[228:231], v[68:71]
	v_mfma_f32_16x16x32_bf16 v[64:67], v[188:191], v[228:231], v[64:67]
	s_barrier
; #define PG8_STAGE(bufoff, gbase, voff) do { _Pragma("unroll") for (int _i = 0; _i < 2; ++_i) \
;         __builtin_amdgcn_global_load_lds((const unsigned*)((const char*)(gbase) + (voff)[_i]), (LAS unsigned*)(lds + (bufoff) + ldsw + _i * 8192), 16, 0, 0); } while (0)
; #define PG8_LDA(dst, b, h) do { _Pragma("unroll") for (int m = 0; m < 4; ++m) _Pragma("unroll") for (int k = 0; k < 2; ++k) dst[m][k] = *(const LAS bf16x8*)(lds + PG8_SA(b, h) + aoff + m * 2048 + k * 1024); } while (0)
; #define PG8_MMA(ai, bj, At, Bt) do { __builtin_amdgcn_s_setprio(1); _Pragma("unroll") for (int m = 0; m < 4; ++m) _Pragma("unroll") for (int n = 0; n < 2; ++n) _Pragma("unroll") for (int k = 0; k < 2; ++k) \
;         acc[ai][bj][m][n] = __builtin_amdgcn_mfma_f32_16x16x32_bf16(Bt[n][k], At[m][k], acc[ai][bj][m][n], 0, 0, 0); __builtin_amdgcn_s_setprio(0); } while (0)
; #define PG8_WAIT_V(n) asm volatile("s_waitcnt vmcnt(" #n ")" ::: "memory")
; #define PG8_WAIT_L(n) asm volatile("s_waitcnt lgkmcnt(" #n ")" ::: "memory")
; #define PG8_BAR __builtin_amdgcn_s_barrier()
; #define PG8_SCHED __builtin_amdgcn_sched_barrier(0)
; template <class Epi, class Sched, bool ALIGN_EPI = true>
; __device__ __forceinline__ void gemm_phase(LAS unsigned char* lds, const Gemm g, const Sched& S, const Epi& E) {
;     ...
;             PG8_LDA(At, 1, 1); PG8_STAGE(PG8_SB(1, 0), b3, voffB); PG8_STAGE(PG8_SB(1, 1), b3 + hstep, voffB); PG8_STAGE(PG8_SA(1, 0), a3, voffA);
;             PG8_WAIT_V(8); PG8_WAIT_L(0); PG8_BAR; PG8_MMA(1, 0, At, B0); PG8_MMA(1, 1, At, B1); PG8_BAR; PG8_SCHED;
;         }
	s_add_i32 s46, s82, s53
	v_lshl_add_u64 v[200:201], v[200:201], 0, s[28:29]
	s_mov_b32 m0, s46
	ds_read_b128 v[192:195], v205 offset:49152
	ds_read_b128 v[196:199], v205 offset:50176
	ds_read_b128 v[208:211], v205 offset:51200
	ds_read_b128 v[212:215], v205 offset:52224
	ds_read_b128 v[216:219], v205 offset:53248
	ds_read_b128 v[220:223], v205 offset:54272
	ds_read_b128 v[224:227], v205 offset:55296
	ds_read_b128 v[228:231], v205 offset:56320
	global_load_lds_dwordx4 v[200:201], off
	s_add_i32 m0, s46, 0x2000
	s_add_u32 s46, s78, 0x80080
	v_lshl_add_u64 v[200:201], v[232:233], 0, s[28:29]
	s_addc_u32 s47, s79, 0
	s_add_i32 s78, s92, s53
	global_load_lds_dwordx4 v[200:201], off
	s_mov_b32 m0, s78
	v_lshl_add_u64 v[200:201], s[46:47], 0, v[146:147]
	global_load_lds_dwordx4 v[200:201], off
	s_add_i32 m0, s78, 0x2000
	v_lshl_add_u64 v[200:201], s[46:47], 0, v[150:151]
	global_load_lds_dwordx4 v[200:201], off
	s_mov_b32 m0, s87
	v_lshl_add_u64 v[200:201], v[234:235], 0, s[28:29]
	global_load_lds_dwordx4 v[200:201], off
	s_mov_b32 m0, s88
	v_lshl_add_u64 v[200:201], v[236:237], 0, s[28:29]
	global_load_lds_dwordx4 v[200:201], off
	s_waitcnt vmcnt(8)
	s_waitcnt lgkmcnt(0)
	s_barrier
	v_mfma_f32_16x16x32_bf16 v[60:63], v[128:131], v[192:195], v[60:63]
	v_mfma_f32_16x16x32_bf16 v[56:59], v[136:139], v[192:195], v[56:59]
	v_mfma_f32_16x16x32_bf16 v[44:47], v[128:131], v[208:211], v[44:47]
	v_mfma_f32_16x16x32_bf16 v[40:43], v[136:139], v[208:211], v[40:43]
	v_mfma_f32_16x16x32_bf16 v[28:31], v[128:131], v[216:219], v[28:31]
	v_mfma_f32_16x16x32_bf16 v[24:27], v[136:139], v[216:219], v[24:27]
	v_mfma_f32_16x16x32_bf16 v[12:15], v[128:131], v[224:227], v[12:15]
	v_mfma_f32_16x16x32_bf16 v[8:11], v[136:139], v[224:227], v[8:11]
	v_mfma_f32_16x16x32_bf16 v[60:63], v[132:135], v[196:199], v[60:63]
	v_mfma_f32_16x16x32_bf16 v[56:59], v[140:143], v[196:199], v[56:59]
	v_mfma_f32_16x16x32_bf16 v[44:47], v[132:135], v[212:215], v[44:47]
	v_mfma_f32_16x16x32_bf16 v[40:43], v[140:143], v[212:215], v[40:43]
	v_mfma_f32_16x16x32_bf16 v[28:31], v[132:135], v[220:223], v[28:31]
	v_mfma_f32_16x16x32_bf16 v[24:27], v[140:143], v[220:223], v[24:27]
	v_mfma_f32_16x16x32_bf16 v[12:15], v[132:135], v[228:231], v[12:15]
	v_mfma_f32_16x16x32_bf16 v[8:11], v[140:143], v[228:231], v[8:11]
	v_mfma_f32_16x16x32_bf16 v[52:55], v[176:179], v[192:195], v[52:55]
	v_mfma_f32_16x16x32_bf16 v[48:51], v[184:187], v[192:195], v[48:51]
	v_mfma_f32_16x16x32_bf16 v[36:39], v[176:179], v[208:211], v[36:39]
	v_mfma_f32_16x16x32_bf16 v[32:35], v[184:187], v[208:211], v[32:35]
	v_mfma_f32_16x16x32_bf16 v[20:23], v[176:179], v[216:219], v[20:23]
	v_mfma_f32_16x16x32_bf16 v[16:19], v[184:187], v[216:219], v[16:19]
	v_mfma_f32_16x16x32_bf16 v[4:7], v[176:179], v[224:227], v[4:7]
	v_mfma_f32_16x16x32_bf16 v[0:3], v[184:187], v[224:227], v[0:3]
	v_mfma_f32_16x16x32_bf16 v[52:55], v[180:183], v[196:199], v[52:55]
	v_mfma_f32_16x16x32_bf16 v[48:51], v[188:191], v[196:199], v[48:51]
	v_mfma_f32_16x16x32_bf16 v[36:39], v[180:183], v[212:215], v[36:39]
	v_mfma_f32_16x16x32_bf16 v[32:35], v[188:191], v[212:215], v[32:35]
	v_mfma_f32_16x16x32_bf16 v[20:23], v[180:183], v[220:223], v[20:23]
	v_mfma_f32_16x16x32_bf16 v[16:19], v[188:191], v[220:223], v[16:19]
	v_mfma_f32_16x16x32_bf16 v[4:7], v[180:183], v[228:231], v[4:7]
	v_mfma_f32_16x16x32_bf16 v[0:3], v[188:191], v[228:231], v[0:3]
	s_barrier
	s_add_i32 vcc_hi, vcc_hi, 2
	s_add_u32 s76, s76, 0x100
	s_addc_u32 s77, s77, 0
	s_add_u32 s97, s97, 0x100
	s_addc_u32 vcc_lo, vcc_lo, 0
	s_cmp_gt_u32 vcc_hi, 29
	s_cbranch_scc0 .LBB0_223
	s_and_b64 vcc, exec, s[34:35]
	s_cbranch_vccz .LBB0_226
	s_barrier

; #define PG8_STAGE(bufoff, gbase, voff) do { _Pragma("unroll") for (int _i = 0; _i < 2; ++_i) \
;         __builtin_amdgcn_global_load_lds((const unsigned*)((const char*)(gbase) + (voff)[_i]), (LAS unsigned*)(lds + (bufoff) + ldsw + _i * 8192), 16, 0, 0); } while (0)
; #define PG8_LDA(dst, b, h) do { _Pragma("unroll") for (int m = 0; m < 4; ++m) _Pragma("unroll") for (int k = 0; k < 2; ++k) dst[m][k] = *(const LAS bf16x8*)(lds + PG8_SA(b, h) + aoff + m * 2048 + k * 1024); } while (0)
; #define PG8_LDB(dst, b, h) do { _Pragma("unroll") for (int n = 0; n < 2; ++n) _Pragma("unroll") for (int k = 0; k < 2; ++k) dst[n][k] = *(const LAS bf16x8*)(lds + PG8_SB(b, h) + boff + n * 2048 + k * 1024); } while (0)
; #define PG8_MMA(ai, bj, At, Bt) do { __builtin_amdgcn_s_setprio(1); _Pragma("unroll") for (int m = 0; m < 4; ++m) _Pragma("unroll") for (int n = 0; n < 2; ++n) _Pragma("unroll") for (int k = 0; k < 2; ++k) \
;         acc[ai][bj][m][n] = __builtin_amdgcn_mfma_f32_16x16x32_bf16(Bt[n][k], At[m][k], acc[ai][bj][m][n], 0, 0, 0); __builtin_amdgcn_s_setprio(0); } while (0)
; #define PG8_WAIT_V(n) asm volatile("s_waitcnt vmcnt(" #n ")" ::: "memory")
; #define PG8_WAIT_L(n) asm volatile("s_waitcnt lgkmcnt(" #n ")" ::: "memory")
; #define PG8_BAR __builtin_amdgcn_s_barrier()
; #define PG8_SCHED __builtin_amdgcn_sched_barrier(0)
; template <class Epi, class Sched, bool ALIGN_EPI = true>
; __device__ __forceinline__ void gemm_phase(LAS unsigned char* lds, const Gemm g, const Sched& S, const Epi& E) {
;     ...
;             const char* a1 = cA + (size_t)(t + 1) * kstep;
;             const char* a2 = last ? nA : cA + (size_t)(t + 2) * kstep; const char* b2 = last ? nB : cB + (size_t)(t + 2) * kstep;
;             const char* a3 = a2 + kstep; const char* b3 = b2 + kstep;
;             PG8_LDB(B0, 0, 0); PG8_LDB(B1, 0, 1); PG8_SCHED; PG8_LDA(At, 0, 0); PG8_STAGE(PG8_SA(1, 1), a1 + hstep, voffA);
;             PG8_WAIT_V(8); PG8_WAIT_L(0); PG8_BAR; PG8_MMA(0, 0, At, B0); PG8_MMA(0, 1, At, B1); PG8_BAR; PG8_SCHED;
;             PG8_LDA(At, 0, 1); PG8_STAGE(PG8_SB(0, 0), b2, voffB); PG8_STAGE(PG8_SB(0, 1), b2 + hstep, voffB); PG8_STAGE(PG8_SA(0, 0), a2, voffA);
.LBB0_560:
	ds_read_b128 v[128:131], v206
	ds_read_b128 v[132:135], v206 offset:1024
	ds_read_b128 v[136:139], v206 offset:2048
	ds_read_b128 v[140:143], v206 offset:3072
	ds_read_b128 v[144:147], v207
	ds_read_b128 v[148:151], v207 offset:1024
	ds_read_b128 v[152:155], v207 offset:2048
	ds_read_b128 v[156:159], v207 offset:3072
	s_add_u32 s28, s26, 0xfff80080
	s_addc_u32 s29, s27, -1
	s_cmp_eq_u32 s58, 28
	s_cselect_b32 s31, s53, s29
	s_cselect_b32 s30, s54, s28
	s_cselect_b32 s29, s9, s57
	s_cselect_b32 s28, s55, s56
	v_lshl_add_u64 v[214:215], s[26:27], 0, v[184:185]
	s_add_i32 m0, s38, 0xc000
	ds_read_b128 v[160:163], v208
	ds_read_b128 v[164:167], v208 offset:1024
	ds_read_b128 v[168:171], v208 offset:2048
	ds_read_b128 v[172:175], v208 offset:3072
	ds_read_b128 v[188:191], v208 offset:4096
	ds_read_b128 v[192:195], v208 offset:5120
	ds_read_b128 v[196:199], v208 offset:6144
	ds_read_b128 v[210:213], v208 offset:7168
	global_load_lds_dwordx4 v[214:215], off
	s_add_i32 m0, s38, 0xe000
	v_lshl_add_u64 v[214:215], s[26:27], 0, v[186:187]
	global_load_lds_dwordx4 v[214:215], off
	s_waitcnt vmcnt(8)
	s_waitcnt lgkmcnt(0)
	s_barrier
	v_mfma_f32_16x16x32_bf16 v[124:127], v[128:131], v[160:163], v[124:127]
	v_mfma_f32_16x16x32_bf16 v[120:123], v[136:139], v[160:163], v[120:123]
	v_mfma_f32_16x16x32_bf16 v[108:111], v[128:131], v[168:171], v[108:111]
	v_mfma_f32_16x16x32_bf16 v[104:107], v[136:139], v[168:171], v[104:107]
	v_mfma_f32_16x16x32_bf16 v[92:95], v[128:131], v[188:191], v[92:95]
	v_mfma_f32_16x16x32_bf16 v[88:91], v[136:139], v[188:191], v[88:91]
	v_mfma_f32_16x16x32_bf16 v[76:79], v[128:131], v[196:199], v[76:79]
	v_mfma_f32_16x16x32_bf16 v[72:75], v[136:139], v[196:199], v[72:75]
	v_mfma_f32_16x16x32_bf16 v[124:127], v[132:135], v[164:167], v[124:127]
	v_mfma_f32_16x16x32_bf16 v[120:123], v[140:143], v[164:167], v[120:123]
	v_mfma_f32_16x16x32_bf16 v[108:111], v[132:135], v[172:175], v[108:111]
	v_mfma_f32_16x16x32_bf16 v[104:107], v[140:143], v[172:175], v[104:107]
	v_mfma_f32_16x16x32_bf16 v[92:95], v[132:135], v[192:195], v[92:95]
	v_mfma_f32_16x16x32_bf16 v[88:91], v[140:143], v[192:195], v[88:91]
	v_mfma_f32_16x16x32_bf16 v[76:79], v[132:135], v[210:213], v[76:79]
	v_mfma_f32_16x16x32_bf16 v[72:75], v[140:143], v[210:213], v[72:75]
	v_mfma_f32_16x16x32_bf16 v[116:119], v[144:147], v[160:163], v[116:119]
	v_mfma_f32_16x16x32_bf16 v[112:115], v[152:155], v[160:163], v[112:115]
	v_mfma_f32_16x16x32_bf16 v[100:103], v[144:147], v[168:171], v[100:103]
	v_mfma_f32_16x16x32_bf16 v[96:99], v[152:155], v[168:171], v[96:99]
	v_mfma_f32_16x16x32_bf16 v[84:87], v[144:147], v[188:191], v[84:87]
	v_mfma_f32_16x16x32_bf16 v[80:83], v[152:155], v[188:191], v[80:83]
	v_mfma_f32_16x16x32_bf16 v[68:71], v[144:147], v[196:199], v[68:71]
	v_mfma_f32_16x16x32_bf16 v[64:67], v[152:155], v[196:199], v[64:67]
	v_mfma_f32_16x16x32_bf16 v[116:119], v[148:151], v[164:167], v[116:119]
	v_mfma_f32_16x16x32_bf16 v[112:115], v[156:159], v[164:167], v[112:115]
	v_mfma_f32_16x16x32_bf16 v[100:103], v[148:151], v[172:175], v[100:103]
	v_mfma_f32_16x16x32_bf16 v[96:99], v[156:159], v[172:175], v[96:99]
	v_mfma_f32_16x16x32_bf16 v[84:87], v[148:151], v[192:195], v[84:87]
	v_mfma_f32_16x16x32_bf16 v[80:83], v[156:159], v[192:195], v[80:83]
	v_mfma_f32_16x16x32_bf16 v[68:71], v[148:151], v[210:213], v[68:71]
	v_mfma_f32_16x16x32_bf16 v[64:67], v[156:159], v[210:213], v[64:67]
	s_barrier
	s_add_i32 s46, s44, s37
	v_lshl_add_u64 v[214:215], s[28:29], 0, v[178:179]
	s_mov_b32 m0, s46
	ds_read_b128 v[160:163], v208 offset:16384
	ds_read_b128 v[164:167], v208 offset:17408
	ds_read_b128 v[168:171], v208 offset:18432
	ds_read_b128 v[172:175], v208 offset:19456
	ds_read_b128 v[188:191], v208 offset:20480
	ds_read_b128 v[192:195], v208 offset:21504
	ds_read_b128 v[196:199], v208 offset:22528
	ds_read_b128 v[210:213], v208 offset:23552
	global_load_lds_dwordx4 v[214:215], off
	s_add_i32 m0, s46, 0x2000
	s_add_u32 s46, s28, 0x80000
	v_lshl_add_u64 v[216:217], s[28:29], 0, v[182:183]
	s_addc_u32 s47, s29, 0
	s_add_i32 s59, s45, s37
	global_load_lds_dwordx4 v[216:217], off
	v_lshl_add_u64 v[218:219], s[46:47], 0, v[178:179]
	s_mov_b32 m0, s59
	v_lshl_add_u64 v[220:221], s[30:31], 0, v[180:181]
	global_load_lds_dwordx4 v[218:219], off
	s_add_i32 m0, s59, 0x2000
	v_lshl_add_u64 v[218:219], s[46:47], 0, v[182:183]
	global_load_lds_dwordx4 v[218:219], off
	s_mov_b32 m0, s38
	v_lshl_add_u64 v[218:219], s[30:31], 0, v[176:177]
	global_load_lds_dwordx4 v[218:219], off
	s_mov_b32 m0, s39
	s_nop 0
	global_load_lds_dwordx4 v[220:221], off
	s_waitcnt vmcnt(8)
	s_waitcnt lgkmcnt(0)
	s_barrier
; #define PG8_STAGE(bufoff, gbase, voff) do { _Pragma("unroll") for (int _i = 0; _i < 2; ++_i) \
;         __builtin_amdgcn_global_load_lds((const unsigned*)((const char*)(gbase) + (voff)[_i]), (LAS unsigned*)(lds + (bufoff) + ldsw + _i * 8192), 16, 0, 0); } while (0)
; #define PG8_LDA(dst, b, h) do { _Pragma("unroll") for (int m = 0; m < 4; ++m) _Pragma("unroll") for (int k = 0; k < 2; ++k) dst[m][k] = *(const LAS bf16x8*)(lds + PG8_SA(b, h) + aoff + m * 2048 + k * 1024); } while (0)
; #define PG8_LDB(dst, b, h) do { _Pragma("unroll") for (int n = 0; n < 2; ++n) _Pragma("unroll") for (int k = 0; k < 2; ++k) dst[n][k] = *(const LAS bf16x8*)(lds + PG8_SB(b, h) + boff + n * 2048 + k * 1024); } while (0)
; #define PG8_MMA(ai, bj, At, Bt) do { __builtin_amdgcn_s_setprio(1); _Pragma("unroll") for (int m = 0; m < 4; ++m) _Pragma("unroll") for (int n = 0; n < 2; ++n) _Pragma("unroll") for (int k = 0; k < 2; ++k) \
;         acc[ai][bj][m][n] = __builtin_amdgcn_mfma_f32_16x16x32_bf16(Bt[n][k], At[m][k], acc[ai][bj][m][n], 0, 0, 0); __builtin_amdgcn_s_setprio(0); } while (0)
; #define PG8_WAIT_V(n) asm volatile("s_waitcnt vmcnt(" #n ")" ::: "memory")
; #define PG8_WAIT_L(n) asm volatile("s_waitcnt lgkmcnt(" #n ")" ::: "memory")
; #define PG8_BAR __builtin_amdgcn_s_barrier()
; #define PG8_SCHED __builtin_amdgcn_sched_barrier(0)
; template <class Epi, class Sched, bool ALIGN_EPI = true>
; __device__ __forceinline__ void gemm_phase(LAS unsigned char* lds, const Gemm g, const Sched& S, const Epi& E) {
;     ...
;             PG8_WAIT_V(8); PG8_WAIT_L(0); PG8_BAR; PG8_MMA(1, 0, At, B0); PG8_MMA(1, 1, At, B1); PG8_BAR; PG8_SCHED;
;             PG8_LDB(B0, 1, 0); PG8_LDB(B1, 1, 1); PG8_SCHED; PG8_LDA(At, 1, 0); PG8_STAGE(PG8_SA(0, 1), a2 + hstep, voffA);
;             PG8_WAIT_V(8); PG8_WAIT_L(0); PG8_BAR; PG8_MMA(0, 0, At, B0); PG8_MMA(0, 1, At, B1); PG8_BAR; PG8_SCHED;
;             PG8_LDA(At, 1, 1); PG8_STAGE(PG8_SB(1, 0), b3, voffB); PG8_STAGE(PG8_SB(1, 1), b3 + hstep, voffB); PG8_STAGE(PG8_SA(1, 0), a3, voffA);
	v_mfma_f32_16x16x32_bf16 v[60:63], v[128:131], v[160:163], v[60:63]
	v_mfma_f32_16x16x32_bf16 v[56:59], v[136:139], v[160:163], v[56:59]
	v_mfma_f32_16x16x32_bf16 v[44:47], v[128:131], v[168:171], v[44:47]
	v_mfma_f32_16x16x32_bf16 v[40:43], v[136:139], v[168:171], v[40:43]
	v_mfma_f32_16x16x32_bf16 v[28:31], v[128:131], v[188:191], v[28:31]
	v_mfma_f32_16x16x32_bf16 v[24:27], v[136:139], v[188:191], v[24:27]
	v_mfma_f32_16x16x32_bf16 v[12:15], v[128:131], v[196:199], v[12:15]
	v_mfma_f32_16x16x32_bf16 v[8:11], v[136:139], v[196:199], v[8:11]
	v_mfma_f32_16x16x32_bf16 v[60:63], v[132:135], v[164:167], v[60:63]
	v_mfma_f32_16x16x32_bf16 v[56:59], v[140:143], v[164:167], v[56:59]
	v_mfma_f32_16x16x32_bf16 v[44:47], v[132:135], v[172:175], v[44:47]
	v_mfma_f32_16x16x32_bf16 v[40:43], v[140:143], v[172:175], v[40:43]
	v_mfma_f32_16x16x32_bf16 v[28:31], v[132:135], v[192:195], v[28:31]
	v_mfma_f32_16x16x32_bf16 v[24:27], v[140:143], v[192:195], v[24:27]
	v_mfma_f32_16x16x32_bf16 v[12:15], v[132:135], v[210:213], v[12:15]
	v_mfma_f32_16x16x32_bf16 v[8:11], v[140:143], v[210:213], v[8:11]
	v_mfma_f32_16x16x32_bf16 v[52:55], v[144:147], v[160:163], v[52:55]
	v_mfma_f32_16x16x32_bf16 v[48:51], v[152:155], v[160:163], v[48:51]
	v_mfma_f32_16x16x32_bf16 v[36:39], v[144:147], v[168:171], v[36:39]
	v_mfma_f32_16x16x32_bf16 v[32:35], v[152:155], v[168:171], v[32:35]
	v_mfma_f32_16x16x32_bf16 v[20:23], v[144:147], v[188:191], v[20:23]
	v_mfma_f32_16x16x32_bf16 v[16:19], v[152:155], v[188:191], v[16:19]
	v_mfma_f32_16x16x32_bf16 v[4:7], v[144:147], v[196:199], v[4:7]
	v_mfma_f32_16x16x32_bf16 v[0:3], v[152:155], v[196:199], v[0:3]
	v_mfma_f32_16x16x32_bf16 v[52:55], v[148:151], v[164:167], v[52:55]
	v_mfma_f32_16x16x32_bf16 v[48:51], v[156:159], v[164:167], v[48:51]
	v_mfma_f32_16x16x32_bf16 v[36:39], v[148:151], v[172:175], v[36:39]
	v_mfma_f32_16x16x32_bf16 v[32:35], v[156:159], v[172:175], v[32:35]
	v_mfma_f32_16x16x32_bf16 v[20:23], v[148:151], v[192:195], v[20:23]
	v_mfma_f32_16x16x32_bf16 v[16:19], v[156:159], v[192:195], v[16:19]
	v_mfma_f32_16x16x32_bf16 v[4:7], v[148:151], v[210:213], v[4:7]
	v_mfma_f32_16x16x32_bf16 v[0:3], v[156:159], v[210:213], v[0:3]
	s_barrier
	s_add_i32 s46, 0, 0x18000
	s_add_i32 s47, 0, 0x1c000
	v_add_u32_e32 v140, s46, v204
	v_add_u32_e32 v156, s47, v204
	ds_read_b128 v[128:131], v140
	ds_read_b128 v[132:135], v140 offset:1024
	ds_read_b128 v[136:139], v140 offset:2048
	ds_read_b128 v[140:143], v140 offset:3072
	ds_read_b128 v[144:147], v156
	ds_read_b128 v[148:151], v156 offset:1024
	ds_read_b128 v[152:155], v156 offset:2048
	ds_read_b128 v[156:159], v156 offset:3072
	s_add_u32 s30, s30, 0x80000
	s_addc_u32 s31, s31, 0
	s_mov_b32 m0, s40
	v_lshl_add_u64 v[222:223], s[30:31], 0, v[176:177]
	ds_read_b128 v[160:163], v208 offset:32768
	ds_read_b128 v[164:167], v208 offset:33792
	ds_read_b128 v[168:171], v208 offset:34816
	ds_read_b128 v[172:175], v208 offset:35840
	ds_read_b128 v[188:191], v208 offset:36864
	ds_read_b128 v[192:195], v208 offset:37888
	ds_read_b128 v[196:199], v208 offset:38912
	ds_read_b128 v[210:213], v208 offset:39936
	global_load_lds_dwordx4 v[222:223], off
	s_mov_b32 m0, s41
	v_lshl_add_u64 v[222:223], s[30:31], 0, v[180:181]
	global_load_lds_dwordx4 v[222:223], off
	s_waitcnt vmcnt(8)
	s_waitcnt lgkmcnt(0)
	s_barrier
	v_mfma_f32_16x16x32_bf16 v[124:127], v[128:131], v[160:163], v[124:127]
	v_mfma_f32_16x16x32_bf16 v[120:123], v[136:139], v[160:163], v[120:123]
	v_mfma_f32_16x16x32_bf16 v[108:111], v[128:131], v[168:171], v[108:111]
	v_mfma_f32_16x16x32_bf16 v[104:107], v[136:139], v[168:171], v[104:107]
	v_mfma_f32_16x16x32_bf16 v[92:95], v[128:131], v[188:191], v[92:95]
	v_mfma_f32_16x16x32_bf16 v[88:91], v[136:139], v[188:191], v[88:91]
	v_mfma_f32_16x16x32_bf16 v[76:79], v[128:131], v[196:199], v[76:79]
	v_mfma_f32_16x16x32_bf16 v[72:75], v[136:139], v[196:199], v[72:75]
	v_mfma_f32_16x16x32_bf16 v[124:127], v[132:135], v[164:167], v[124:127]
	v_mfma_f32_16x16x32_bf16 v[120:123], v[140:143], v[164:167], v[120:123]
	v_mfma_f32_16x16x32_bf16 v[108:111], v[132:135], v[172:175], v[108:111]
	v_mfma_f32_16x16x32_bf16 v[104:107], v[140:143], v[172:175], v[104:107]
	v_mfma_f32_16x16x32_bf16 v[92:95], v[132:135], v[192:195], v[92:95]
	v_mfma_f32_16x16x32_bf16 v[88:91], v[140:143], v[192:195], v[88:91]
	v_mfma_f32_16x16x32_bf16 v[76:79], v[132:135], v[210:213], v[76:79]
	v_mfma_f32_16x16x32_bf16 v[72:75], v[140:143], v[210:213], v[72:75]
	v_mfma_f32_16x16x32_bf16 v[116:119], v[144:147], v[160:163], v[116:119]
	v_mfma_f32_16x16x32_bf16 v[112:115], v[152:155], v[160:163], v[112:115]
	v_mfma_f32_16x16x32_bf16 v[100:103], v[144:147], v[168:171], v[100:103]
	v_mfma_f32_16x16x32_bf16 v[96:99], v[152:155], v[168:171], v[96:99]
	v_mfma_f32_16x16x32_bf16 v[84:87], v[144:147], v[188:191], v[84:87]
	v_mfma_f32_16x16x32_bf16 v[80:83], v[152:155], v[188:191], v[80:83]
	v_mfma_f32_16x16x32_bf16 v[68:71], v[144:147], v[196:199], v[68:71]
	v_mfma_f32_16x16x32_bf16 v[64:67], v[152:155], v[196:199], v[64:67]
	v_mfma_f32_16x16x32_bf16 v[116:119], v[148:151], v[164:167], v[116:119]
	v_mfma_f32_16x16x32_bf16 v[112:115], v[156:159], v[164:167], v[112:115]
	v_mfma_f32_16x16x32_bf16 v[100:103], v[148:151], v[172:175], v[100:103]
	v_mfma_f32_16x16x32_bf16 v[96:99], v[156:159], v[172:175], v[96:99]
	v_mfma_f32_16x16x32_bf16 v[84:87], v[148:151], v[192:195], v[84:87]
	v_mfma_f32_16x16x32_bf16 v[80:83], v[156:159], v[192:195], v[80:83]
	v_mfma_f32_16x16x32_bf16 v[68:71], v[148:151], v[210:213], v[68:71]
	v_mfma_f32_16x16x32_bf16 v[64:67], v[156:159], v[210:213], v[64:67]
	s_barrier
; #define PG8_STAGE(bufoff, gbase, voff) do { _Pragma("unroll") for (int _i = 0; _i < 2; ++_i) \
;         __builtin_amdgcn_global_load_lds((const unsigned*)((const char*)(gbase) + (voff)[_i]), (LAS unsigned*)(lds + (bufoff) + ldsw + _i * 8192), 16, 0, 0); } while (0)
; #define PG8_LDA(dst, b, h) do { _Pragma("unroll") for (int m = 0; m < 4; ++m) _Pragma("unroll") for (int k = 0; k < 2; ++k) dst[m][k] = *(const LAS bf16x8*)(lds + PG8_SA(b, h) + aoff + m * 2048 + k * 1024); } while (0)
; #define PG8_MMA(ai, bj, At, Bt) do { __builtin_amdgcn_s_setprio(1); _Pragma("unroll") for (int m = 0; m < 4; ++m) _Pragma("unroll") for (int n = 0; n < 2; ++n) _Pragma("unroll") for (int k = 0; k < 2; ++k) \
;         acc[ai][bj][m][n] = __builtin_amdgcn_mfma_f32_16x16x32_bf16(Bt[n][k], At[m][k], acc[ai][bj][m][n], 0, 0, 0); __builtin_amdgcn_s_setprio(0); } while (0)
; #define PG8_WAIT_V(n) asm volatile("s_waitcnt vmcnt(" #n ")" ::: "memory")
; #define PG8_WAIT_L(n) asm volatile("s_waitcnt lgkmcnt(" #n ")" ::: "memory")
; #define PG8_BAR __builtin_amdgcn_s_barrier()
; #define PG8_SCHED __builtin_amdgcn_sched_barrier(0)
; template <class Epi, class Sched, bool ALIGN_EPI = true>
; __device__ __forceinline__ void gemm_phase(LAS unsigned char* lds, const Gemm g, const Sched& S, const Epi& E) {
;     ...
;             PG8_LDA(At, 1, 1); PG8_STAGE(PG8_SB(1, 0), b3, voffB); PG8_STAGE(PG8_SB(1, 1), b3 + hstep, voffB); PG8_STAGE(PG8_SA(1, 0), a3, voffA);
;             PG8_WAIT_V(8); PG8_WAIT_L(0); PG8_BAR; PG8_MMA(1, 0, At, B0); PG8_MMA(1, 1, At, B1); PG8_BAR; PG8_SCHED;
;         }
	s_add_i32 s30, s46, s37
	v_lshl_add_u64 v[214:215], v[214:215], 0, s[20:21]
	s_mov_b32 m0, s30
	ds_read_b128 v[160:163], v208 offset:49152
	ds_read_b128 v[164:167], v208 offset:50176
	ds_read_b128 v[168:171], v208 offset:51200
	ds_read_b128 v[172:175], v208 offset:52224
	ds_read_b128 v[188:191], v208 offset:53248
	ds_read_b128 v[192:195], v208 offset:54272
	ds_read_b128 v[196:199], v208 offset:55296
	ds_read_b128 v[210:213], v208 offset:56320
	global_load_lds_dwordx4 v[214:215], off
	s_add_i32 m0, s30, 0x2000
	s_add_u32 s28, s28, 0x80080
	v_lshl_add_u64 v[214:215], v[216:217], 0, s[20:21]
	s_addc_u32 s29, s29, 0
	s_add_i32 s30, s47, s37
	global_load_lds_dwordx4 v[214:215], off
	s_mov_b32 m0, s30
	v_lshl_add_u64 v[214:215], s[28:29], 0, v[178:179]
	global_load_lds_dwordx4 v[214:215], off
	s_add_i32 m0, s30, 0x2000
	v_lshl_add_u64 v[214:215], s[28:29], 0, v[182:183]
	global_load_lds_dwordx4 v[214:215], off
	s_mov_b32 m0, s42
	v_lshl_add_u64 v[214:215], v[218:219], 0, s[20:21]
	global_load_lds_dwordx4 v[214:215], off
	s_mov_b32 m0, s43
	v_lshl_add_u64 v[214:215], v[220:221], 0, s[20:21]
	global_load_lds_dwordx4 v[214:215], off
	s_waitcnt vmcnt(8)
	s_waitcnt lgkmcnt(0)
	s_barrier
	v_mfma_f32_16x16x32_bf16 v[60:63], v[128:131], v[160:163], v[60:63]
	v_mfma_f32_16x16x32_bf16 v[56:59], v[136:139], v[160:163], v[56:59]
	v_mfma_f32_16x16x32_bf16 v[44:47], v[128:131], v[168:171], v[44:47]
	v_mfma_f32_16x16x32_bf16 v[40:43], v[136:139], v[168:171], v[40:43]
	v_mfma_f32_16x16x32_bf16 v[28:31], v[128:131], v[188:191], v[28:31]
	v_mfma_f32_16x16x32_bf16 v[24:27], v[136:139], v[188:191], v[24:27]
	v_mfma_f32_16x16x32_bf16 v[12:15], v[128:131], v[196:199], v[12:15]
	v_mfma_f32_16x16x32_bf16 v[8:11], v[136:139], v[196:199], v[8:11]
	v_mfma_f32_16x16x32_bf16 v[60:63], v[132:135], v[164:167], v[60:63]
	v_mfma_f32_16x16x32_bf16 v[56:59], v[140:143], v[164:167], v[56:59]
	v_mfma_f32_16x16x32_bf16 v[44:47], v[132:135], v[172:175], v[44:47]
	v_mfma_f32_16x16x32_bf16 v[40:43], v[140:143], v[172:175], v[40:43]
	v_mfma_f32_16x16x32_bf16 v[28:31], v[132:135], v[192:195], v[28:31]
	v_mfma_f32_16x16x32_bf16 v[24:27], v[140:143], v[192:195], v[24:27]
	v_mfma_f32_16x16x32_bf16 v[12:15], v[132:135], v[210:213], v[12:15]
	v_mfma_f32_16x16x32_bf16 v[8:11], v[140:143], v[210:213], v[8:11]
	v_mfma_f32_16x16x32_bf16 v[52:55], v[144:147], v[160:163], v[52:55]
	v_mfma_f32_16x16x32_bf16 v[48:51], v[152:155], v[160:163], v[48:51]
	v_mfma_f32_16x16x32_bf16 v[36:39], v[144:147], v[168:171], v[36:39]
	v_mfma_f32_16x16x32_bf16 v[32:35], v[152:155], v[168:171], v[32:35]
	v_mfma_f32_16x16x32_bf16 v[20:23], v[144:147], v[188:191], v[20:23]
	v_mfma_f32_16x16x32_bf16 v[16:19], v[152:155], v[188:191], v[16:19]
	v_mfma_f32_16x16x32_bf16 v[4:7], v[144:147], v[196:199], v[4:7]
	v_mfma_f32_16x16x32_bf16 v[0:3], v[152:155], v[196:199], v[0:3]
	v_mfma_f32_16x16x32_bf16 v[52:55], v[148:151], v[164:167], v[52:55]
	v_mfma_f32_16x16x32_bf16 v[48:51], v[156:159], v[164:167], v[48:51]
	v_mfma_f32_16x16x32_bf16 v[36:39], v[148:151], v[172:175], v[36:39]
	v_mfma_f32_16x16x32_bf16 v[32:35], v[156:159], v[172:175], v[32:35]
	v_mfma_f32_16x16x32_bf16 v[20:23], v[148:151], v[192:195], v[20:23]
	v_mfma_f32_16x16x32_bf16 v[16:19], v[156:159], v[192:195], v[16:19]
	v_mfma_f32_16x16x32_bf16 v[4:7], v[148:151], v[210:213], v[4:7]
	v_mfma_f32_16x16x32_bf16 v[0:3], v[156:159], v[210:213], v[0:3]
	s_barrier
	s_add_i32 s58, s58, 2
	s_add_u32 s26, s26, 0x100
	s_addc_u32 s27, s27, 0
	s_add_u32 s56, s56, 0x100
	s_addc_u32 s57, s57, 0
	s_cmp_gt_u32 s58, 29
	s_cbranch_scc0 .LBB0_560
	s_and_b64 vcc, exec, s[22:23]
	s_cbranch_vccz .LBB0_563
	s_barrier

; #define PG8_STAGE(bufoff, gbase, voff) do { _Pragma("unroll") for (int _i = 0; _i < 2; ++_i) \
;         __builtin_amdgcn_global_load_lds((const unsigned*)((const char*)(gbase) + (voff)[_i]), (LAS unsigned*)(lds + (bufoff) + ldsw + _i * 8192), 16, 0, 0); } while (0)
; #define PG8_LDA(dst, b, h) do { _Pragma("unroll") for (int m = 0; m < 4; ++m) _Pragma("unroll") for (int k = 0; k < 2; ++k) dst[m][k] = *(const LAS bf16x8*)(lds + PG8_SA(b, h) + aoff + m * 2048 + k * 1024); } while (0)
; #define PG8_LDB(dst, b, h) do { _Pragma("unroll") for (int n = 0; n < 2; ++n) _Pragma("unroll") for (int k = 0; k < 2; ++k) dst[n][k] = *(const LAS bf16x8*)(lds + PG8_SB(b, h) + boff + n * 2048 + k * 1024); } while (0)
; #define PG8_MMA(ai, bj, At, Bt) do { __builtin_amdgcn_s_setprio(1); _Pragma("unroll") for (int m = 0; m < 4; ++m) _Pragma("unroll") for (int n = 0; n < 2; ++n) _Pragma("unroll") for (int k = 0; k < 2; ++k) \
;         acc[ai][bj][m][n] = __builtin_amdgcn_mfma_f32_16x16x32_bf16(Bt[n][k], At[m][k], acc[ai][bj][m][n], 0, 0, 0); __builtin_amdgcn_s_setprio(0); } while (0)
; #define PG8_WAIT_V(n) asm volatile("s_waitcnt vmcnt(" #n ")" ::: "memory")
; #define PG8_WAIT_L(n) asm volatile("s_waitcnt lgkmcnt(" #n ")" ::: "memory")
; #define PG8_BAR __builtin_amdgcn_s_barrier()
; #define PG8_SCHED __builtin_amdgcn_sched_barrier(0)
; template <class Epi, class Sched, bool ALIGN_EPI = true>
; __device__ __forceinline__ void gemm_phase(LAS unsigned char* lds, const Gemm g, const Sched& S, const Epi& E) {
;     ...
;             const char* a1 = cA + (size_t)(t + 1) * kstep;
;             const char* a2 = last ? nA : cA + (size_t)(t + 2) * kstep; const char* b2 = last ? nB : cB + (size_t)(t + 2) * kstep;
;             const char* a3 = a2 + kstep; const char* b3 = b2 + kstep;
;             PG8_LDB(B0, 0, 0); PG8_LDB(B1, 0, 1); PG8_SCHED; PG8_LDA(At, 0, 0); PG8_STAGE(PG8_SA(1, 1), a1 + hstep, voffA);
;             PG8_WAIT_V(8); PG8_WAIT_L(0); PG8_BAR; PG8_MMA(0, 0, At, B0); PG8_MMA(0, 1, At, B1); PG8_BAR; PG8_SCHED;
;             PG8_LDA(At, 0, 1); PG8_STAGE(PG8_SB(0, 0), b2, voffB); PG8_STAGE(PG8_SB(0, 1), b2 + hstep, voffB); PG8_STAGE(PG8_SA(0, 0), a2, voffA);
.LBB0_647:
	ds_read_b128 v[152:155], v147
	ds_read_b128 v[156:159], v147 offset:1024
	ds_read_b128 v[160:163], v147 offset:2048
	ds_read_b128 v[164:167], v147 offset:3072
	ds_read_b128 v[168:171], v148
	ds_read_b128 v[172:175], v148 offset:1024
	ds_read_b128 v[176:179], v148 offset:2048
	ds_read_b128 v[180:183], v148 offset:3072
	s_add_u32 s26, s24, 0xfff80080
	s_addc_u32 s27, s25, -1
	s_cmp_eq_u32 s56, 28
	s_cselect_b32 s29, s51, s27
	s_cselect_b32 s28, s52, s26
	s_cselect_b32 s27, s7, s55
	s_cselect_b32 s26, s53, s54
	v_lshl_add_u64 v[140:141], s[24:25], 0, v[136:137]
	s_add_i32 m0, s37, 0xc000
	ds_read_b128 v[184:187], v149
	ds_read_b128 v[188:191], v149 offset:1024
	ds_read_b128 v[192:195], v149 offset:2048
	ds_read_b128 v[196:199], v149 offset:3072
	ds_read_b128 v[204:207], v149 offset:4096
	ds_read_b128 v[208:211], v149 offset:5120
	ds_read_b128 v[212:215], v149 offset:6144
	ds_read_b128 v[216:219], v149 offset:7168
	global_load_lds_dwordx4 v[140:141], off
	s_add_i32 m0, s37, 0xe000
	v_lshl_add_u64 v[140:141], s[24:25], 0, v[138:139]
	global_load_lds_dwordx4 v[140:141], off
	s_waitcnt vmcnt(8)
	s_waitcnt lgkmcnt(0)
	s_barrier
	v_mfma_f32_16x16x32_bf16 v[112:115], v[152:155], v[184:187], v[112:115]
	v_mfma_f32_16x16x32_bf16 v[108:111], v[160:163], v[184:187], v[108:111]
	v_mfma_f32_16x16x32_bf16 v[100:103], v[152:155], v[192:195], v[100:103]
	v_mfma_f32_16x16x32_bf16 v[96:99], v[160:163], v[192:195], v[96:99]
	v_mfma_f32_16x16x32_bf16 v[92:95], v[152:155], v[204:207], v[92:95]
	v_mfma_f32_16x16x32_bf16 v[84:87], v[160:163], v[204:207], v[84:87]
	v_mfma_f32_16x16x32_bf16 v[76:79], v[152:155], v[212:215], v[76:79]
	v_mfma_f32_16x16x32_bf16 v[68:71], v[160:163], v[212:215], v[68:71]
	v_mfma_f32_16x16x32_bf16 v[112:115], v[156:159], v[188:191], v[112:115]
	v_mfma_f32_16x16x32_bf16 v[108:111], v[164:167], v[188:191], v[108:111]
	v_mfma_f32_16x16x32_bf16 v[100:103], v[156:159], v[196:199], v[100:103]
	v_mfma_f32_16x16x32_bf16 v[96:99], v[164:167], v[196:199], v[96:99]
	v_mfma_f32_16x16x32_bf16 v[92:95], v[156:159], v[208:211], v[92:95]
	v_mfma_f32_16x16x32_bf16 v[84:87], v[164:167], v[208:211], v[84:87]
	v_mfma_f32_16x16x32_bf16 v[76:79], v[156:159], v[216:219], v[76:79]
	v_mfma_f32_16x16x32_bf16 v[68:71], v[164:167], v[216:219], v[68:71]
	v_mfma_f32_16x16x32_bf16 v[124:127], v[168:171], v[184:187], v[124:127]
	v_mfma_f32_16x16x32_bf16 v[120:123], v[176:179], v[184:187], v[120:123]
	v_mfma_f32_16x16x32_bf16 v[116:119], v[168:171], v[192:195], v[116:119]
	v_mfma_f32_16x16x32_bf16 v[104:107], v[176:179], v[192:195], v[104:107]
	v_mfma_f32_16x16x32_bf16 v[88:91], v[168:171], v[204:207], v[88:91]
	v_mfma_f32_16x16x32_bf16 v[80:83], v[176:179], v[204:207], v[80:83]
	v_mfma_f32_16x16x32_bf16 v[72:75], v[168:171], v[212:215], v[72:75]
	v_mfma_f32_16x16x32_bf16 v[64:67], v[176:179], v[212:215], v[64:67]
	v_mfma_f32_16x16x32_bf16 v[124:127], v[172:175], v[188:191], v[124:127]
	v_mfma_f32_16x16x32_bf16 v[120:123], v[180:183], v[188:191], v[120:123]
	v_mfma_f32_16x16x32_bf16 v[116:119], v[172:175], v[196:199], v[116:119]
	v_mfma_f32_16x16x32_bf16 v[104:107], v[180:183], v[196:199], v[104:107]
	v_mfma_f32_16x16x32_bf16 v[88:91], v[172:175], v[208:211], v[88:91]
	v_mfma_f32_16x16x32_bf16 v[80:83], v[180:183], v[208:211], v[80:83]
	v_mfma_f32_16x16x32_bf16 v[72:75], v[172:175], v[216:219], v[72:75]
	v_mfma_f32_16x16x32_bf16 v[64:67], v[180:183], v[216:219], v[64:67]
	s_barrier
	s_add_i32 s46, s43, s36
	v_lshl_add_u64 v[140:141], s[26:27], 0, v[130:131]
	s_mov_b32 m0, s46
	ds_read_b128 v[184:187], v149 offset:16384
	ds_read_b128 v[188:191], v149 offset:17408
	ds_read_b128 v[192:195], v149 offset:18432
	ds_read_b128 v[196:199], v149 offset:19456
	ds_read_b128 v[204:207], v149 offset:20480
	ds_read_b128 v[208:211], v149 offset:21504
	ds_read_b128 v[212:215], v149 offset:22528
	ds_read_b128 v[216:219], v149 offset:23552
	global_load_lds_dwordx4 v[140:141], off
	s_add_i32 m0, s46, 0x2000
	s_add_u32 s46, s26, 0x80000
	v_lshl_add_u64 v[200:201], s[26:27], 0, v[134:135]
	s_addc_u32 s47, s27, 0
	s_add_i32 s57, s44, s36
	global_load_lds_dwordx4 v[200:201], off
	v_lshl_add_u64 v[220:221], s[46:47], 0, v[130:131]
	s_mov_b32 m0, s57
	v_lshl_add_u64 v[222:223], s[28:29], 0, v[132:133]
	global_load_lds_dwordx4 v[220:221], off
	s_add_i32 m0, s57, 0x2000
	v_lshl_add_u64 v[220:221], s[46:47], 0, v[134:135]
	global_load_lds_dwordx4 v[220:221], off
	s_mov_b32 m0, s37
	v_lshl_add_u64 v[220:221], s[28:29], 0, v[128:129]
	global_load_lds_dwordx4 v[220:221], off
	s_mov_b32 m0, s38
	s_nop 0
	global_load_lds_dwordx4 v[222:223], off
	s_waitcnt vmcnt(8)
	s_waitcnt lgkmcnt(0)
	s_barrier
; #define PG8_STAGE(bufoff, gbase, voff) do { _Pragma("unroll") for (int _i = 0; _i < 2; ++_i) \
;         __builtin_amdgcn_global_load_lds((const unsigned*)((const char*)(gbase) + (voff)[_i]), (LAS unsigned*)(lds + (bufoff) + ldsw + _i * 8192), 16, 0, 0); } while (0)
; #define PG8_LDA(dst, b, h) do { _Pragma("unroll") for (int m = 0; m < 4; ++m) _Pragma("unroll") for (int k = 0; k < 2; ++k) dst[m][k] = *(const LAS bf16x8*)(lds + PG8_SA(b, h) + aoff + m * 2048 + k * 1024); } while (0)
; #define PG8_LDB(dst, b, h) do { _Pragma("unroll") for (int n = 0; n < 2; ++n) _Pragma("unroll") for (int k = 0; k < 2; ++k) dst[n][k] = *(const LAS bf16x8*)(lds + PG8_SB(b, h) + boff + n * 2048 + k * 1024); } while (0)
; #define PG8_MMA(ai, bj, At, Bt) do { __builtin_amdgcn_s_setprio(1); _Pragma("unroll") for (int m = 0; m < 4; ++m) _Pragma("unroll") for (int n = 0; n < 2; ++n) _Pragma("unroll") for (int k = 0; k < 2; ++k) \
;         acc[ai][bj][m][n] = __builtin_amdgcn_mfma_f32_16x16x32_bf16(Bt[n][k], At[m][k], acc[ai][bj][m][n], 0, 0, 0); __builtin_amdgcn_s_setprio(0); } while (0)
; #define PG8_WAIT_V(n) asm volatile("s_waitcnt vmcnt(" #n ")" ::: "memory")
; #define PG8_WAIT_L(n) asm volatile("s_waitcnt lgkmcnt(" #n ")" ::: "memory")
; #define PG8_BAR __builtin_amdgcn_s_barrier()
; #define PG8_SCHED __builtin_amdgcn_sched_barrier(0)
; template <class Epi, class Sched, bool ALIGN_EPI = true>
; __device__ __forceinline__ void gemm_phase(LAS unsigned char* lds, const Gemm g, const Sched& S, const Epi& E) {
;     ...
;             PG8_WAIT_V(8); PG8_WAIT_L(0); PG8_BAR; PG8_MMA(1, 0, At, B0); PG8_MMA(1, 1, At, B1); PG8_BAR; PG8_SCHED;
;             PG8_LDB(B0, 1, 0); PG8_LDB(B1, 1, 1); PG8_SCHED; PG8_LDA(At, 1, 0); PG8_STAGE(PG8_SA(0, 1), a2 + hstep, voffA);
;             PG8_WAIT_V(8); PG8_WAIT_L(0); PG8_BAR; PG8_MMA(0, 0, At, B0); PG8_MMA(0, 1, At, B1); PG8_BAR; PG8_SCHED;
;             PG8_LDA(At, 1, 1); PG8_STAGE(PG8_SB(1, 0), b3, voffB); PG8_STAGE(PG8_SB(1, 1), b3 + hstep, voffB); PG8_STAGE(PG8_SA(1, 0), a3, voffA);
	v_mfma_f32_16x16x32_bf16 v[60:63], v[152:155], v[184:187], v[60:63]
	v_mfma_f32_16x16x32_bf16 v[52:55], v[160:163], v[184:187], v[52:55]
	v_mfma_f32_16x16x32_bf16 v[44:47], v[152:155], v[192:195], v[44:47]
	v_mfma_f32_16x16x32_bf16 v[36:39], v[160:163], v[192:195], v[36:39]
	v_mfma_f32_16x16x32_bf16 v[28:31], v[152:155], v[204:207], v[28:31]
	v_mfma_f32_16x16x32_bf16 v[20:23], v[160:163], v[204:207], v[20:23]
	v_mfma_f32_16x16x32_bf16 v[12:15], v[152:155], v[212:215], v[12:15]
	v_mfma_f32_16x16x32_bf16 v[4:7], v[160:163], v[212:215], v[4:7]
	v_mfma_f32_16x16x32_bf16 v[60:63], v[156:159], v[188:191], v[60:63]
	v_mfma_f32_16x16x32_bf16 v[52:55], v[164:167], v[188:191], v[52:55]
	v_mfma_f32_16x16x32_bf16 v[44:47], v[156:159], v[196:199], v[44:47]
	v_mfma_f32_16x16x32_bf16 v[36:39], v[164:167], v[196:199], v[36:39]
	v_mfma_f32_16x16x32_bf16 v[28:31], v[156:159], v[208:211], v[28:31]
	v_mfma_f32_16x16x32_bf16 v[20:23], v[164:167], v[208:211], v[20:23]
	v_mfma_f32_16x16x32_bf16 v[12:15], v[156:159], v[216:219], v[12:15]
	v_mfma_f32_16x16x32_bf16 v[4:7], v[164:167], v[216:219], v[4:7]
	v_mfma_f32_16x16x32_bf16 v[56:59], v[168:171], v[184:187], v[56:59]
	v_mfma_f32_16x16x32_bf16 v[48:51], v[176:179], v[184:187], v[48:51]
	v_mfma_f32_16x16x32_bf16 v[40:43], v[168:171], v[192:195], v[40:43]
	v_mfma_f32_16x16x32_bf16 v[32:35], v[176:179], v[192:195], v[32:35]
	v_mfma_f32_16x16x32_bf16 v[24:27], v[168:171], v[204:207], v[24:27]
	v_mfma_f32_16x16x32_bf16 v[16:19], v[176:179], v[204:207], v[16:19]
	v_mfma_f32_16x16x32_bf16 v[8:11], v[168:171], v[212:215], v[8:11]
	v_mfma_f32_16x16x32_bf16 v[0:3], v[176:179], v[212:215], v[0:3]
	v_mfma_f32_16x16x32_bf16 v[56:59], v[172:175], v[188:191], v[56:59]
	v_mfma_f32_16x16x32_bf16 v[48:51], v[180:183], v[188:191], v[48:51]
	v_mfma_f32_16x16x32_bf16 v[40:43], v[172:175], v[196:199], v[40:43]
	v_mfma_f32_16x16x32_bf16 v[32:35], v[180:183], v[196:199], v[32:35]
	v_mfma_f32_16x16x32_bf16 v[24:27], v[172:175], v[208:211], v[24:27]
	v_mfma_f32_16x16x32_bf16 v[16:19], v[180:183], v[208:211], v[16:19]
	v_mfma_f32_16x16x32_bf16 v[8:11], v[172:175], v[216:219], v[8:11]
	v_mfma_f32_16x16x32_bf16 v[0:3], v[180:183], v[216:219], v[0:3]
	s_barrier
	s_add_i32 s46, 0, 0x18000
	v_add_u32_e32 v151, s46, v145
	s_add_i32 s47, 0, 0x1c000
	ds_read_b128 v[152:155], v151
	ds_read_b128 v[156:159], v151 offset:1024
	ds_read_b128 v[160:163], v151 offset:2048
	ds_read_b128 v[164:167], v151 offset:3072
	v_add_u32_e32 v151, s47, v145
	ds_read_b128 v[168:171], v151
	ds_read_b128 v[172:175], v151 offset:1024
	ds_read_b128 v[176:179], v151 offset:2048
	ds_read_b128 v[180:183], v151 offset:3072
	s_add_u32 s28, s28, 0x80000
	s_addc_u32 s29, s29, 0
	s_mov_b32 m0, s39
	v_lshl_add_u64 v[224:225], s[28:29], 0, v[128:129]
	ds_read_b128 v[184:187], v149 offset:32768
	ds_read_b128 v[188:191], v149 offset:33792
	ds_read_b128 v[192:195], v149 offset:34816
	ds_read_b128 v[196:199], v149 offset:35840
	ds_read_b128 v[204:207], v149 offset:36864
	ds_read_b128 v[208:211], v149 offset:37888
	ds_read_b128 v[212:215], v149 offset:38912
	ds_read_b128 v[216:219], v149 offset:39936
	global_load_lds_dwordx4 v[224:225], off
	s_mov_b32 m0, s40
	v_lshl_add_u64 v[224:225], s[28:29], 0, v[132:133]
	global_load_lds_dwordx4 v[224:225], off
	s_waitcnt vmcnt(8)
	s_waitcnt lgkmcnt(0)
	s_barrier
	v_mfma_f32_16x16x32_bf16 v[112:115], v[152:155], v[184:187], v[112:115]
	v_mfma_f32_16x16x32_bf16 v[108:111], v[160:163], v[184:187], v[108:111]
	v_mfma_f32_16x16x32_bf16 v[100:103], v[152:155], v[192:195], v[100:103]
	v_mfma_f32_16x16x32_bf16 v[96:99], v[160:163], v[192:195], v[96:99]
	v_mfma_f32_16x16x32_bf16 v[92:95], v[152:155], v[204:207], v[92:95]
	v_mfma_f32_16x16x32_bf16 v[84:87], v[160:163], v[204:207], v[84:87]
	v_mfma_f32_16x16x32_bf16 v[76:79], v[152:155], v[212:215], v[76:79]
	v_mfma_f32_16x16x32_bf16 v[68:71], v[160:163], v[212:215], v[68:71]
	v_mfma_f32_16x16x32_bf16 v[112:115], v[156:159], v[188:191], v[112:115]
	v_mfma_f32_16x16x32_bf16 v[108:111], v[164:167], v[188:191], v[108:111]
	v_mfma_f32_16x16x32_bf16 v[100:103], v[156:159], v[196:199], v[100:103]
	v_mfma_f32_16x16x32_bf16 v[96:99], v[164:167], v[196:199], v[96:99]
	v_mfma_f32_16x16x32_bf16 v[92:95], v[156:159], v[208:211], v[92:95]
	v_mfma_f32_16x16x32_bf16 v[84:87], v[164:167], v[208:211], v[84:87]
	v_mfma_f32_16x16x32_bf16 v[76:79], v[156:159], v[216:219], v[76:79]
	v_mfma_f32_16x16x32_bf16 v[68:71], v[164:167], v[216:219], v[68:71]
	v_mfma_f32_16x16x32_bf16 v[124:127], v[168:171], v[184:187], v[124:127]
	v_mfma_f32_16x16x32_bf16 v[120:123], v[176:179], v[184:187], v[120:123]
	v_mfma_f32_16x16x32_bf16 v[116:119], v[168:171], v[192:195], v[116:119]
	v_mfma_f32_16x16x32_bf16 v[104:107], v[176:179], v[192:195], v[104:107]
	v_mfma_f32_16x16x32_bf16 v[88:91], v[168:171], v[204:207], v[88:91]
	v_mfma_f32_16x16x32_bf16 v[80:83], v[176:179], v[204:207], v[80:83]
	v_mfma_f32_16x16x32_bf16 v[72:75], v[168:171], v[212:215], v[72:75]
	v_mfma_f32_16x16x32_bf16 v[64:67], v[176:179], v[212:215], v[64:67]
	v_mfma_f32_16x16x32_bf16 v[124:127], v[172:175], v[188:191], v[124:127]
	v_mfma_f32_16x16x32_bf16 v[120:123], v[180:183], v[188:191], v[120:123]
	v_mfma_f32_16x16x32_bf16 v[116:119], v[172:175], v[196:199], v[116:119]
	v_mfma_f32_16x16x32_bf16 v[104:107], v[180:183], v[196:199], v[104:107]
	v_mfma_f32_16x16x32_bf16 v[88:91], v[172:175], v[208:211], v[88:91]
	v_mfma_f32_16x16x32_bf16 v[80:83], v[180:183], v[208:211], v[80:83]
	v_mfma_f32_16x16x32_bf16 v[72:75], v[172:175], v[216:219], v[72:75]
	v_mfma_f32_16x16x32_bf16 v[64:67], v[180:183], v[216:219], v[64:67]
	s_barrier
; #define PG8_STAGE(bufoff, gbase, voff) do { _Pragma("unroll") for (int _i = 0; _i < 2; ++_i) \
;         __builtin_amdgcn_global_load_lds((const unsigned*)((const char*)(gbase) + (voff)[_i]), (LAS unsigned*)(lds + (bufoff) + ldsw + _i * 8192), 16, 0, 0); } while (0)
; #define PG8_LDA(dst, b, h) do { _Pragma("unroll") for (int m = 0; m < 4; ++m) _Pragma("unroll") for (int k = 0; k < 2; ++k) dst[m][k] = *(const LAS bf16x8*)(lds + PG8_SA(b, h) + aoff + m * 2048 + k * 1024); } while (0)
; #define PG8_MMA(ai, bj, At, Bt) do { __builtin_amdgcn_s_setprio(1); _Pragma("unroll") for (int m = 0; m < 4; ++m) _Pragma("unroll") for (int n = 0; n < 2; ++n) _Pragma("unroll") for (int k = 0; k < 2; ++k) \
;         acc[ai][bj][m][n] = __builtin_amdgcn_mfma_f32_16x16x32_bf16(Bt[n][k], At[m][k], acc[ai][bj][m][n], 0, 0, 0); __builtin_amdgcn_s_setprio(0); } while (0)
; #define PG8_WAIT_V(n) asm volatile("s_waitcnt vmcnt(" #n ")" ::: "memory")
; #define PG8_WAIT_L(n) asm volatile("s_waitcnt lgkmcnt(" #n ")" ::: "memory")
; #define PG8_BAR __builtin_amdgcn_s_barrier()
; #define PG8_SCHED __builtin_amdgcn_sched_barrier(0)
; template <class Epi, class Sched, bool ALIGN_EPI = true>
; __device__ __forceinline__ void gemm_phase(LAS unsigned char* lds, const Gemm g, const Sched& S, const Epi& E) {
;     ...
;             PG8_LDA(At, 1, 1); PG8_STAGE(PG8_SB(1, 0), b3, voffB); PG8_STAGE(PG8_SB(1, 1), b3 + hstep, voffB); PG8_STAGE(PG8_SA(1, 0), a3, voffA);
;             PG8_WAIT_V(8); PG8_WAIT_L(0); PG8_BAR; PG8_MMA(1, 0, At, B0); PG8_MMA(1, 1, At, B1); PG8_BAR; PG8_SCHED;
;         }
	s_add_i32 s28, s46, s36
	v_lshl_add_u64 v[140:141], v[140:141], 0, s[18:19]
	s_mov_b32 m0, s28
	ds_read_b128 v[184:187], v149 offset:49152
	ds_read_b128 v[188:191], v149 offset:50176
	ds_read_b128 v[192:195], v149 offset:51200
	ds_read_b128 v[196:199], v149 offset:52224
	ds_read_b128 v[204:207], v149 offset:53248
	ds_read_b128 v[208:211], v149 offset:54272
	ds_read_b128 v[212:215], v149 offset:55296
	ds_read_b128 v[216:219], v149 offset:56320
	global_load_lds_dwordx4 v[140:141], off
	s_add_i32 m0, s28, 0x2000
	s_add_u32 s26, s26, 0x80080
	v_lshl_add_u64 v[140:141], v[200:201], 0, s[18:19]
	s_addc_u32 s27, s27, 0
	s_add_i32 s28, s47, s36
	global_load_lds_dwordx4 v[140:141], off
	s_mov_b32 m0, s28
	v_lshl_add_u64 v[140:141], s[26:27], 0, v[130:131]
	global_load_lds_dwordx4 v[140:141], off
	s_add_i32 m0, s28, 0x2000
	v_lshl_add_u64 v[140:141], s[26:27], 0, v[134:135]
	global_load_lds_dwordx4 v[140:141], off
	s_mov_b32 m0, s41
	v_lshl_add_u64 v[140:141], v[220:221], 0, s[18:19]
	global_load_lds_dwordx4 v[140:141], off
	s_mov_b32 m0, s42
	v_lshl_add_u64 v[140:141], v[222:223], 0, s[18:19]
	global_load_lds_dwordx4 v[140:141], off
	s_waitcnt vmcnt(8)
	s_waitcnt lgkmcnt(0)
	s_barrier
	v_mfma_f32_16x16x32_bf16 v[60:63], v[152:155], v[184:187], v[60:63]
	v_mfma_f32_16x16x32_bf16 v[52:55], v[160:163], v[184:187], v[52:55]
	v_mfma_f32_16x16x32_bf16 v[44:47], v[152:155], v[192:195], v[44:47]
	v_mfma_f32_16x16x32_bf16 v[36:39], v[160:163], v[192:195], v[36:39]
	v_mfma_f32_16x16x32_bf16 v[28:31], v[152:155], v[204:207], v[28:31]
	v_mfma_f32_16x16x32_bf16 v[20:23], v[160:163], v[204:207], v[20:23]
	v_mfma_f32_16x16x32_bf16 v[12:15], v[152:155], v[212:215], v[12:15]
	v_mfma_f32_16x16x32_bf16 v[4:7], v[160:163], v[212:215], v[4:7]
	v_mfma_f32_16x16x32_bf16 v[60:63], v[156:159], v[188:191], v[60:63]
	v_mfma_f32_16x16x32_bf16 v[52:55], v[164:167], v[188:191], v[52:55]
	v_mfma_f32_16x16x32_bf16 v[44:47], v[156:159], v[196:199], v[44:47]
	v_mfma_f32_16x16x32_bf16 v[36:39], v[164:167], v[196:199], v[36:39]
	v_mfma_f32_16x16x32_bf16 v[28:31], v[156:159], v[208:211], v[28:31]
	v_mfma_f32_16x16x32_bf16 v[20:23], v[164:167], v[208:211], v[20:23]
	v_mfma_f32_16x16x32_bf16 v[12:15], v[156:159], v[216:219], v[12:15]
	v_mfma_f32_16x16x32_bf16 v[4:7], v[164:167], v[216:219], v[4:7]
	v_mfma_f32_16x16x32_bf16 v[56:59], v[168:171], v[184:187], v[56:59]
	v_mfma_f32_16x16x32_bf16 v[48:51], v[176:179], v[184:187], v[48:51]
	v_mfma_f32_16x16x32_bf16 v[40:43], v[168:171], v[192:195], v[40:43]
	v_mfma_f32_16x16x32_bf16 v[32:35], v[176:179], v[192:195], v[32:35]
	v_mfma_f32_16x16x32_bf16 v[24:27], v[168:171], v[204:207], v[24:27]
	v_mfma_f32_16x16x32_bf16 v[16:19], v[176:179], v[204:207], v[16:19]
	v_mfma_f32_16x16x32_bf16 v[8:11], v[168:171], v[212:215], v[8:11]
	v_mfma_f32_16x16x32_bf16 v[0:3], v[176:179], v[212:215], v[0:3]
	v_mfma_f32_16x16x32_bf16 v[56:59], v[172:175], v[188:191], v[56:59]
	v_mfma_f32_16x16x32_bf16 v[48:51], v[180:183], v[188:191], v[48:51]
	v_mfma_f32_16x16x32_bf16 v[40:43], v[172:175], v[196:199], v[40:43]
	v_mfma_f32_16x16x32_bf16 v[32:35], v[180:183], v[196:199], v[32:35]
	v_mfma_f32_16x16x32_bf16 v[24:27], v[172:175], v[208:211], v[24:27]
	v_mfma_f32_16x16x32_bf16 v[16:19], v[180:183], v[208:211], v[16:19]
	v_mfma_f32_16x16x32_bf16 v[8:11], v[172:175], v[216:219], v[8:11]
	v_mfma_f32_16x16x32_bf16 v[0:3], v[180:183], v[216:219], v[0:3]
	s_barrier
	s_add_i32 s56, s56, 2
	s_add_u32 s24, s24, 0x100
	s_addc_u32 s25, s25, 0
	s_add_u32 s54, s54, 0x100
	s_addc_u32 s55, s55, 0
	s_cmp_gt_u32 s56, 29
	s_cbranch_scc0 .LBB0_647
	s_and_b64 vcc, exec, s[20:21]
	s_cbranch_vccz .LBB0_650
	s_barrier

; #define PG8_STAGE(bufoff, gbase, voff) do { _Pragma("unroll") for (int _i = 0; _i < 2; ++_i) \
;         __builtin_amdgcn_global_load_lds((const unsigned*)((const char*)(gbase) + (voff)[_i]), (LAS unsigned*)(lds + (bufoff) + ldsw + _i * 8192), 16, 0, 0); } while (0)
; #define PG8_LDA(dst, b, h) do { _Pragma("unroll") for (int m = 0; m < 4; ++m) _Pragma("unroll") for (int k = 0; k < 2; ++k) dst[m][k] = *(const LAS bf16x8*)(lds + PG8_SA(b, h) + aoff + m * 2048 + k * 1024); } while (0)
; #define PG8_LDB(dst, b, h) do { _Pragma("unroll") for (int n = 0; n < 2; ++n) _Pragma("unroll") for (int k = 0; k < 2; ++k) dst[n][k] = *(const LAS bf16x8*)(lds + PG8_SB(b, h) + boff + n * 2048 + k * 1024); } while (0)
; #define PG8_MMA(ai, bj, At, Bt) do { __builtin_amdgcn_s_setprio(1); _Pragma("unroll") for (int m = 0; m < 4; ++m) _Pragma("unroll") for (int n = 0; n < 2; ++n) _Pragma("unroll") for (int k = 0; k < 2; ++k) \
;         acc[ai][bj][m][n] = __builtin_amdgcn_mfma_f32_16x16x32_bf16(Bt[n][k], At[m][k], acc[ai][bj][m][n], 0, 0, 0); __builtin_amdgcn_s_setprio(0); } while (0)
; #define PG8_WAIT_V(n) asm volatile("s_waitcnt vmcnt(" #n ")" ::: "memory")
; #define PG8_WAIT_L(n) asm volatile("s_waitcnt lgkmcnt(" #n ")" ::: "memory")
; template <class Epi, class Sched, bool ALIGN_EPI = true>
; __device__ __forceinline__ void gemm_phase(LAS unsigned char* lds, const Gemm g, const Sched& S, const Epi& E) {
;     ...
;         const bool has_next = PG8_NEXT(ui + 1, nxt);
;         const char* nA = has_next ? (const char*)g.A + (size_t)nxt.pm * tstep : cA; const char* nB = has_next ? (const char*)g.Bt + (size_t)nxt.pn * tstep : cB;
;         for (int t = 0; t < nt; t += 2) {
;             const bool last = (t == nt - 2);
;             const char* a1 = cA + (size_t)(t + 1) * kstep;
;             const char* a2 = last ? nA : cA + (size_t)(t + 2) * kstep; const char* b2 = last ? nB : cB + (size_t)(t + 2) * kstep;
;             const char* a3 = a2 + kstep; const char* b3 = b2 + kstep;
;             PG8_LDB(B0, 0, 0); PG8_LDB(B1, 0, 1); PG8_SCHED; PG8_LDA(At, 0, 0); PG8_STAGE(PG8_SA(1, 1), a1 + hstep, voffA);
;             PG8_WAIT_V(8); PG8_WAIT_L(0); PG8_BAR; PG8_MMA(0, 0, At, B0); PG8_MMA(0, 1, At, B1); PG8_BAR; PG8_SCHED;
;             PG8_LDA(At, 0, 1); PG8_STAGE(PG8_SB(0, 0), b2, voffB); PG8_STAGE(PG8_SB(0, 1), b2 + hstep, voffB); PG8_STAGE(PG8_SA(0, 0), a2, voffA);
.LBB0_667:
	v_readlane_b32 s14, v137, s56
	ds_read_b128 v[0:3], v140
	ds_read_b128 v[4:7], v140 offset:1024
	ds_read_b128 v[8:11], v140 offset:2048
	ds_read_b128 v[12:15], v140 offset:3072
	ds_read_b128 v[16:19], v141
	ds_read_b128 v[20:23], v141 offset:1024
	ds_read_b128 v[24:27], v141 offset:2048
	ds_read_b128 v[28:31], v141 offset:3072
	s_cmp_gt_i32 s14, -1
	s_mov_b64 s[48:49], s[6:7]
	s_cselect_b64 s[38:39], -1, 0
	s_lshl_b64 s[6:7], s[14:15], 17
	s_add_u32 s36, s3, s6
	s_addc_u32 s37, s50, s7
	v_readlane_b32 s34, v136, s56
	s_and_b64 s[6:7], s[38:39], exec
	s_cselect_b32 s45, s37, s43
	s_cselect_b32 s44, s36, s42
	s_ashr_i32 s35, s34, 31
	s_lshl_b64 s[6:7], s[34:35], 17
	s_add_u32 s6, s51, s6
	s_addc_u32 s7, s52, s7
	s_and_b64 s[40:41], s[38:39], exec
	s_cselect_b32 s41, s7, s49
	s_cselect_b32 s40, s6, s48
	s_add_u32 s46, s42, 0x10080
	s_addc_u32 s47, s43, 0
	s_mov_b32 m0, s59
	v_lshl_add_u64 v[64:65], s[46:47], 0, v[128:129]
	ds_read_b128 v[32:35], v142
	ds_read_b128 v[36:39], v142 offset:1024
	ds_read_b128 v[40:43], v142 offset:2048
	ds_read_b128 v[44:47], v142 offset:3072
	ds_read_b128 v[48:51], v142 offset:4096
	ds_read_b128 v[52:55], v142 offset:5120
	ds_read_b128 v[56:59], v142 offset:6144
	ds_read_b128 v[60:63], v142 offset:7168
	global_load_lds_dwordx4 v[64:65], off
	s_mov_b32 m0, s60
	v_lshl_add_u64 v[64:65], s[46:47], 0, v[132:133]
	global_load_lds_dwordx4 v[64:65], off
	s_waitcnt vmcnt(8)
	s_waitcnt lgkmcnt(0)
	s_barrier
	v_mfma_f32_16x16x32_bf16 v[64:67], v[0:3], v[32:35], 0
	v_mfma_f32_16x16x32_bf16 v[68:71], v[8:11], v[32:35], 0
	v_mfma_f32_16x16x32_bf16 v[72:75], v[0:3], v[40:43], 0
	v_mfma_f32_16x16x32_bf16 v[76:79], v[8:11], v[40:43], 0
	v_mfma_f32_16x16x32_bf16 v[80:83], v[0:3], v[48:51], 0
	v_mfma_f32_16x16x32_bf16 v[84:87], v[8:11], v[48:51], 0
	v_mfma_f32_16x16x32_bf16 v[88:91], v[0:3], v[56:59], 0
	v_mfma_f32_16x16x32_bf16 v[92:95], v[8:11], v[56:59], 0
	v_mfma_f32_16x16x32_bf16 v[64:67], v[4:7], v[36:39], v[64:67]
	v_mfma_f32_16x16x32_bf16 v[68:71], v[12:15], v[36:39], v[68:71]
	v_mfma_f32_16x16x32_bf16 v[72:75], v[4:7], v[44:47], v[72:75]
	v_mfma_f32_16x16x32_bf16 v[76:79], v[12:15], v[44:47], v[76:79]
	v_mfma_f32_16x16x32_bf16 v[80:83], v[4:7], v[52:55], v[80:83]
	v_mfma_f32_16x16x32_bf16 v[84:87], v[12:15], v[52:55], v[84:87]
	v_mfma_f32_16x16x32_bf16 v[88:91], v[4:7], v[60:63], v[88:91]
	v_mfma_f32_16x16x32_bf16 v[92:95], v[12:15], v[60:63], v[92:95]
	v_mfma_f32_16x16x32_bf16 v[96:99], v[16:19], v[32:35], 0
	v_mfma_f32_16x16x32_bf16 v[32:35], v[24:27], v[32:35], 0
	v_mfma_f32_16x16x32_bf16 v[96:99], v[20:23], v[36:39], v[96:99]
	v_mfma_f32_16x16x32_bf16 v[32:35], v[28:31], v[36:39], v[32:35]
	v_mfma_f32_16x16x32_bf16 v[36:39], v[16:19], v[40:43], 0
	v_mfma_f32_16x16x32_bf16 v[40:43], v[24:27], v[40:43], 0
	v_mfma_f32_16x16x32_bf16 v[36:39], v[20:23], v[44:47], v[36:39]
	v_mfma_f32_16x16x32_bf16 v[40:43], v[28:31], v[44:47], v[40:43]
	v_mfma_f32_16x16x32_bf16 v[44:47], v[16:19], v[48:51], 0
	v_mfma_f32_16x16x32_bf16 v[48:51], v[24:27], v[48:51], 0
	v_mfma_f32_16x16x32_bf16 v[44:47], v[20:23], v[52:55], v[44:47]
	v_mfma_f32_16x16x32_bf16 v[48:51], v[28:31], v[52:55], v[48:51]
	v_mfma_f32_16x16x32_bf16 v[52:55], v[16:19], v[56:59], 0
	v_mfma_f32_16x16x32_bf16 v[56:59], v[24:27], v[56:59], 0
	v_mfma_f32_16x16x32_bf16 v[52:55], v[20:23], v[60:63], v[52:55]
	v_mfma_f32_16x16x32_bf16 v[56:59], v[28:31], v[60:63], v[56:59]
	s_barrier
	v_lshl_add_u64 v[212:213], s[48:49], 0, v[130:131]
	s_mov_b32 m0, s61
	v_lshl_add_u64 v[146:147], v[212:213], 0, s[16:17]
	v_lshl_add_u64 v[214:215], s[48:49], 0, v[134:135]
	s_add_u32 s46, s48, 0x10100
	ds_read_b128 v[60:63], v142 offset:16384
	ds_read_b128 v[100:103], v142 offset:17408
	ds_read_b128 v[104:107], v142 offset:18432
	ds_read_b128 v[108:111], v142 offset:19456
	ds_read_b128 v[112:115], v142 offset:20480
	ds_read_b128 v[116:119], v142 offset:21504
	ds_read_b128 v[120:123], v142 offset:22528
	ds_read_b128 v[124:127], v142 offset:23552
	global_load_lds_dwordx4 v[146:147], off
	v_lshl_add_u64 v[146:147], v[214:215], 0, s[16:17]
	s_mov_b32 m0, s62
	s_addc_u32 s47, s49, 0
	global_load_lds_dwordx4 v[146:147], off
	v_lshl_add_u64 v[146:147], s[46:47], 0, v[130:131]
	s_mov_b32 m0, s63
	v_lshl_add_u64 v[216:217], s[42:43], 0, v[128:129]
	global_load_lds_dwordx4 v[146:147], off
	v_lshl_add_u64 v[146:147], s[46:47], 0, v[134:135]
	s_mov_b32 m0, s76
	v_lshl_add_u64 v[218:219], s[42:43], 0, v[132:133]
	global_load_lds_dwordx4 v[146:147], off
	s_mov_b32 m0, s23
	v_lshl_add_u64 v[146:147], v[216:217], 0, s[16:17]
	global_load_lds_dwordx4 v[146:147], off
	s_mov_b32 m0, s53
	v_lshl_add_u64 v[146:147], v[218:219], 0, s[16:17]
	global_load_lds_dwordx4 v[146:147], off
	s_waitcnt vmcnt(8)
	s_waitcnt lgkmcnt(0)
	s_barrier
; #define PG8_STAGE(bufoff, gbase, voff) do { _Pragma("unroll") for (int _i = 0; _i < 2; ++_i) \
;         __builtin_amdgcn_global_load_lds((const unsigned*)((const char*)(gbase) + (voff)[_i]), (LAS unsigned*)(lds + (bufoff) + ldsw + _i * 8192), 16, 0, 0); } while (0)
; #define PG8_LDA(dst, b, h) do { _Pragma("unroll") for (int m = 0; m < 4; ++m) _Pragma("unroll") for (int k = 0; k < 2; ++k) dst[m][k] = *(const LAS bf16x8*)(lds + PG8_SA(b, h) + aoff + m * 2048 + k * 1024); } while (0)
; #define PG8_LDB(dst, b, h) do { _Pragma("unroll") for (int n = 0; n < 2; ++n) _Pragma("unroll") for (int k = 0; k < 2; ++k) dst[n][k] = *(const LAS bf16x8*)(lds + PG8_SB(b, h) + boff + n * 2048 + k * 1024); } while (0)
; #define PG8_MMA(ai, bj, At, Bt) do { __builtin_amdgcn_s_setprio(1); _Pragma("unroll") for (int m = 0; m < 4; ++m) _Pragma("unroll") for (int n = 0; n < 2; ++n) _Pragma("unroll") for (int k = 0; k < 2; ++k) \
;         acc[ai][bj][m][n] = __builtin_amdgcn_mfma_f32_16x16x32_bf16(Bt[n][k], At[m][k], acc[ai][bj][m][n], 0, 0, 0); __builtin_amdgcn_s_setprio(0); } while (0)
; #define PG8_WAIT_V(n) asm volatile("s_waitcnt vmcnt(" #n ")" ::: "memory")
; #define PG8_WAIT_L(n) asm volatile("s_waitcnt lgkmcnt(" #n ")" ::: "memory")
; #define PG8_BAR __builtin_amdgcn_s_barrier()
; #define PG8_SCHED __builtin_amdgcn_sched_barrier(0)
; template <class Epi, class Sched, bool ALIGN_EPI = true>
; __device__ __forceinline__ void gemm_phase(LAS unsigned char* lds, const Gemm g, const Sched& S, const Epi& E) {
;     ...
;             PG8_LDA(At, 0, 1); PG8_STAGE(PG8_SB(0, 0), b2, voffB); PG8_STAGE(PG8_SB(0, 1), b2 + hstep, voffB); PG8_STAGE(PG8_SA(0, 0), a2, voffA);
;             PG8_WAIT_V(8); PG8_WAIT_L(0); PG8_BAR; PG8_MMA(1, 0, At, B0); PG8_MMA(1, 1, At, B1); PG8_BAR; PG8_SCHED;
;             PG8_LDB(B0, 1, 0); PG8_LDB(B1, 1, 1); PG8_SCHED; PG8_LDA(At, 1, 0); PG8_STAGE(PG8_SA(0, 1), a2 + hstep, voffA);
;             PG8_WAIT_V(8); PG8_WAIT_L(0); PG8_BAR; PG8_MMA(0, 0, At, B0); PG8_MMA(0, 1, At, B1); PG8_BAR; PG8_SCHED;
	v_mfma_f32_16x16x32_bf16 v[146:149], v[0:3], v[60:63], 0
	v_mfma_f32_16x16x32_bf16 v[154:157], v[0:3], v[104:107], 0
	v_mfma_f32_16x16x32_bf16 v[162:165], v[0:3], v[112:115], 0
	v_mfma_f32_16x16x32_bf16 v[0:3], v[0:3], v[120:123], 0
	v_mfma_f32_16x16x32_bf16 v[146:149], v[4:7], v[100:103], v[146:149]
	v_mfma_f32_16x16x32_bf16 v[154:157], v[4:7], v[108:111], v[154:157]
	v_mfma_f32_16x16x32_bf16 v[162:165], v[4:7], v[116:119], v[162:165]
	v_mfma_f32_16x16x32_bf16 v[0:3], v[4:7], v[124:127], v[0:3]
	v_mfma_f32_16x16x32_bf16 v[4:7], v[8:11], v[120:123], 0
	v_mfma_f32_16x16x32_bf16 v[150:153], v[8:11], v[60:63], 0
	v_mfma_f32_16x16x32_bf16 v[158:161], v[8:11], v[104:107], 0
	v_mfma_f32_16x16x32_bf16 v[166:169], v[8:11], v[112:115], 0
	v_mfma_f32_16x16x32_bf16 v[4:7], v[12:15], v[124:127], v[4:7]
	v_mfma_f32_16x16x32_bf16 v[150:153], v[12:15], v[100:103], v[150:153]
	v_mfma_f32_16x16x32_bf16 v[158:161], v[12:15], v[108:111], v[158:161]
	v_mfma_f32_16x16x32_bf16 v[166:169], v[12:15], v[116:119], v[166:169]
	v_mfma_f32_16x16x32_bf16 v[8:11], v[16:19], v[60:63], 0
	v_mfma_f32_16x16x32_bf16 v[12:15], v[24:27], v[60:63], 0
	v_mfma_f32_16x16x32_bf16 v[8:11], v[20:23], v[100:103], v[8:11]
	v_mfma_f32_16x16x32_bf16 v[12:15], v[28:31], v[100:103], v[12:15]
	v_mfma_f32_16x16x32_bf16 v[60:63], v[16:19], v[104:107], 0
	v_mfma_f32_16x16x32_bf16 v[100:103], v[24:27], v[104:107], 0
	v_mfma_f32_16x16x32_bf16 v[104:107], v[16:19], v[112:115], 0
	v_mfma_f32_16x16x32_bf16 v[16:19], v[16:19], v[120:123], 0
	v_mfma_f32_16x16x32_bf16 v[60:63], v[20:23], v[108:111], v[60:63]
	v_mfma_f32_16x16x32_bf16 v[100:103], v[28:31], v[108:111], v[100:103]
	v_mfma_f32_16x16x32_bf16 v[104:107], v[20:23], v[116:119], v[104:107]
	v_mfma_f32_16x16x32_bf16 v[108:111], v[24:27], v[112:115], 0
	v_mfma_f32_16x16x32_bf16 v[16:19], v[20:23], v[124:127], v[16:19]
	v_mfma_f32_16x16x32_bf16 v[20:23], v[24:27], v[120:123], 0
	v_mfma_f32_16x16x32_bf16 v[108:111], v[28:31], v[116:119], v[108:111]
	v_mfma_f32_16x16x32_bf16 v[20:23], v[28:31], v[124:127], v[20:23]
	s_barrier
	ds_read_b128 v[24:27], v143
	ds_read_b128 v[28:31], v143 offset:1024
	ds_read_b128 v[112:115], v143 offset:2048
	ds_read_b128 v[116:119], v143 offset:3072
	ds_read_b128 v[120:123], v144
	ds_read_b128 v[124:127], v144 offset:1024
	ds_read_b128 v[170:173], v144 offset:2048
	ds_read_b128 v[174:177], v144 offset:3072
	s_add_u32 s46, s42, 0x10100
	s_addc_u32 s47, s43, 0
	s_mov_b32 m0, s54
	v_lshl_add_u64 v[220:221], s[46:47], 0, v[128:129]
	ds_read_b128 v[178:181], v142 offset:32768
	ds_read_b128 v[182:185], v142 offset:33792
	ds_read_b128 v[186:189], v142 offset:34816
	ds_read_b128 v[190:193], v142 offset:35840
	ds_read_b128 v[194:197], v142 offset:36864
	ds_read_b128 v[198:201], v142 offset:37888
	ds_read_b128 v[204:207], v142 offset:38912
	ds_read_b128 v[208:211], v142 offset:39936
	global_load_lds_dwordx4 v[220:221], off
	s_mov_b32 m0, s55
	v_lshl_add_u64 v[220:221], s[46:47], 0, v[132:133]
	global_load_lds_dwordx4 v[220:221], off
	s_waitcnt vmcnt(8)
	s_waitcnt lgkmcnt(0)
	s_barrier
	v_mfma_f32_16x16x32_bf16 v[64:67], v[24:27], v[178:181], v[64:67]
	v_mfma_f32_16x16x32_bf16 v[68:71], v[112:115], v[178:181], v[68:71]
	v_mfma_f32_16x16x32_bf16 v[72:75], v[24:27], v[186:189], v[72:75]
	v_mfma_f32_16x16x32_bf16 v[76:79], v[112:115], v[186:189], v[76:79]
	v_mfma_f32_16x16x32_bf16 v[80:83], v[24:27], v[194:197], v[80:83]
	v_mfma_f32_16x16x32_bf16 v[84:87], v[112:115], v[194:197], v[84:87]
	v_mfma_f32_16x16x32_bf16 v[88:91], v[24:27], v[204:207], v[88:91]
	v_mfma_f32_16x16x32_bf16 v[92:95], v[112:115], v[204:207], v[92:95]
	v_mfma_f32_16x16x32_bf16 v[64:67], v[28:31], v[182:185], v[64:67]
	v_mfma_f32_16x16x32_bf16 v[68:71], v[116:119], v[182:185], v[68:71]
	v_mfma_f32_16x16x32_bf16 v[72:75], v[28:31], v[190:193], v[72:75]
	v_mfma_f32_16x16x32_bf16 v[76:79], v[116:119], v[190:193], v[76:79]
	v_mfma_f32_16x16x32_bf16 v[80:83], v[28:31], v[198:201], v[80:83]
	v_mfma_f32_16x16x32_bf16 v[84:87], v[116:119], v[198:201], v[84:87]
	v_mfma_f32_16x16x32_bf16 v[88:91], v[28:31], v[208:211], v[88:91]
	v_mfma_f32_16x16x32_bf16 v[92:95], v[116:119], v[208:211], v[92:95]
	v_mfma_f32_16x16x32_bf16 v[96:99], v[120:123], v[178:181], v[96:99]
	v_mfma_f32_16x16x32_bf16 v[32:35], v[170:173], v[178:181], v[32:35]
	v_mfma_f32_16x16x32_bf16 v[36:39], v[120:123], v[186:189], v[36:39]
	v_mfma_f32_16x16x32_bf16 v[40:43], v[170:173], v[186:189], v[40:43]
	v_mfma_f32_16x16x32_bf16 v[44:47], v[120:123], v[194:197], v[44:47]
	v_mfma_f32_16x16x32_bf16 v[48:51], v[170:173], v[194:197], v[48:51]
	v_mfma_f32_16x16x32_bf16 v[52:55], v[120:123], v[204:207], v[52:55]
	v_mfma_f32_16x16x32_bf16 v[56:59], v[170:173], v[204:207], v[56:59]
	v_mfma_f32_16x16x32_bf16 v[96:99], v[124:127], v[182:185], v[96:99]
	v_mfma_f32_16x16x32_bf16 v[32:35], v[174:177], v[182:185], v[32:35]
	v_mfma_f32_16x16x32_bf16 v[36:39], v[124:127], v[190:193], v[36:39]
	v_mfma_f32_16x16x32_bf16 v[40:43], v[174:177], v[190:193], v[40:43]
	v_mfma_f32_16x16x32_bf16 v[44:47], v[124:127], v[198:201], v[44:47]
	v_mfma_f32_16x16x32_bf16 v[48:51], v[174:177], v[198:201], v[48:51]
	v_mfma_f32_16x16x32_bf16 v[52:55], v[124:127], v[208:211], v[52:55]
	v_mfma_f32_16x16x32_bf16 v[56:59], v[174:177], v[208:211], v[56:59]
	s_barrier
; #define PG8_STAGE(bufoff, gbase, voff) do { _Pragma("unroll") for (int _i = 0; _i < 2; ++_i) \
;         __builtin_amdgcn_global_load_lds((const unsigned*)((const char*)(gbase) + (voff)[_i]), (LAS unsigned*)(lds + (bufoff) + ldsw + _i * 8192), 16, 0, 0); } while (0)
; #define PG8_LDA(dst, b, h) do { _Pragma("unroll") for (int m = 0; m < 4; ++m) _Pragma("unroll") for (int k = 0; k < 2; ++k) dst[m][k] = *(const LAS bf16x8*)(lds + PG8_SA(b, h) + aoff + m * 2048 + k * 1024); } while (0)
; #define PG8_LDB(dst, b, h) do { _Pragma("unroll") for (int n = 0; n < 2; ++n) _Pragma("unroll") for (int k = 0; k < 2; ++k) dst[n][k] = *(const LAS bf16x8*)(lds + PG8_SB(b, h) + boff + n * 2048 + k * 1024); } while (0)
; #define PG8_MMA(ai, bj, At, Bt) do { __builtin_amdgcn_s_setprio(1); _Pragma("unroll") for (int m = 0; m < 4; ++m) _Pragma("unroll") for (int n = 0; n < 2; ++n) _Pragma("unroll") for (int k = 0; k < 2; ++k) \
;         acc[ai][bj][m][n] = __builtin_amdgcn_mfma_f32_16x16x32_bf16(Bt[n][k], At[m][k], acc[ai][bj][m][n], 0, 0, 0); __builtin_amdgcn_s_setprio(0); } while (0)
; #define PG8_WAIT_V(n) asm volatile("s_waitcnt vmcnt(" #n ")" ::: "memory")
; template <class Epi, class Sched, bool ALIGN_EPI = true>
; __device__ __forceinline__ void gemm_phase(LAS unsigned char* lds, const Gemm g, const Sched& S, const Epi& E) {
;     ...
;             PG8_LDB(B0, 0, 0); PG8_LDB(B1, 0, 1); PG8_SCHED; PG8_LDA(At, 0, 0); PG8_STAGE(PG8_SA(1, 1), a1 + hstep, voffA);
;             PG8_WAIT_V(8); PG8_WAIT_L(0); PG8_BAR; PG8_MMA(0, 0, At, B0); PG8_MMA(0, 1, At, B1); PG8_BAR; PG8_SCHED;
;             PG8_LDA(At, 0, 1); PG8_STAGE(PG8_SB(0, 0), b2, voffB); PG8_STAGE(PG8_SB(0, 1), b2 + hstep, voffB); PG8_STAGE(PG8_SA(0, 0), a2, voffA);
;             PG8_WAIT_V(8); PG8_WAIT_L(0); PG8_BAR; PG8_MMA(1, 0, At, B0); PG8_MMA(1, 1, At, B1); PG8_BAR; PG8_SCHED;
;             PG8_LDB(B0, 1, 0); PG8_LDB(B1, 1, 1); PG8_SCHED; PG8_LDA(At, 1, 0); PG8_STAGE(PG8_SA(0, 1), a2 + hstep, voffA);
;             PG8_WAIT_V(8); PG8_WAIT_L(0); PG8_BAR; PG8_MMA(0, 0, At, B0); PG8_MMA(0, 1, At, B1); PG8_BAR; PG8_SCHED;
;             PG8_LDA(At, 1, 1); PG8_STAGE(PG8_SB(1, 0), b3, voffB); PG8_STAGE(PG8_SB(1, 1), b3 + hstep, voffB); PG8_STAGE(PG8_SA(1, 0), a3, voffA);
;             PG8_WAIT_V(8); PG8_WAIT_L(0); PG8_BAR; PG8_MMA(1, 0, At, B0); PG8_MMA(1, 1, At, B1); PG8_BAR; PG8_SCHED;
	s_mov_b32 m0, s77
	v_lshl_add_u64 v[212:213], v[212:213], 0, s[18:19]
	s_add_u32 s46, s48, 0x10180
	ds_read_b128 v[178:181], v142 offset:49152
	ds_read_b128 v[182:185], v142 offset:50176
	ds_read_b128 v[186:189], v142 offset:51200
	ds_read_b128 v[190:193], v142 offset:52224
	ds_read_b128 v[194:197], v142 offset:53248
	ds_read_b128 v[198:201], v142 offset:54272
	ds_read_b128 v[204:207], v142 offset:55296
	ds_read_b128 v[208:211], v142 offset:56320
	global_load_lds_dwordx4 v[212:213], off
	v_lshl_add_u64 v[212:213], v[214:215], 0, s[18:19]
	s_mov_b32 m0, s78
	s_addc_u32 s47, s49, 0
	global_load_lds_dwordx4 v[212:213], off
	s_mov_b32 m0, s79
	v_lshl_add_u64 v[212:213], s[46:47], 0, v[130:131]
	global_load_lds_dwordx4 v[212:213], off
	s_mov_b32 m0, s80
	v_lshl_add_u64 v[212:213], s[46:47], 0, v[134:135]
	global_load_lds_dwordx4 v[212:213], off
	s_mov_b32 m0, s57
	v_lshl_add_u64 v[212:213], v[216:217], 0, s[18:19]
	global_load_lds_dwordx4 v[212:213], off
	s_mov_b32 m0, s58
	v_lshl_add_u64 v[212:213], v[218:219], 0, s[18:19]
	global_load_lds_dwordx4 v[212:213], off
	s_waitcnt vmcnt(8)
	s_waitcnt lgkmcnt(0)
	s_barrier
	v_mfma_f32_16x16x32_bf16 v[0:3], v[24:27], v[204:207], v[0:3]
	v_mfma_f32_16x16x32_bf16 v[4:7], v[112:115], v[204:207], v[4:7]
	v_mfma_f32_16x16x32_bf16 v[146:149], v[24:27], v[178:181], v[146:149]
	v_mfma_f32_16x16x32_bf16 v[150:153], v[112:115], v[178:181], v[150:153]
	v_mfma_f32_16x16x32_bf16 v[154:157], v[24:27], v[186:189], v[154:157]
	v_mfma_f32_16x16x32_bf16 v[158:161], v[112:115], v[186:189], v[158:161]
	v_mfma_f32_16x16x32_bf16 v[162:165], v[24:27], v[194:197], v[162:165]
	v_mfma_f32_16x16x32_bf16 v[166:169], v[112:115], v[194:197], v[166:169]
	v_mfma_f32_16x16x32_bf16 v[0:3], v[28:31], v[208:211], v[0:3]
	v_mfma_f32_16x16x32_bf16 v[4:7], v[116:119], v[208:211], v[4:7]
	v_mfma_f32_16x16x32_bf16 v[146:149], v[28:31], v[182:185], v[146:149]
	v_mfma_f32_16x16x32_bf16 v[150:153], v[116:119], v[182:185], v[150:153]
	v_mfma_f32_16x16x32_bf16 v[154:157], v[28:31], v[190:193], v[154:157]
	v_mfma_f32_16x16x32_bf16 v[158:161], v[116:119], v[190:193], v[158:161]
	v_mfma_f32_16x16x32_bf16 v[162:165], v[28:31], v[198:201], v[162:165]
	v_mfma_f32_16x16x32_bf16 v[166:169], v[116:119], v[198:201], v[166:169]
	v_mfma_f32_16x16x32_bf16 v[8:11], v[120:123], v[178:181], v[8:11]
	v_mfma_f32_16x16x32_bf16 v[12:15], v[170:173], v[178:181], v[12:15]
	v_mfma_f32_16x16x32_bf16 v[24:27], v[120:123], v[186:189], v[60:63]
	v_mfma_f32_16x16x32_bf16 v[28:31], v[170:173], v[186:189], v[100:103]
	v_mfma_f32_16x16x32_bf16 v[60:63], v[120:123], v[194:197], v[104:107]
	v_mfma_f32_16x16x32_bf16 v[100:103], v[170:173], v[194:197], v[108:111]
	v_mfma_f32_16x16x32_bf16 v[16:19], v[120:123], v[204:207], v[16:19]
	v_mfma_f32_16x16x32_bf16 v[20:23], v[170:173], v[204:207], v[20:23]
	v_mfma_f32_16x16x32_bf16 v[8:11], v[124:127], v[182:185], v[8:11]
	v_mfma_f32_16x16x32_bf16 v[12:15], v[174:177], v[182:185], v[12:15]
	v_mfma_f32_16x16x32_bf16 v[24:27], v[124:127], v[190:193], v[24:27]
	v_mfma_f32_16x16x32_bf16 v[28:31], v[174:177], v[190:193], v[28:31]
	v_mfma_f32_16x16x32_bf16 v[60:63], v[124:127], v[198:201], v[60:63]
	v_mfma_f32_16x16x32_bf16 v[100:103], v[174:177], v[198:201], v[100:103]
	v_mfma_f32_16x16x32_bf16 v[16:19], v[124:127], v[208:211], v[16:19]
	v_mfma_f32_16x16x32_bf16 v[20:23], v[174:177], v[208:211], v[20:23]
	s_barrier
	ds_read_b128 v[104:107], v140
	ds_read_b128 v[108:111], v140 offset:1024
	ds_read_b128 v[112:115], v140 offset:2048
	ds_read_b128 v[116:119], v140 offset:3072
	ds_read_b128 v[120:123], v141
	ds_read_b128 v[124:127], v141 offset:1024
	ds_read_b128 v[170:173], v141 offset:2048
	ds_read_b128 v[174:177], v141 offset:3072
	s_add_u32 s42, s42, 0x10180
	s_addc_u32 s43, s43, 0
	s_mov_b32 m0, s59
	v_lshl_add_u64 v[212:213], s[42:43], 0, v[128:129]
	ds_read_b128 v[178:181], v142
	ds_read_b128 v[182:185], v142 offset:1024
	ds_read_b128 v[186:189], v142 offset:2048
	ds_read_b128 v[190:193], v142 offset:3072
	ds_read_b128 v[194:197], v142 offset:4096
	ds_read_b128 v[198:201], v142 offset:5120
	ds_read_b128 v[204:207], v142 offset:6144
	ds_read_b128 v[208:211], v142 offset:7168
	global_load_lds_dwordx4 v[212:213], off
	s_mov_b32 m0, s60
	v_lshl_add_u64 v[212:213], s[42:43], 0, v[132:133]
	global_load_lds_dwordx4 v[212:213], off
	s_waitcnt vmcnt(8)
	s_waitcnt lgkmcnt(0)
	s_barrier
	v_mfma_f32_16x16x32_bf16 v[64:67], v[104:107], v[178:181], v[64:67]
	v_mfma_f32_16x16x32_bf16 v[68:71], v[112:115], v[178:181], v[68:71]
	v_mfma_f32_16x16x32_bf16 v[72:75], v[104:107], v[186:189], v[72:75]
	v_mfma_f32_16x16x32_bf16 v[76:79], v[112:115], v[186:189], v[76:79]
	v_mfma_f32_16x16x32_bf16 v[80:83], v[104:107], v[194:197], v[80:83]
	v_mfma_f32_16x16x32_bf16 v[84:87], v[112:115], v[194:197], v[84:87]
	v_mfma_f32_16x16x32_bf16 v[88:91], v[104:107], v[204:207], v[88:91]
	v_mfma_f32_16x16x32_bf16 v[92:95], v[112:115], v[204:207], v[92:95]
	v_mfma_f32_16x16x32_bf16 v[64:67], v[108:111], v[182:185], v[64:67]
	v_mfma_f32_16x16x32_bf16 v[68:71], v[116:119], v[182:185], v[68:71]
	v_mfma_f32_16x16x32_bf16 v[72:75], v[108:111], v[190:193], v[72:75]
	v_mfma_f32_16x16x32_bf16 v[76:79], v[116:119], v[190:193], v[76:79]
	v_mfma_f32_16x16x32_bf16 v[80:83], v[108:111], v[198:201], v[80:83]
	v_mfma_f32_16x16x32_bf16 v[84:87], v[116:119], v[198:201], v[84:87]
	v_mfma_f32_16x16x32_bf16 v[88:91], v[108:111], v[208:211], v[88:91]
	v_mfma_f32_16x16x32_bf16 v[92:95], v[116:119], v[208:211], v[92:95]
	v_mfma_f32_16x16x32_bf16 v[32:35], v[170:173], v[178:181], v[32:35]
	v_mfma_f32_16x16x32_bf16 v[36:39], v[120:123], v[186:189], v[36:39]
	v_mfma_f32_16x16x32_bf16 v[40:43], v[170:173], v[186:189], v[40:43]
	v_mfma_f32_16x16x32_bf16 v[44:47], v[120:123], v[194:197], v[44:47]
	v_mfma_f32_16x16x32_bf16 v[48:51], v[170:173], v[194:197], v[48:51]
	v_mfma_f32_16x16x32_bf16 v[52:55], v[120:123], v[204:207], v[52:55]
	v_mfma_f32_16x16x32_bf16 v[56:59], v[170:173], v[204:207], v[56:59]
	v_mfma_f32_16x16x32_bf16 v[96:99], v[120:123], v[178:181], v[96:99]
	v_mfma_f32_16x16x32_bf16 v[32:35], v[174:177], v[182:185], v[32:35]
	v_mfma_f32_16x16x32_bf16 v[36:39], v[124:127], v[190:193], v[36:39]
	v_mfma_f32_16x16x32_bf16 v[40:43], v[174:177], v[190:193], v[40:43]
	v_mfma_f32_16x16x32_bf16 v[44:47], v[124:127], v[198:201], v[44:47]
	v_mfma_f32_16x16x32_bf16 v[48:51], v[174:177], v[198:201], v[48:51]
	v_mfma_f32_16x16x32_bf16 v[52:55], v[124:127], v[208:211], v[52:55]
	v_mfma_f32_16x16x32_bf16 v[56:59], v[174:177], v[208:211], v[56:59]
	v_mfma_f32_16x16x32_bf16 v[212:215], v[124:127], v[182:185], v[96:99]
	s_barrier
; #define PG8_STAGE(bufoff, gbase, voff) do { _Pragma("unroll") for (int _i = 0; _i < 2; ++_i) \
;         __builtin_amdgcn_global_load_lds((const unsigned*)((const char*)(gbase) + (voff)[_i]), (LAS unsigned*)(lds + (bufoff) + ldsw + _i * 8192), 16, 0, 0); } while (0)
; #define PG8_LDA(dst, b, h) do { _Pragma("unroll") for (int m = 0; m < 4; ++m) _Pragma("unroll") for (int k = 0; k < 2; ++k) dst[m][k] = *(const LAS bf16x8*)(lds + PG8_SA(b, h) + aoff + m * 2048 + k * 1024); } while (0)
; #define PG8_LDB(dst, b, h) do { _Pragma("unroll") for (int n = 0; n < 2; ++n) _Pragma("unroll") for (int k = 0; k < 2; ++k) dst[n][k] = *(const LAS bf16x8*)(lds + PG8_SB(b, h) + boff + n * 2048 + k * 1024); } while (0)
; #define PG8_MMA(ai, bj, At, Bt) do { __builtin_amdgcn_s_setprio(1); _Pragma("unroll") for (int m = 0; m < 4; ++m) _Pragma("unroll") for (int n = 0; n < 2; ++n) _Pragma("unroll") for (int k = 0; k < 2; ++k) \
;         acc[ai][bj][m][n] = __builtin_amdgcn_mfma_f32_16x16x32_bf16(Bt[n][k], At[m][k], acc[ai][bj][m][n], 0, 0, 0); __builtin_amdgcn_s_setprio(0); } while (0)
; #define PG8_WAIT_V(n) asm volatile("s_waitcnt vmcnt(" #n ")" ::: "memory")
; #define PG8_WAIT_L(n) asm volatile("s_waitcnt lgkmcnt(" #n ")" ::: "memory")
; #define PG8_BAR __builtin_amdgcn_s_barrier()
; #define PG8_SCHED __builtin_amdgcn_sched_barrier(0)
; template <class Epi, class Sched, bool ALIGN_EPI = true>
; __device__ __forceinline__ void gemm_phase(LAS unsigned char* lds, const Gemm g, const Sched& S, const Epi& E) {
;     ...
;             PG8_LDA(At, 0, 1); PG8_STAGE(PG8_SB(0, 0), b2, voffB); PG8_STAGE(PG8_SB(0, 1), b2 + hstep, voffB); PG8_STAGE(PG8_SA(0, 0), a2, voffA);
;             PG8_WAIT_V(8); PG8_WAIT_L(0); PG8_BAR; PG8_MMA(1, 0, At, B0); PG8_MMA(1, 1, At, B1); PG8_BAR; PG8_SCHED;
;             PG8_LDB(B0, 1, 0); PG8_LDB(B1, 1, 1); PG8_SCHED; PG8_LDA(At, 1, 0); PG8_STAGE(PG8_SA(0, 1), a2 + hstep, voffA);
;             PG8_WAIT_V(8); PG8_WAIT_L(0); PG8_BAR; PG8_MMA(0, 0, At, B0); PG8_MMA(0, 1, At, B1); PG8_BAR; PG8_SCHED;
	s_mov_b32 m0, s61
	v_lshl_add_u64 v[248:249], s[40:41], 0, v[130:131]
	s_add_u32 s42, s40, 0x10000
	ds_read_b128 v[96:99], v142 offset:16384
	ds_read_b128 v[178:181], v142 offset:17408
	ds_read_b128 v[182:185], v142 offset:18432
	ds_read_b128 v[186:189], v142 offset:19456
	ds_read_b128 v[190:193], v142 offset:20480
	ds_read_b128 v[194:197], v142 offset:21504
	ds_read_b128 v[198:201], v142 offset:22528
	ds_read_b128 v[204:207], v142 offset:23552
	global_load_lds_dwordx4 v[248:249], off
	v_lshl_add_u64 v[250:251], s[40:41], 0, v[134:135]
	s_mov_b32 m0, s62
	s_addc_u32 s43, s41, 0
	global_load_lds_dwordx4 v[250:251], off
	v_lshl_add_u64 v[208:209], s[42:43], 0, v[130:131]
	s_mov_b32 m0, s63
	v_lshl_add_u64 v[252:253], s[44:45], 0, v[128:129]
	global_load_lds_dwordx4 v[208:209], off
	v_lshl_add_u64 v[208:209], s[42:43], 0, v[134:135]
	s_mov_b32 m0, s76
	v_lshl_add_u64 v[202:203], s[44:45], 0, v[132:133]
	global_load_lds_dwordx4 v[208:209], off
	s_mov_b32 m0, s23
	s_nop 0
	global_load_lds_dwordx4 v[252:253], off
	s_mov_b32 m0, s53
	s_nop 0
	global_load_lds_dwordx4 v[202:203], off
	s_waitcnt vmcnt(8)
	s_waitcnt lgkmcnt(0)
	s_barrier
	v_mfma_f32_16x16x32_bf16 v[0:3], v[104:107], v[198:201], v[0:3]
	v_mfma_f32_16x16x32_bf16 v[4:7], v[112:115], v[198:201], v[4:7]
	v_mfma_f32_16x16x32_bf16 v[146:149], v[104:107], v[96:99], v[146:149]
	v_mfma_f32_16x16x32_bf16 v[150:153], v[112:115], v[96:99], v[150:153]
	v_mfma_f32_16x16x32_bf16 v[154:157], v[104:107], v[182:185], v[154:157]
	v_mfma_f32_16x16x32_bf16 v[158:161], v[112:115], v[182:185], v[158:161]
	v_mfma_f32_16x16x32_bf16 v[162:165], v[104:107], v[190:193], v[162:165]
	v_mfma_f32_16x16x32_bf16 v[166:169], v[112:115], v[190:193], v[166:169]
	v_mfma_f32_16x16x32_bf16 v[0:3], v[108:111], v[204:207], v[0:3]
	v_mfma_f32_16x16x32_bf16 v[4:7], v[116:119], v[204:207], v[4:7]
	v_mfma_f32_16x16x32_bf16 v[146:149], v[108:111], v[178:181], v[146:149]
	v_mfma_f32_16x16x32_bf16 v[150:153], v[116:119], v[178:181], v[150:153]
	v_mfma_f32_16x16x32_bf16 v[154:157], v[108:111], v[186:189], v[154:157]
	v_mfma_f32_16x16x32_bf16 v[158:161], v[116:119], v[186:189], v[158:161]
	v_mfma_f32_16x16x32_bf16 v[162:165], v[108:111], v[194:197], v[162:165]
	v_mfma_f32_16x16x32_bf16 v[166:169], v[116:119], v[194:197], v[166:169]
	v_mfma_f32_16x16x32_bf16 v[8:11], v[120:123], v[96:99], v[8:11]
	v_mfma_f32_16x16x32_bf16 v[12:15], v[170:173], v[96:99], v[12:15]
	v_mfma_f32_16x16x32_bf16 v[24:27], v[120:123], v[182:185], v[24:27]
	v_mfma_f32_16x16x32_bf16 v[8:11], v[124:127], v[178:181], v[8:11]
	v_mfma_f32_16x16x32_bf16 v[12:15], v[174:177], v[178:181], v[12:15]
	v_mfma_f32_16x16x32_bf16 v[178:181], v[124:127], v[186:189], v[24:27]
	v_mfma_f32_16x16x32_bf16 v[24:27], v[170:173], v[182:185], v[28:31]
	v_mfma_f32_16x16x32_bf16 v[182:185], v[174:177], v[186:189], v[24:27]
	v_mfma_f32_16x16x32_bf16 v[24:27], v[120:123], v[190:193], v[60:63]
	v_mfma_f32_16x16x32_bf16 v[186:189], v[124:127], v[194:197], v[24:27]
	v_mfma_f32_16x16x32_bf16 v[24:27], v[170:173], v[190:193], v[100:103]
	v_mfma_f32_16x16x32_bf16 v[16:19], v[120:123], v[198:201], v[16:19]
	v_mfma_f32_16x16x32_bf16 v[190:193], v[174:177], v[194:197], v[24:27]
	v_mfma_f32_16x16x32_bf16 v[194:197], v[124:127], v[204:207], v[16:19]
	v_mfma_f32_16x16x32_bf16 v[16:19], v[170:173], v[198:201], v[20:23]
	v_mfma_f32_16x16x32_bf16 v[170:173], v[174:177], v[204:207], v[16:19]
	s_barrier
	ds_read_b128 v[60:63], v143
	ds_read_b128 v[174:177], v143 offset:1024
	ds_read_b128 v[198:201], v143 offset:2048
	ds_read_b128 v[204:207], v143 offset:3072
	ds_read_b128 v[208:211], v144
	ds_read_b128 v[216:219], v144 offset:1024
	ds_read_b128 v[220:223], v144 offset:2048
	ds_read_b128 v[224:227], v144 offset:3072
	s_add_u32 s42, s44, 0x10000
	s_addc_u32 s43, s45, 0
	s_mov_b32 m0, s54
	v_lshl_add_u64 v[24:25], s[42:43], 0, v[128:129]
	ds_read_b128 v[16:19], v142 offset:32768
	ds_read_b128 v[20:23], v142 offset:33792
	ds_read_b128 v[108:111], v142 offset:34816
	ds_read_b128 v[228:231], v142 offset:35840
	ds_read_b128 v[232:235], v142 offset:36864
	ds_read_b128 v[236:239], v142 offset:37888
	ds_read_b128 v[240:243], v142 offset:38912
	ds_read_b128 v[244:247], v142 offset:39936
	global_load_lds_dwordx4 v[24:25], off
	s_mov_b32 m0, s55
	v_lshl_add_u64 v[24:25], s[42:43], 0, v[132:133]
	global_load_lds_dwordx4 v[24:25], off
	s_waitcnt vmcnt(8)
	s_waitcnt lgkmcnt(0)
	s_barrier
; #define PG8_STAGE(bufoff, gbase, voff) do { _Pragma("unroll") for (int _i = 0; _i < 2; ++_i) \
;         __builtin_amdgcn_global_load_lds((const unsigned*)((const char*)(gbase) + (voff)[_i]), (LAS unsigned*)(lds + (bufoff) + ldsw + _i * 8192), 16, 0, 0); } while (0)
; #define PG8_LDA(dst, b, h) do { _Pragma("unroll") for (int m = 0; m < 4; ++m) _Pragma("unroll") for (int k = 0; k < 2; ++k) dst[m][k] = *(const LAS bf16x8*)(lds + PG8_SA(b, h) + aoff + m * 2048 + k * 1024); } while (0)
; #define PG8_MMA(ai, bj, At, Bt) do { __builtin_amdgcn_s_setprio(1); _Pragma("unroll") for (int m = 0; m < 4; ++m) _Pragma("unroll") for (int n = 0; n < 2; ++n) _Pragma("unroll") for (int k = 0; k < 2; ++k) \
;         acc[ai][bj][m][n] = __builtin_amdgcn_mfma_f32_16x16x32_bf16(Bt[n][k], At[m][k], acc[ai][bj][m][n], 0, 0, 0); __builtin_amdgcn_s_setprio(0); } while (0)
; #define PG8_WAIT_V(n) asm volatile("s_waitcnt vmcnt(" #n ")" ::: "memory")
; #define PG8_WAIT_L(n) asm volatile("s_waitcnt lgkmcnt(" #n ")" ::: "memory")
; #define PG8_BAR __builtin_amdgcn_s_barrier()
; #define PG8_SCHED __builtin_amdgcn_sched_barrier(0)
; template <class Epi, class Sched, bool ALIGN_EPI = true>
; __device__ __forceinline__ void gemm_phase(LAS unsigned char* lds, const Gemm g, const Sched& S, const Epi& E) {
;     ...
;             PG8_WAIT_V(8); PG8_WAIT_L(0); PG8_BAR; PG8_MMA(0, 0, At, B0); PG8_MMA(0, 1, At, B1); PG8_BAR; PG8_SCHED;
;             PG8_LDA(At, 1, 1); PG8_STAGE(PG8_SB(1, 0), b3, voffB); PG8_STAGE(PG8_SB(1, 1), b3 + hstep, voffB); PG8_STAGE(PG8_SA(1, 0), a3, voffA);
;             PG8_WAIT_V(8); PG8_WAIT_L(0); PG8_BAR; PG8_MMA(1, 0, At, B0); PG8_MMA(1, 1, At, B1); PG8_BAR; PG8_SCHED;
;         }
;         if constexpr (ALIGN_EPI) { if (wr == 0) PG8_BAR; }
	v_mfma_f32_16x16x32_bf16 v[24:27], v[60:63], v[16:19], v[64:67]
	v_mfma_f32_16x16x32_bf16 v[112:115], v[174:177], v[20:23], v[24:27]
	v_mfma_f32_16x16x32_bf16 v[24:27], v[198:201], v[16:19], v[68:71]
	v_mfma_f32_16x16x32_bf16 v[116:119], v[204:207], v[20:23], v[24:27]
	v_mfma_f32_16x16x32_bf16 v[24:27], v[60:63], v[108:111], v[72:75]
	v_mfma_f32_16x16x32_bf16 v[96:99], v[174:177], v[228:231], v[24:27]
	v_mfma_f32_16x16x32_bf16 v[24:27], v[198:201], v[108:111], v[76:79]
	v_mfma_f32_16x16x32_bf16 v[100:103], v[204:207], v[228:231], v[24:27]
	v_mfma_f32_16x16x32_bf16 v[24:27], v[60:63], v[232:235], v[80:83]
	v_mfma_f32_16x16x32_bf16 v[64:67], v[174:177], v[236:239], v[24:27]
	v_mfma_f32_16x16x32_bf16 v[24:27], v[198:201], v[232:235], v[84:87]
	v_mfma_f32_16x16x32_bf16 v[68:71], v[204:207], v[236:239], v[24:27]
	v_mfma_f32_16x16x32_bf16 v[24:27], v[60:63], v[240:243], v[88:91]
	v_mfma_f32_16x16x32_bf16 v[28:31], v[198:201], v[240:243], v[92:95]
	v_mfma_f32_16x16x32_bf16 v[24:27], v[174:177], v[244:247], v[24:27]
	v_mfma_f32_16x16x32_bf16 v[28:31], v[204:207], v[244:247], v[28:31]
	v_mfma_f32_16x16x32_bf16 v[72:75], v[208:211], v[16:19], v[212:215]
	v_mfma_f32_16x16x32_bf16 v[16:19], v[220:223], v[16:19], v[32:35]
	v_mfma_f32_16x16x32_bf16 v[124:127], v[224:227], v[20:23], v[16:19]
	v_mfma_f32_16x16x32_bf16 v[16:19], v[208:211], v[108:111], v[36:39]
	v_mfma_f32_16x16x32_bf16 v[104:107], v[216:219], v[228:231], v[16:19]
	v_mfma_f32_16x16x32_bf16 v[16:19], v[220:223], v[108:111], v[40:43]
	v_mfma_f32_16x16x32_bf16 v[108:111], v[224:227], v[228:231], v[16:19]
	v_mfma_f32_16x16x32_bf16 v[16:19], v[208:211], v[232:235], v[44:47]
	v_mfma_f32_16x16x32_bf16 v[120:123], v[216:219], v[20:23], v[72:75]
	v_mfma_f32_16x16x32_bf16 v[72:75], v[216:219], v[236:239], v[16:19]
	v_mfma_f32_16x16x32_bf16 v[16:19], v[220:223], v[232:235], v[48:51]
	v_mfma_f32_16x16x32_bf16 v[76:79], v[224:227], v[236:239], v[16:19]
	v_mfma_f32_16x16x32_bf16 v[16:19], v[208:211], v[240:243], v[52:55]
	v_mfma_f32_16x16x32_bf16 v[40:43], v[216:219], v[244:247], v[16:19]
	v_mfma_f32_16x16x32_bf16 v[16:19], v[220:223], v[240:243], v[56:59]
	v_mfma_f32_16x16x32_bf16 v[44:47], v[224:227], v[244:247], v[16:19]
	s_barrier
	s_mov_b32 m0, s77
	s_nop 3
	v_lshl_add_u64 v[16:17], v[248:249], 0, s[12:13]
	s_add_u32 s40, s40, 0x10080
	ds_read_b128 v[32:35], v142 offset:49152
	ds_read_b128 v[36:39], v142 offset:50176
	ds_read_b128 v[212:215], v142 offset:51200
	ds_read_b128 v[228:231], v142 offset:52224
	ds_read_b128 v[232:235], v142 offset:53248
	ds_read_b128 v[236:239], v142 offset:54272
	ds_read_b128 v[240:243], v142 offset:55296
	ds_read_b128 v[244:247], v142 offset:56320
	global_load_lds_dwordx4 v[16:17], off
	v_lshl_add_u64 v[16:17], v[250:251], 0, s[12:13]
	s_mov_b32 m0, s78
	s_addc_u32 s41, s41, 0
	global_load_lds_dwordx4 v[16:17], off
	s_mov_b32 m0, s79
	v_lshl_add_u64 v[16:17], s[40:41], 0, v[130:131]
	global_load_lds_dwordx4 v[16:17], off
	s_mov_b32 m0, s80
	v_lshl_add_u64 v[16:17], s[40:41], 0, v[134:135]
	global_load_lds_dwordx4 v[16:17], off
	s_mov_b32 m0, s57
	v_lshl_add_u64 v[16:17], v[252:253], 0, s[12:13]
	global_load_lds_dwordx4 v[16:17], off
	s_mov_b32 m0, s58
	v_lshl_add_u64 v[16:17], v[202:203], 0, s[12:13]
	global_load_lds_dwordx4 v[16:17], off
	s_waitcnt vmcnt(8)
	s_waitcnt lgkmcnt(0)
	s_barrier
	v_mfma_f32_16x16x32_bf16 v[16:19], v[60:63], v[32:35], v[146:149]
	v_mfma_f32_16x16x32_bf16 v[80:83], v[174:177], v[36:39], v[16:19]
	v_mfma_f32_16x16x32_bf16 v[16:19], v[198:201], v[32:35], v[150:153]
	v_mfma_f32_16x16x32_bf16 v[84:87], v[204:207], v[36:39], v[16:19]
	v_mfma_f32_16x16x32_bf16 v[16:19], v[60:63], v[212:215], v[154:157]
	v_mfma_f32_16x16x32_bf16 v[48:51], v[174:177], v[228:231], v[16:19]
	v_mfma_f32_16x16x32_bf16 v[16:19], v[198:201], v[212:215], v[158:161]
	v_mfma_f32_16x16x32_bf16 v[52:55], v[204:207], v[228:231], v[16:19]
	v_mfma_f32_16x16x32_bf16 v[16:19], v[60:63], v[232:235], v[162:165]
	v_mfma_f32_16x16x32_bf16 v[20:23], v[198:201], v[232:235], v[166:169]
	v_mfma_f32_16x16x32_bf16 v[0:3], v[60:63], v[240:243], v[0:3]
	v_mfma_f32_16x16x32_bf16 v[4:7], v[198:201], v[240:243], v[4:7]
	v_mfma_f32_16x16x32_bf16 v[16:19], v[174:177], v[236:239], v[16:19]
	v_mfma_f32_16x16x32_bf16 v[20:23], v[204:207], v[236:239], v[20:23]
	v_mfma_f32_16x16x32_bf16 v[0:3], v[174:177], v[244:247], v[0:3]
	v_mfma_f32_16x16x32_bf16 v[4:7], v[204:207], v[244:247], v[4:7]
	v_mfma_f32_16x16x32_bf16 v[8:11], v[208:211], v[32:35], v[8:11]
	v_mfma_f32_16x16x32_bf16 v[88:91], v[216:219], v[36:39], v[8:11]
	v_mfma_f32_16x16x32_bf16 v[8:11], v[220:223], v[32:35], v[12:15]
	v_mfma_f32_16x16x32_bf16 v[92:95], v[224:227], v[36:39], v[8:11]
	v_mfma_f32_16x16x32_bf16 v[8:11], v[208:211], v[212:215], v[178:181]
	v_mfma_f32_16x16x32_bf16 v[56:59], v[216:219], v[228:231], v[8:11]
	v_mfma_f32_16x16x32_bf16 v[8:11], v[220:223], v[212:215], v[182:185]
	v_mfma_f32_16x16x32_bf16 v[60:63], v[224:227], v[228:231], v[8:11]
	v_mfma_f32_16x16x32_bf16 v[8:11], v[208:211], v[232:235], v[186:189]
	v_mfma_f32_16x16x32_bf16 v[32:35], v[216:219], v[236:239], v[8:11]
	v_mfma_f32_16x16x32_bf16 v[8:11], v[220:223], v[232:235], v[190:193]
	v_mfma_f32_16x16x32_bf16 v[36:39], v[224:227], v[236:239], v[8:11]
	v_mfma_f32_16x16x32_bf16 v[8:11], v[208:211], v[240:243], v[194:197]
	v_mfma_f32_16x16x32_bf16 v[12:15], v[220:223], v[240:243], v[170:173]
	v_mfma_f32_16x16x32_bf16 v[8:11], v[216:219], v[244:247], v[8:11]
	v_mfma_f32_16x16x32_bf16 v[12:15], v[224:227], v[244:247], v[12:15]
	s_barrier
	s_and_b64 vcc, exec, s[4:5]
	s_cbranch_vccnz .LBB0_669
	s_barrier

; #define PG8_STAGE(bufoff, gbase, voff) do { _Pragma("unroll") for (int _i = 0; _i < 2; ++_i) \
;         __builtin_amdgcn_global_load_lds((const unsigned*)((const char*)(gbase) + (voff)[_i]), (LAS unsigned*)(lds + (bufoff) + ldsw + _i * 8192), 16, 0, 0); } while (0)
; #define PG8_LDA(dst, b, h) do { _Pragma("unroll") for (int m = 0; m < 4; ++m) _Pragma("unroll") for (int k = 0; k < 2; ++k) dst[m][k] = *(const LAS bf16x8*)(lds + PG8_SA(b, h) + aoff + m * 2048 + k * 1024); } while (0)
; #define PG8_LDB(dst, b, h) do { _Pragma("unroll") for (int n = 0; n < 2; ++n) _Pragma("unroll") for (int k = 0; k < 2; ++k) dst[n][k] = *(const LAS bf16x8*)(lds + PG8_SB(b, h) + boff + n * 2048 + k * 1024); } while (0)
; #define PG8_MMA(ai, bj, At, Bt) do { __builtin_amdgcn_s_setprio(1); _Pragma("unroll") for (int m = 0; m < 4; ++m) _Pragma("unroll") for (int n = 0; n < 2; ++n) _Pragma("unroll") for (int k = 0; k < 2; ++k) \
;         acc[ai][bj][m][n] = __builtin_amdgcn_mfma_f32_16x16x32_bf16(Bt[n][k], At[m][k], acc[ai][bj][m][n], 0, 0, 0); __builtin_amdgcn_s_setprio(0); } while (0)
; #define PG8_WAIT_V(n) asm volatile("s_waitcnt vmcnt(" #n ")" ::: "memory")
; #define PG8_WAIT_L(n) asm volatile("s_waitcnt lgkmcnt(" #n ")" ::: "memory")
; #define PG8_BAR __builtin_amdgcn_s_barrier()
; #define PG8_SCHED __builtin_amdgcn_sched_barrier(0)
; template <class Epi, class Sched, bool ALIGN_EPI = true>
; __device__ __forceinline__ void gemm_phase(LAS unsigned char* lds, const Gemm g, const Sched& S, const Epi& E) {
;     ...
;             const char* a1 = cA + (size_t)(t + 1) * kstep;
;             const char* a2 = last ? nA : cA + (size_t)(t + 2) * kstep; const char* b2 = last ? nB : cB + (size_t)(t + 2) * kstep;
;             const char* a3 = a2 + kstep; const char* b3 = b2 + kstep;
;             PG8_LDB(B0, 0, 0); PG8_LDB(B1, 0, 1); PG8_SCHED; PG8_LDA(At, 0, 0); PG8_STAGE(PG8_SA(1, 1), a1 + hstep, voffA);
;             PG8_WAIT_V(8); PG8_WAIT_L(0); PG8_BAR; PG8_MMA(0, 0, At, B0); PG8_MMA(0, 1, At, B1); PG8_BAR; PG8_SCHED;
;             PG8_LDA(At, 0, 1); PG8_STAGE(PG8_SB(0, 0), b2, voffB); PG8_STAGE(PG8_SB(0, 1), b2 + hstep, voffB); PG8_STAGE(PG8_SA(0, 0), a2, voffA);
.LBB0_746:
	ds_read_b128 v[128:131], v187
	ds_read_b128 v[132:135], v187 offset:1024
	ds_read_b128 v[136:139], v187 offset:2048
	ds_read_b128 v[140:143], v187 offset:3072
	ds_read_b128 v[144:147], v188
	ds_read_b128 v[148:151], v188 offset:1024
	ds_read_b128 v[164:167], v188 offset:2048
	ds_read_b128 v[168:171], v188 offset:3072
	s_add_u32 s24, s22, 0x100
	s_addc_u32 s25, s23, 0
	s_cmpk_eq_i32 s56, 0x54
	s_cselect_b32 s29, s19, s25
	s_cselect_b32 s28, s18, s24
	s_cselect_b32 s27, s21, s55
	s_cselect_b32 s26, s20, s54
	s_mov_b32 m0, s43
	v_lshl_add_u64 v[180:181], s[22:23], 0, v[160:161]
	ds_read_b128 v[172:175], v189
	ds_read_b128 v[176:179], v189 offset:1024
	ds_read_b128 v[192:195], v189 offset:2048
	ds_read_b128 v[196:199], v189 offset:3072
	ds_read_b128 v[204:207], v189 offset:4096
	ds_read_b128 v[208:211], v189 offset:5120
	ds_read_b128 v[212:215], v189 offset:6144
	ds_read_b128 v[216:219], v189 offset:7168
	global_load_lds_dwordx4 v[180:181], off
	s_mov_b32 m0, s44
	v_lshl_add_u64 v[180:181], s[22:23], 0, v[162:163]
	global_load_lds_dwordx4 v[180:181], off
	s_waitcnt vmcnt(8)
	s_waitcnt lgkmcnt(0)
	s_barrier
	v_mfma_f32_16x16x32_bf16 v[124:127], v[128:131], v[172:175], v[124:127]
	v_mfma_f32_16x16x32_bf16 v[120:123], v[136:139], v[172:175], v[120:123]
	v_mfma_f32_16x16x32_bf16 v[108:111], v[128:131], v[192:195], v[108:111]
	v_mfma_f32_16x16x32_bf16 v[104:107], v[136:139], v[192:195], v[104:107]
	v_mfma_f32_16x16x32_bf16 v[92:95], v[128:131], v[204:207], v[92:95]
	v_mfma_f32_16x16x32_bf16 v[88:91], v[136:139], v[204:207], v[88:91]
	v_mfma_f32_16x16x32_bf16 v[76:79], v[128:131], v[212:215], v[76:79]
	v_mfma_f32_16x16x32_bf16 v[72:75], v[136:139], v[212:215], v[72:75]
	v_mfma_f32_16x16x32_bf16 v[124:127], v[132:135], v[176:179], v[124:127]
	v_mfma_f32_16x16x32_bf16 v[120:123], v[140:143], v[176:179], v[120:123]
	v_mfma_f32_16x16x32_bf16 v[108:111], v[132:135], v[196:199], v[108:111]
	v_mfma_f32_16x16x32_bf16 v[104:107], v[140:143], v[196:199], v[104:107]
	v_mfma_f32_16x16x32_bf16 v[92:95], v[132:135], v[208:211], v[92:95]
	v_mfma_f32_16x16x32_bf16 v[88:91], v[140:143], v[208:211], v[88:91]
	v_mfma_f32_16x16x32_bf16 v[76:79], v[132:135], v[216:219], v[76:79]
	v_mfma_f32_16x16x32_bf16 v[72:75], v[140:143], v[216:219], v[72:75]
	v_mfma_f32_16x16x32_bf16 v[116:119], v[144:147], v[172:175], v[116:119]
	v_mfma_f32_16x16x32_bf16 v[112:115], v[164:167], v[172:175], v[112:115]
	v_mfma_f32_16x16x32_bf16 v[100:103], v[144:147], v[192:195], v[100:103]
	v_mfma_f32_16x16x32_bf16 v[96:99], v[164:167], v[192:195], v[96:99]
	v_mfma_f32_16x16x32_bf16 v[84:87], v[144:147], v[204:207], v[84:87]
	v_mfma_f32_16x16x32_bf16 v[80:83], v[164:167], v[204:207], v[80:83]
	v_mfma_f32_16x16x32_bf16 v[68:71], v[144:147], v[212:215], v[68:71]
	v_mfma_f32_16x16x32_bf16 v[64:67], v[164:167], v[212:215], v[64:67]
	v_mfma_f32_16x16x32_bf16 v[116:119], v[148:151], v[176:179], v[116:119]
	v_mfma_f32_16x16x32_bf16 v[112:115], v[168:171], v[176:179], v[112:115]
	v_mfma_f32_16x16x32_bf16 v[100:103], v[148:151], v[196:199], v[100:103]
	v_mfma_f32_16x16x32_bf16 v[96:99], v[168:171], v[196:199], v[96:99]
	v_mfma_f32_16x16x32_bf16 v[84:87], v[148:151], v[208:211], v[84:87]
	v_mfma_f32_16x16x32_bf16 v[80:83], v[168:171], v[208:211], v[80:83]
	v_mfma_f32_16x16x32_bf16 v[68:71], v[148:151], v[216:219], v[68:71]
	v_mfma_f32_16x16x32_bf16 v[64:67], v[168:171], v[216:219], v[64:67]
	s_barrier
	s_mov_b32 m0, s45
	v_lshl_add_u64 v[180:181], s[26:27], 0, v[154:155]
	s_add_u32 s22, s26, 0x160000
	ds_read_b128 v[172:175], v189 offset:16384
	ds_read_b128 v[176:179], v189 offset:17408
	ds_read_b128 v[192:195], v189 offset:18432
	ds_read_b128 v[196:199], v189 offset:19456
	ds_read_b128 v[204:207], v189 offset:20480
	ds_read_b128 v[208:211], v189 offset:21504
	ds_read_b128 v[212:215], v189 offset:22528
	ds_read_b128 v[216:219], v189 offset:23552
	global_load_lds_dwordx4 v[180:181], off
	v_lshl_add_u64 v[200:201], s[26:27], 0, v[158:159]
	s_mov_b32 m0, s48
	s_addc_u32 s23, s27, 0
	global_load_lds_dwordx4 v[200:201], off
	v_lshl_add_u64 v[202:203], s[22:23], 0, v[154:155]
	s_mov_b32 m0, s49
	v_lshl_add_u64 v[220:221], s[28:29], 0, v[156:157]
	global_load_lds_dwordx4 v[202:203], off
	s_add_i32 m0, s49, 0x2000
	v_lshl_add_u64 v[202:203], s[22:23], 0, v[158:159]
	global_load_lds_dwordx4 v[202:203], off
	s_mov_b32 m0, s36
	v_lshl_add_u64 v[202:203], s[28:29], 0, v[152:153]
	global_load_lds_dwordx4 v[202:203], off
	s_mov_b32 m0, s37
	s_nop 0
	global_load_lds_dwordx4 v[220:221], off
	s_waitcnt vmcnt(8)
	s_waitcnt lgkmcnt(0)
	s_barrier
; #define PG8_STAGE(bufoff, gbase, voff) do { _Pragma("unroll") for (int _i = 0; _i < 2; ++_i) \
;         __builtin_amdgcn_global_load_lds((const unsigned*)((const char*)(gbase) + (voff)[_i]), (LAS unsigned*)(lds + (bufoff) + ldsw + _i * 8192), 16, 0, 0); } while (0)
; #define PG8_LDA(dst, b, h) do { _Pragma("unroll") for (int m = 0; m < 4; ++m) _Pragma("unroll") for (int k = 0; k < 2; ++k) dst[m][k] = *(const LAS bf16x8*)(lds + PG8_SA(b, h) + aoff + m * 2048 + k * 1024); } while (0)
; #define PG8_LDB(dst, b, h) do { _Pragma("unroll") for (int n = 0; n < 2; ++n) _Pragma("unroll") for (int k = 0; k < 2; ++k) dst[n][k] = *(const LAS bf16x8*)(lds + PG8_SB(b, h) + boff + n * 2048 + k * 1024); } while (0)
; #define PG8_MMA(ai, bj, At, Bt) do { __builtin_amdgcn_s_setprio(1); _Pragma("unroll") for (int m = 0; m < 4; ++m) _Pragma("unroll") for (int n = 0; n < 2; ++n) _Pragma("unroll") for (int k = 0; k < 2; ++k) \
;         acc[ai][bj][m][n] = __builtin_amdgcn_mfma_f32_16x16x32_bf16(Bt[n][k], At[m][k], acc[ai][bj][m][n], 0, 0, 0); __builtin_amdgcn_s_setprio(0); } while (0)
; #define PG8_WAIT_V(n) asm volatile("s_waitcnt vmcnt(" #n ")" ::: "memory")
; #define PG8_WAIT_L(n) asm volatile("s_waitcnt lgkmcnt(" #n ")" ::: "memory")
; #define PG8_BAR __builtin_amdgcn_s_barrier()
; #define PG8_SCHED __builtin_amdgcn_sched_barrier(0)
; template <class Epi, class Sched, bool ALIGN_EPI = true>
; __device__ __forceinline__ void gemm_phase(LAS unsigned char* lds, const Gemm g, const Sched& S, const Epi& E) {
;     ...
;             PG8_WAIT_V(8); PG8_WAIT_L(0); PG8_BAR; PG8_MMA(1, 0, At, B0); PG8_MMA(1, 1, At, B1); PG8_BAR; PG8_SCHED;
;             PG8_LDB(B0, 1, 0); PG8_LDB(B1, 1, 1); PG8_SCHED; PG8_LDA(At, 1, 0); PG8_STAGE(PG8_SA(0, 1), a2 + hstep, voffA);
;             PG8_WAIT_V(8); PG8_WAIT_L(0); PG8_BAR; PG8_MMA(0, 0, At, B0); PG8_MMA(0, 1, At, B1); PG8_BAR; PG8_SCHED;
;             PG8_LDA(At, 1, 1); PG8_STAGE(PG8_SB(1, 0), b3, voffB); PG8_STAGE(PG8_SB(1, 1), b3 + hstep, voffB); PG8_STAGE(PG8_SA(1, 0), a3, voffA);
	v_mfma_f32_16x16x32_bf16 v[60:63], v[128:131], v[172:175], v[60:63]
	v_mfma_f32_16x16x32_bf16 v[56:59], v[136:139], v[172:175], v[56:59]
	v_mfma_f32_16x16x32_bf16 v[44:47], v[128:131], v[192:195], v[44:47]
	v_mfma_f32_16x16x32_bf16 v[40:43], v[136:139], v[192:195], v[40:43]
	v_mfma_f32_16x16x32_bf16 v[28:31], v[128:131], v[204:207], v[28:31]
	v_mfma_f32_16x16x32_bf16 v[24:27], v[136:139], v[204:207], v[24:27]
	v_mfma_f32_16x16x32_bf16 v[12:15], v[128:131], v[212:215], v[12:15]
	v_mfma_f32_16x16x32_bf16 v[8:11], v[136:139], v[212:215], v[8:11]
	v_mfma_f32_16x16x32_bf16 v[60:63], v[132:135], v[176:179], v[60:63]
	v_mfma_f32_16x16x32_bf16 v[56:59], v[140:143], v[176:179], v[56:59]
	v_mfma_f32_16x16x32_bf16 v[44:47], v[132:135], v[196:199], v[44:47]
	v_mfma_f32_16x16x32_bf16 v[40:43], v[140:143], v[196:199], v[40:43]
	v_mfma_f32_16x16x32_bf16 v[28:31], v[132:135], v[208:211], v[28:31]
	v_mfma_f32_16x16x32_bf16 v[24:27], v[140:143], v[208:211], v[24:27]
	v_mfma_f32_16x16x32_bf16 v[12:15], v[132:135], v[216:219], v[12:15]
	v_mfma_f32_16x16x32_bf16 v[8:11], v[140:143], v[216:219], v[8:11]
	v_mfma_f32_16x16x32_bf16 v[52:55], v[144:147], v[172:175], v[52:55]
	v_mfma_f32_16x16x32_bf16 v[48:51], v[164:167], v[172:175], v[48:51]
	v_mfma_f32_16x16x32_bf16 v[36:39], v[144:147], v[192:195], v[36:39]
	v_mfma_f32_16x16x32_bf16 v[32:35], v[164:167], v[192:195], v[32:35]
	v_mfma_f32_16x16x32_bf16 v[20:23], v[144:147], v[204:207], v[20:23]
	v_mfma_f32_16x16x32_bf16 v[16:19], v[164:167], v[204:207], v[16:19]
	v_mfma_f32_16x16x32_bf16 v[4:7], v[144:147], v[212:215], v[4:7]
	v_mfma_f32_16x16x32_bf16 v[0:3], v[164:167], v[212:215], v[0:3]
	v_mfma_f32_16x16x32_bf16 v[52:55], v[148:151], v[176:179], v[52:55]
	v_mfma_f32_16x16x32_bf16 v[48:51], v[168:171], v[176:179], v[48:51]
	v_mfma_f32_16x16x32_bf16 v[36:39], v[148:151], v[196:199], v[36:39]
	v_mfma_f32_16x16x32_bf16 v[32:35], v[168:171], v[196:199], v[32:35]
	v_mfma_f32_16x16x32_bf16 v[20:23], v[148:151], v[208:211], v[20:23]
	v_mfma_f32_16x16x32_bf16 v[16:19], v[168:171], v[208:211], v[16:19]
	v_mfma_f32_16x16x32_bf16 v[4:7], v[148:151], v[216:219], v[4:7]
	v_mfma_f32_16x16x32_bf16 v[0:3], v[168:171], v[216:219], v[0:3]
	s_barrier
	s_add_i32 s46, 0, 0x18000
	s_add_i32 s47, 0, 0x1c000
	v_add_u32_e32 v140, s46, v185
	v_add_u32_e32 v168, s47, v185
	ds_read_b128 v[128:131], v140
	ds_read_b128 v[132:135], v140 offset:1024
	ds_read_b128 v[136:139], v140 offset:2048
	ds_read_b128 v[140:143], v140 offset:3072
	ds_read_b128 v[144:147], v168
	ds_read_b128 v[148:151], v168 offset:1024
	ds_read_b128 v[164:167], v168 offset:2048
	ds_read_b128 v[168:171], v168 offset:3072
	s_add_u32 s22, s28, 0x160000
	s_addc_u32 s23, s29, 0
	s_mov_b32 m0, s38
	v_lshl_add_u64 v[222:223], s[22:23], 0, v[152:153]
	ds_read_b128 v[172:175], v189 offset:32768
	ds_read_b128 v[176:179], v189 offset:33792
	ds_read_b128 v[192:195], v189 offset:34816
	ds_read_b128 v[196:199], v189 offset:35840
	ds_read_b128 v[204:207], v189 offset:36864
	ds_read_b128 v[208:211], v189 offset:37888
	ds_read_b128 v[212:215], v189 offset:38912
	ds_read_b128 v[216:219], v189 offset:39936
	global_load_lds_dwordx4 v[222:223], off
	s_mov_b32 m0, s39
	v_lshl_add_u64 v[222:223], s[22:23], 0, v[156:157]
	global_load_lds_dwordx4 v[222:223], off
	s_waitcnt vmcnt(8)
	s_waitcnt lgkmcnt(0)
	s_barrier
	v_mfma_f32_16x16x32_bf16 v[124:127], v[128:131], v[172:175], v[124:127]
	v_mfma_f32_16x16x32_bf16 v[120:123], v[136:139], v[172:175], v[120:123]
	v_mfma_f32_16x16x32_bf16 v[108:111], v[128:131], v[192:195], v[108:111]
	v_mfma_f32_16x16x32_bf16 v[104:107], v[136:139], v[192:195], v[104:107]
	v_mfma_f32_16x16x32_bf16 v[92:95], v[128:131], v[204:207], v[92:95]
	v_mfma_f32_16x16x32_bf16 v[88:91], v[136:139], v[204:207], v[88:91]
	v_mfma_f32_16x16x32_bf16 v[76:79], v[128:131], v[212:215], v[76:79]
	v_mfma_f32_16x16x32_bf16 v[72:75], v[136:139], v[212:215], v[72:75]
	v_mfma_f32_16x16x32_bf16 v[124:127], v[132:135], v[176:179], v[124:127]
	v_mfma_f32_16x16x32_bf16 v[120:123], v[140:143], v[176:179], v[120:123]
	v_mfma_f32_16x16x32_bf16 v[108:111], v[132:135], v[196:199], v[108:111]
	v_mfma_f32_16x16x32_bf16 v[104:107], v[140:143], v[196:199], v[104:107]
	v_mfma_f32_16x16x32_bf16 v[92:95], v[132:135], v[208:211], v[92:95]
	v_mfma_f32_16x16x32_bf16 v[88:91], v[140:143], v[208:211], v[88:91]
	v_mfma_f32_16x16x32_bf16 v[76:79], v[132:135], v[216:219], v[76:79]
	v_mfma_f32_16x16x32_bf16 v[72:75], v[140:143], v[216:219], v[72:75]
	v_mfma_f32_16x16x32_bf16 v[116:119], v[144:147], v[172:175], v[116:119]
	v_mfma_f32_16x16x32_bf16 v[112:115], v[164:167], v[172:175], v[112:115]
	v_mfma_f32_16x16x32_bf16 v[100:103], v[144:147], v[192:195], v[100:103]
	v_mfma_f32_16x16x32_bf16 v[96:99], v[164:167], v[192:195], v[96:99]
	v_mfma_f32_16x16x32_bf16 v[84:87], v[144:147], v[204:207], v[84:87]
	v_mfma_f32_16x16x32_bf16 v[80:83], v[164:167], v[204:207], v[80:83]
	v_mfma_f32_16x16x32_bf16 v[68:71], v[144:147], v[212:215], v[68:71]
	v_mfma_f32_16x16x32_bf16 v[64:67], v[164:167], v[212:215], v[64:67]
	v_mfma_f32_16x16x32_bf16 v[116:119], v[148:151], v[176:179], v[116:119]
	v_mfma_f32_16x16x32_bf16 v[112:115], v[168:171], v[176:179], v[112:115]
	v_mfma_f32_16x16x32_bf16 v[100:103], v[148:151], v[196:199], v[100:103]
	v_mfma_f32_16x16x32_bf16 v[96:99], v[168:171], v[196:199], v[96:99]
	v_mfma_f32_16x16x32_bf16 v[84:87], v[148:151], v[208:211], v[84:87]
	v_mfma_f32_16x16x32_bf16 v[80:83], v[168:171], v[208:211], v[80:83]
	v_mfma_f32_16x16x32_bf16 v[68:71], v[148:151], v[216:219], v[68:71]
	v_mfma_f32_16x16x32_bf16 v[64:67], v[168:171], v[216:219], v[64:67]
	s_barrier
; #define PG8_STAGE(bufoff, gbase, voff) do { _Pragma("unroll") for (int _i = 0; _i < 2; ++_i) \
;         __builtin_amdgcn_global_load_lds((const unsigned*)((const char*)(gbase) + (voff)[_i]), (LAS unsigned*)(lds + (bufoff) + ldsw + _i * 8192), 16, 0, 0); } while (0)
; #define PG8_LDA(dst, b, h) do { _Pragma("unroll") for (int m = 0; m < 4; ++m) _Pragma("unroll") for (int k = 0; k < 2; ++k) dst[m][k] = *(const LAS bf16x8*)(lds + PG8_SA(b, h) + aoff + m * 2048 + k * 1024); } while (0)
; #define PG8_MMA(ai, bj, At, Bt) do { __builtin_amdgcn_s_setprio(1); _Pragma("unroll") for (int m = 0; m < 4; ++m) _Pragma("unroll") for (int n = 0; n < 2; ++n) _Pragma("unroll") for (int k = 0; k < 2; ++k) \
;         acc[ai][bj][m][n] = __builtin_amdgcn_mfma_f32_16x16x32_bf16(Bt[n][k], At[m][k], acc[ai][bj][m][n], 0, 0, 0); __builtin_amdgcn_s_setprio(0); } while (0)
; #define PG8_WAIT_V(n) asm volatile("s_waitcnt vmcnt(" #n ")" ::: "memory")
; #define PG8_WAIT_L(n) asm volatile("s_waitcnt lgkmcnt(" #n ")" ::: "memory")
; #define PG8_BAR __builtin_amdgcn_s_barrier()
; #define PG8_SCHED __builtin_amdgcn_sched_barrier(0)
; template <class Epi, class Sched, bool ALIGN_EPI = true>
; __device__ __forceinline__ void gemm_phase(LAS unsigned char* lds, const Gemm g, const Sched& S, const Epi& E) {
;     ...
;             PG8_LDA(At, 1, 1); PG8_STAGE(PG8_SB(1, 0), b3, voffB); PG8_STAGE(PG8_SB(1, 1), b3 + hstep, voffB); PG8_STAGE(PG8_SA(1, 0), a3, voffA);
;             PG8_WAIT_V(8); PG8_WAIT_L(0); PG8_BAR; PG8_MMA(1, 0, At, B0); PG8_MMA(1, 1, At, B1); PG8_BAR; PG8_SCHED;
;         }
	s_add_i32 s22, s46, s35
	v_lshl_add_u64 v[180:181], v[180:181], 0, s[14:15]
	s_mov_b32 m0, s22
	ds_read_b128 v[172:175], v189 offset:49152
	ds_read_b128 v[176:179], v189 offset:50176
	ds_read_b128 v[192:195], v189 offset:51200
	ds_read_b128 v[196:199], v189 offset:52224
	ds_read_b128 v[204:207], v189 offset:53248
	ds_read_b128 v[208:211], v189 offset:54272
	ds_read_b128 v[212:215], v189 offset:55296
	ds_read_b128 v[216:219], v189 offset:56320
	global_load_lds_dwordx4 v[180:181], off
	s_add_i32 m0, s22, 0x2000
	s_add_u32 s22, s26, 0x160080
	v_lshl_add_u64 v[180:181], v[200:201], 0, s[14:15]
	s_addc_u32 s23, s27, 0
	s_add_i32 s26, s47, s35
	global_load_lds_dwordx4 v[180:181], off
	s_mov_b32 m0, s26
	v_lshl_add_u64 v[180:181], s[22:23], 0, v[154:155]
	global_load_lds_dwordx4 v[180:181], off
	s_add_i32 m0, s26, 0x2000
	v_lshl_add_u64 v[180:181], s[22:23], 0, v[158:159]
	global_load_lds_dwordx4 v[180:181], off
	s_mov_b32 m0, s40
	v_lshl_add_u64 v[180:181], v[202:203], 0, s[14:15]
	global_load_lds_dwordx4 v[180:181], off
	s_mov_b32 m0, s41
	v_lshl_add_u64 v[180:181], v[220:221], 0, s[14:15]
	global_load_lds_dwordx4 v[180:181], off
	s_waitcnt vmcnt(8)
	s_waitcnt lgkmcnt(0)
	s_barrier
	v_mfma_f32_16x16x32_bf16 v[60:63], v[128:131], v[172:175], v[60:63]
	v_mfma_f32_16x16x32_bf16 v[56:59], v[136:139], v[172:175], v[56:59]
	v_mfma_f32_16x16x32_bf16 v[44:47], v[128:131], v[192:195], v[44:47]
	v_mfma_f32_16x16x32_bf16 v[40:43], v[136:139], v[192:195], v[40:43]
	v_mfma_f32_16x16x32_bf16 v[28:31], v[128:131], v[204:207], v[28:31]
	v_mfma_f32_16x16x32_bf16 v[24:27], v[136:139], v[204:207], v[24:27]
	v_mfma_f32_16x16x32_bf16 v[12:15], v[128:131], v[212:215], v[12:15]
	v_mfma_f32_16x16x32_bf16 v[8:11], v[136:139], v[212:215], v[8:11]
	v_mfma_f32_16x16x32_bf16 v[60:63], v[132:135], v[176:179], v[60:63]
	v_mfma_f32_16x16x32_bf16 v[56:59], v[140:143], v[176:179], v[56:59]
	v_mfma_f32_16x16x32_bf16 v[44:47], v[132:135], v[196:199], v[44:47]
	v_mfma_f32_16x16x32_bf16 v[40:43], v[140:143], v[196:199], v[40:43]
	v_mfma_f32_16x16x32_bf16 v[28:31], v[132:135], v[208:211], v[28:31]
	v_mfma_f32_16x16x32_bf16 v[24:27], v[140:143], v[208:211], v[24:27]
	v_mfma_f32_16x16x32_bf16 v[12:15], v[132:135], v[216:219], v[12:15]
	v_mfma_f32_16x16x32_bf16 v[8:11], v[140:143], v[216:219], v[8:11]
	v_mfma_f32_16x16x32_bf16 v[52:55], v[144:147], v[172:175], v[52:55]
	v_mfma_f32_16x16x32_bf16 v[48:51], v[164:167], v[172:175], v[48:51]
	v_mfma_f32_16x16x32_bf16 v[36:39], v[144:147], v[192:195], v[36:39]
	v_mfma_f32_16x16x32_bf16 v[32:35], v[164:167], v[192:195], v[32:35]
	v_mfma_f32_16x16x32_bf16 v[20:23], v[144:147], v[204:207], v[20:23]
	v_mfma_f32_16x16x32_bf16 v[16:19], v[164:167], v[204:207], v[16:19]
	v_mfma_f32_16x16x32_bf16 v[4:7], v[144:147], v[212:215], v[4:7]
	v_mfma_f32_16x16x32_bf16 v[0:3], v[164:167], v[212:215], v[0:3]
	v_mfma_f32_16x16x32_bf16 v[52:55], v[148:151], v[176:179], v[52:55]
	v_mfma_f32_16x16x32_bf16 v[48:51], v[168:171], v[176:179], v[48:51]
	v_mfma_f32_16x16x32_bf16 v[36:39], v[148:151], v[196:199], v[36:39]
	v_mfma_f32_16x16x32_bf16 v[32:35], v[168:171], v[196:199], v[32:35]
	v_mfma_f32_16x16x32_bf16 v[20:23], v[148:151], v[208:211], v[20:23]
	v_mfma_f32_16x16x32_bf16 v[16:19], v[168:171], v[208:211], v[16:19]
	v_mfma_f32_16x16x32_bf16 v[4:7], v[148:151], v[216:219], v[4:7]
	v_mfma_f32_16x16x32_bf16 v[0:3], v[168:171], v[216:219], v[0:3]
	s_barrier
	s_add_i32 s56, s56, 2
	s_add_u32 s54, s54, 0x100
	s_addc_u32 s55, s55, 0
	s_cmpk_gt_u32 s56, 0x55
	s_mov_b64 s[22:23], s[24:25]
	s_cbranch_scc0 .LBB0_746
	s_and_b64 vcc, exec, s[16:17]
	s_cbranch_vccz .LBB0_749
	s_barrier

; #define PG8_STAGE(bufoff, gbase, voff) do { _Pragma("unroll") for (int _i = 0; _i < 2; ++_i) \
;         __builtin_amdgcn_global_load_lds((const unsigned*)((const char*)(gbase) + (voff)[_i]), (LAS unsigned*)(lds + (bufoff) + ldsw + _i * 8192), 16, 0, 0); } while (0)
; #define PG8_LDA(dst, b, h) do { _Pragma("unroll") for (int m = 0; m < 4; ++m) _Pragma("unroll") for (int k = 0; k < 2; ++k) dst[m][k] = *(const LAS bf16x8*)(lds + PG8_SA(b, h) + aoff + m * 2048 + k * 1024); } while (0)
; #define PG8_LDB(dst, b, h) do { _Pragma("unroll") for (int n = 0; n < 2; ++n) _Pragma("unroll") for (int k = 0; k < 2; ++k) dst[n][k] = *(const LAS bf16x8*)(lds + PG8_SB(b, h) + boff + n * 2048 + k * 1024); } while (0)
; #define PG8_MMA(ai, bj, At, Bt) do { __builtin_amdgcn_s_setprio(1); _Pragma("unroll") for (int m = 0; m < 4; ++m) _Pragma("unroll") for (int n = 0; n < 2; ++n) _Pragma("unroll") for (int k = 0; k < 2; ++k) \
;         acc[ai][bj][m][n] = __builtin_amdgcn_mfma_f32_16x16x32_bf16(Bt[n][k], At[m][k], acc[ai][bj][m][n], 0, 0, 0); __builtin_amdgcn_s_setprio(0); } while (0)
; #define PG8_WAIT_V(n) asm volatile("s_waitcnt vmcnt(" #n ")" ::: "memory")
; #define PG8_WAIT_L(n) asm volatile("s_waitcnt lgkmcnt(" #n ")" ::: "memory")
; #define PG8_BAR __builtin_amdgcn_s_barrier()
; #define PG8_SCHED __builtin_amdgcn_sched_barrier(0)
; template <class Epi, class Sched, bool ALIGN_EPI = true>
; __device__ __forceinline__ void gemm_phase(LAS unsigned char* lds, const Gemm g, const Sched& S, const Epi& E) {
;     ...
;             PG8_LDB(B0, 0, 0); PG8_LDB(B1, 0, 1); PG8_SCHED; PG8_LDA(At, 0, 0); PG8_STAGE(PG8_SA(1, 1), a1 + hstep, voffA);
;             PG8_WAIT_V(8); PG8_WAIT_L(0); PG8_BAR; PG8_MMA(0, 0, At, B0); PG8_MMA(0, 1, At, B1); PG8_BAR; PG8_SCHED;
;             PG8_LDA(At, 0, 1); PG8_STAGE(PG8_SB(0, 0), b2, voffB); PG8_STAGE(PG8_SB(0, 1), b2 + hstep, voffB); PG8_STAGE(PG8_SA(0, 0), a2, voffA);
;             PG8_WAIT_V(8); PG8_WAIT_L(0); PG8_BAR; PG8_MMA(1, 0, At, B0); PG8_MMA(1, 1, At, B1); PG8_BAR; PG8_SCHED;
;             PG8_LDB(B0, 1, 0); PG8_LDB(B1, 1, 1); PG8_SCHED; PG8_LDA(At, 1, 0); PG8_STAGE(PG8_SA(0, 1), a2 + hstep, voffA);
.LBB0_837:
	ds_read_b128 v[120:123], v208
	ds_read_b128 v[124:127], v208 offset:1024
	ds_read_b128 v[132:135], v208 offset:2048
	ds_read_b128 v[136:139], v208 offset:3072
	ds_read_b128 v[144:147], v209
	ds_read_b128 v[148:151], v209 offset:1024
	ds_read_b128 v[152:155], v209 offset:2048
	ds_read_b128 v[156:159], v209 offset:3072
	s_add_u32 s36, s34, 0xfff80080
	s_addc_u32 s37, s35, -1
	s_cmp_eq_u32 s60, 28
	s_cselect_b32 s39, s55, s37
	s_cselect_b32 s38, s56, s36
	s_cselect_b32 s37, s11, s59
	s_cselect_b32 s36, s57, s58
	v_lshl_add_u64 v[200:201], s[34:35], 0, v[184:185]
	s_add_i32 m0, s42, 0xc000
	ds_read_b128 v[160:163], v210
	ds_read_b128 v[164:167], v210 offset:1024
	ds_read_b128 v[168:171], v210 offset:2048
	ds_read_b128 v[172:175], v210 offset:3072
	ds_read_b128 v[188:191], v210 offset:4096
	ds_read_b128 v[192:195], v210 offset:5120
	ds_read_b128 v[196:199], v210 offset:6144
	ds_read_b128 v[214:217], v210 offset:7168
	global_load_lds_dwordx4 v[200:201], off
	s_add_i32 m0, s42, 0xe000
	v_lshl_add_u64 v[200:201], s[34:35], 0, v[186:187]
	global_load_lds_dwordx4 v[200:201], off
	s_waitcnt vmcnt(8)
	s_waitcnt lgkmcnt(0)
	s_barrier
	v_mfma_f32_16x16x32_bf16 v[140:143], v[120:123], v[160:163], v[140:143]
	v_mfma_f32_16x16x32_bf16 v[128:131], v[132:135], v[160:163], v[128:131]
	v_mfma_f32_16x16x32_bf16 v[108:111], v[120:123], v[168:171], v[108:111]
	v_mfma_f32_16x16x32_bf16 v[104:107], v[132:135], v[168:171], v[104:107]
	v_mfma_f32_16x16x32_bf16 v[92:95], v[120:123], v[188:191], v[92:95]
	v_mfma_f32_16x16x32_bf16 v[88:91], v[132:135], v[188:191], v[88:91]
	v_mfma_f32_16x16x32_bf16 v[76:79], v[120:123], v[196:199], v[76:79]
	v_mfma_f32_16x16x32_bf16 v[72:75], v[132:135], v[196:199], v[72:75]
	v_mfma_f32_16x16x32_bf16 v[140:143], v[124:127], v[164:167], v[140:143]
	v_mfma_f32_16x16x32_bf16 v[128:131], v[136:139], v[164:167], v[128:131]
	v_mfma_f32_16x16x32_bf16 v[108:111], v[124:127], v[172:175], v[108:111]
	v_mfma_f32_16x16x32_bf16 v[104:107], v[136:139], v[172:175], v[104:107]
	v_mfma_f32_16x16x32_bf16 v[92:95], v[124:127], v[192:195], v[92:95]
	v_mfma_f32_16x16x32_bf16 v[88:91], v[136:139], v[192:195], v[88:91]
	v_mfma_f32_16x16x32_bf16 v[76:79], v[124:127], v[214:217], v[76:79]
	v_mfma_f32_16x16x32_bf16 v[72:75], v[136:139], v[214:217], v[72:75]
	v_mfma_f32_16x16x32_bf16 v[116:119], v[144:147], v[160:163], v[116:119]
	v_mfma_f32_16x16x32_bf16 v[112:115], v[152:155], v[160:163], v[112:115]
	v_mfma_f32_16x16x32_bf16 v[100:103], v[144:147], v[168:171], v[100:103]
	v_mfma_f32_16x16x32_bf16 v[96:99], v[152:155], v[168:171], v[96:99]
	v_mfma_f32_16x16x32_bf16 v[84:87], v[144:147], v[188:191], v[84:87]
	v_mfma_f32_16x16x32_bf16 v[80:83], v[152:155], v[188:191], v[80:83]
	v_mfma_f32_16x16x32_bf16 v[68:71], v[144:147], v[196:199], v[68:71]
	v_mfma_f32_16x16x32_bf16 v[64:67], v[152:155], v[196:199], v[64:67]
	v_mfma_f32_16x16x32_bf16 v[116:119], v[148:151], v[164:167], v[116:119]
	v_mfma_f32_16x16x32_bf16 v[112:115], v[156:159], v[164:167], v[112:115]
	v_mfma_f32_16x16x32_bf16 v[100:103], v[148:151], v[172:175], v[100:103]
	v_mfma_f32_16x16x32_bf16 v[96:99], v[156:159], v[172:175], v[96:99]
	v_mfma_f32_16x16x32_bf16 v[84:87], v[148:151], v[192:195], v[84:87]
	v_mfma_f32_16x16x32_bf16 v[80:83], v[156:159], v[192:195], v[80:83]
	v_mfma_f32_16x16x32_bf16 v[68:71], v[148:151], v[214:217], v[68:71]
	v_mfma_f32_16x16x32_bf16 v[64:67], v[156:159], v[214:217], v[64:67]
	s_barrier
	s_add_i32 s46, s50, s41
	v_lshl_add_u64 v[200:201], s[36:37], 0, v[178:179]
	s_mov_b32 m0, s46
	ds_read_b128 v[160:163], v210 offset:16384
	ds_read_b128 v[164:167], v210 offset:17408
	ds_read_b128 v[168:171], v210 offset:18432
	ds_read_b128 v[172:175], v210 offset:19456
	ds_read_b128 v[188:191], v210 offset:20480
	ds_read_b128 v[192:195], v210 offset:21504
	ds_read_b128 v[196:199], v210 offset:22528
	ds_read_b128 v[214:217], v210 offset:23552
	global_load_lds_dwordx4 v[200:201], off
	s_add_i32 m0, s46, 0x2000
	s_add_u32 s46, s36, 0x80000
	v_lshl_add_u64 v[218:219], s[36:37], 0, v[182:183]
	s_addc_u32 s47, s37, 0
	s_add_i32 s61, s51, s41
	global_load_lds_dwordx4 v[218:219], off
	v_lshl_add_u64 v[220:221], s[46:47], 0, v[178:179]
	s_mov_b32 m0, s61
	v_lshl_add_u64 v[222:223], s[38:39], 0, v[180:181]
	global_load_lds_dwordx4 v[220:221], off
	s_add_i32 m0, s61, 0x2000
	v_lshl_add_u64 v[220:221], s[46:47], 0, v[182:183]
	global_load_lds_dwordx4 v[220:221], off
	s_mov_b32 m0, s42
	v_lshl_add_u64 v[220:221], s[38:39], 0, v[176:177]
	global_load_lds_dwordx4 v[220:221], off
	s_mov_b32 m0, s43
	s_nop 0
	global_load_lds_dwordx4 v[222:223], off
	s_waitcnt vmcnt(8)
	s_waitcnt lgkmcnt(0)
	s_barrier
; #define PG8_STAGE(bufoff, gbase, voff) do { _Pragma("unroll") for (int _i = 0; _i < 2; ++_i) \
;         __builtin_amdgcn_global_load_lds((const unsigned*)((const char*)(gbase) + (voff)[_i]), (LAS unsigned*)(lds + (bufoff) + ldsw + _i * 8192), 16, 0, 0); } while (0)
; #define PG8_LDA(dst, b, h) do { _Pragma("unroll") for (int m = 0; m < 4; ++m) _Pragma("unroll") for (int k = 0; k < 2; ++k) dst[m][k] = *(const LAS bf16x8*)(lds + PG8_SA(b, h) + aoff + m * 2048 + k * 1024); } while (0)
; #define PG8_LDB(dst, b, h) do { _Pragma("unroll") for (int n = 0; n < 2; ++n) _Pragma("unroll") for (int k = 0; k < 2; ++k) dst[n][k] = *(const LAS bf16x8*)(lds + PG8_SB(b, h) + boff + n * 2048 + k * 1024); } while (0)
; #define PG8_MMA(ai, bj, At, Bt) do { __builtin_amdgcn_s_setprio(1); _Pragma("unroll") for (int m = 0; m < 4; ++m) _Pragma("unroll") for (int n = 0; n < 2; ++n) _Pragma("unroll") for (int k = 0; k < 2; ++k) \
;         acc[ai][bj][m][n] = __builtin_amdgcn_mfma_f32_16x16x32_bf16(Bt[n][k], At[m][k], acc[ai][bj][m][n], 0, 0, 0); __builtin_amdgcn_s_setprio(0); } while (0)
; #define PG8_WAIT_V(n) asm volatile("s_waitcnt vmcnt(" #n ")" ::: "memory")
; #define PG8_WAIT_L(n) asm volatile("s_waitcnt lgkmcnt(" #n ")" ::: "memory")
; #define PG8_BAR __builtin_amdgcn_s_barrier()
; #define PG8_SCHED __builtin_amdgcn_sched_barrier(0)
; template <class Epi, class Sched, bool ALIGN_EPI = true>
; __device__ __forceinline__ void gemm_phase(LAS unsigned char* lds, const Gemm g, const Sched& S, const Epi& E) {
;     ...
;             PG8_WAIT_V(8); PG8_WAIT_L(0); PG8_BAR; PG8_MMA(1, 0, At, B0); PG8_MMA(1, 1, At, B1); PG8_BAR; PG8_SCHED;
;             PG8_LDB(B0, 1, 0); PG8_LDB(B1, 1, 1); PG8_SCHED; PG8_LDA(At, 1, 0); PG8_STAGE(PG8_SA(0, 1), a2 + hstep, voffA);
;             PG8_WAIT_V(8); PG8_WAIT_L(0); PG8_BAR; PG8_MMA(0, 0, At, B0); PG8_MMA(0, 1, At, B1); PG8_BAR; PG8_SCHED;
	v_mfma_f32_16x16x32_bf16 v[60:63], v[120:123], v[160:163], v[60:63]
	v_mfma_f32_16x16x32_bf16 v[56:59], v[132:135], v[160:163], v[56:59]
	v_mfma_f32_16x16x32_bf16 v[44:47], v[120:123], v[168:171], v[44:47]
	v_mfma_f32_16x16x32_bf16 v[40:43], v[132:135], v[168:171], v[40:43]
	v_mfma_f32_16x16x32_bf16 v[28:31], v[120:123], v[188:191], v[28:31]
	v_mfma_f32_16x16x32_bf16 v[24:27], v[132:135], v[188:191], v[24:27]
	v_mfma_f32_16x16x32_bf16 v[12:15], v[120:123], v[196:199], v[12:15]
	v_mfma_f32_16x16x32_bf16 v[8:11], v[132:135], v[196:199], v[8:11]
	v_mfma_f32_16x16x32_bf16 v[60:63], v[124:127], v[164:167], v[60:63]
	v_mfma_f32_16x16x32_bf16 v[56:59], v[136:139], v[164:167], v[56:59]
	v_mfma_f32_16x16x32_bf16 v[44:47], v[124:127], v[172:175], v[44:47]
	v_mfma_f32_16x16x32_bf16 v[40:43], v[136:139], v[172:175], v[40:43]
	v_mfma_f32_16x16x32_bf16 v[28:31], v[124:127], v[192:195], v[28:31]
	v_mfma_f32_16x16x32_bf16 v[24:27], v[136:139], v[192:195], v[24:27]
	v_mfma_f32_16x16x32_bf16 v[12:15], v[124:127], v[214:217], v[12:15]
	v_mfma_f32_16x16x32_bf16 v[8:11], v[136:139], v[214:217], v[8:11]
	v_mfma_f32_16x16x32_bf16 v[52:55], v[144:147], v[160:163], v[52:55]
	v_mfma_f32_16x16x32_bf16 v[48:51], v[152:155], v[160:163], v[48:51]
	v_mfma_f32_16x16x32_bf16 v[36:39], v[144:147], v[168:171], v[36:39]
	v_mfma_f32_16x16x32_bf16 v[32:35], v[152:155], v[168:171], v[32:35]
	v_mfma_f32_16x16x32_bf16 v[20:23], v[144:147], v[188:191], v[20:23]
	v_mfma_f32_16x16x32_bf16 v[16:19], v[152:155], v[188:191], v[16:19]
	v_mfma_f32_16x16x32_bf16 v[4:7], v[144:147], v[196:199], v[4:7]
	v_mfma_f32_16x16x32_bf16 v[0:3], v[152:155], v[196:199], v[0:3]
	v_mfma_f32_16x16x32_bf16 v[52:55], v[148:151], v[164:167], v[52:55]
	v_mfma_f32_16x16x32_bf16 v[48:51], v[156:159], v[164:167], v[48:51]
	v_mfma_f32_16x16x32_bf16 v[36:39], v[148:151], v[172:175], v[36:39]
	v_mfma_f32_16x16x32_bf16 v[32:35], v[156:159], v[172:175], v[32:35]
	v_mfma_f32_16x16x32_bf16 v[20:23], v[148:151], v[192:195], v[20:23]
	v_mfma_f32_16x16x32_bf16 v[16:19], v[156:159], v[192:195], v[16:19]
	v_mfma_f32_16x16x32_bf16 v[4:7], v[148:151], v[214:217], v[4:7]
	v_mfma_f32_16x16x32_bf16 v[0:3], v[156:159], v[214:217], v[0:3]
	s_barrier
	s_add_i32 s46, 0, 0x18000
	s_add_i32 s47, 0, 0x1c000
	v_add_u32_e32 v136, s46, v206
	v_add_u32_e32 v156, s47, v206
	ds_read_b128 v[120:123], v136
	ds_read_b128 v[124:127], v136 offset:1024
	ds_read_b128 v[132:135], v136 offset:2048
	ds_read_b128 v[136:139], v136 offset:3072
	ds_read_b128 v[144:147], v156
	ds_read_b128 v[148:151], v156 offset:1024
	ds_read_b128 v[152:155], v156 offset:2048
	ds_read_b128 v[156:159], v156 offset:3072
	s_add_u32 s38, s38, 0x80000
	s_addc_u32 s39, s39, 0
	s_mov_b32 m0, s44
	v_lshl_add_u64 v[224:225], s[38:39], 0, v[176:177]
	ds_read_b128 v[160:163], v210 offset:32768
	ds_read_b128 v[164:167], v210 offset:33792
	ds_read_b128 v[168:171], v210 offset:34816
	ds_read_b128 v[172:175], v210 offset:35840
	ds_read_b128 v[188:191], v210 offset:36864
	ds_read_b128 v[192:195], v210 offset:37888
	ds_read_b128 v[196:199], v210 offset:38912
	ds_read_b128 v[214:217], v210 offset:39936
	global_load_lds_dwordx4 v[224:225], off
	s_mov_b32 m0, s45
	v_lshl_add_u64 v[224:225], s[38:39], 0, v[180:181]
	global_load_lds_dwordx4 v[224:225], off
	s_waitcnt vmcnt(8)
	s_waitcnt lgkmcnt(0)
	s_barrier
	v_mfma_f32_16x16x32_bf16 v[140:143], v[120:123], v[160:163], v[140:143]
	v_mfma_f32_16x16x32_bf16 v[128:131], v[132:135], v[160:163], v[128:131]
	v_mfma_f32_16x16x32_bf16 v[108:111], v[120:123], v[168:171], v[108:111]
	v_mfma_f32_16x16x32_bf16 v[104:107], v[132:135], v[168:171], v[104:107]
	v_mfma_f32_16x16x32_bf16 v[92:95], v[120:123], v[188:191], v[92:95]
	v_mfma_f32_16x16x32_bf16 v[88:91], v[132:135], v[188:191], v[88:91]
	v_mfma_f32_16x16x32_bf16 v[76:79], v[120:123], v[196:199], v[76:79]
	v_mfma_f32_16x16x32_bf16 v[72:75], v[132:135], v[196:199], v[72:75]
	v_mfma_f32_16x16x32_bf16 v[140:143], v[124:127], v[164:167], v[140:143]
	v_mfma_f32_16x16x32_bf16 v[128:131], v[136:139], v[164:167], v[128:131]
	v_mfma_f32_16x16x32_bf16 v[108:111], v[124:127], v[172:175], v[108:111]
	v_mfma_f32_16x16x32_bf16 v[104:107], v[136:139], v[172:175], v[104:107]
	v_mfma_f32_16x16x32_bf16 v[92:95], v[124:127], v[192:195], v[92:95]
	v_mfma_f32_16x16x32_bf16 v[88:91], v[136:139], v[192:195], v[88:91]
	v_mfma_f32_16x16x32_bf16 v[76:79], v[124:127], v[214:217], v[76:79]
	v_mfma_f32_16x16x32_bf16 v[72:75], v[136:139], v[214:217], v[72:75]
	v_mfma_f32_16x16x32_bf16 v[116:119], v[144:147], v[160:163], v[116:119]
	v_mfma_f32_16x16x32_bf16 v[112:115], v[152:155], v[160:163], v[112:115]
	v_mfma_f32_16x16x32_bf16 v[100:103], v[144:147], v[168:171], v[100:103]
	v_mfma_f32_16x16x32_bf16 v[96:99], v[152:155], v[168:171], v[96:99]
	v_mfma_f32_16x16x32_bf16 v[84:87], v[144:147], v[188:191], v[84:87]
	v_mfma_f32_16x16x32_bf16 v[80:83], v[152:155], v[188:191], v[80:83]
	v_mfma_f32_16x16x32_bf16 v[68:71], v[144:147], v[196:199], v[68:71]
	v_mfma_f32_16x16x32_bf16 v[64:67], v[152:155], v[196:199], v[64:67]
	v_mfma_f32_16x16x32_bf16 v[116:119], v[148:151], v[164:167], v[116:119]
	v_mfma_f32_16x16x32_bf16 v[112:115], v[156:159], v[164:167], v[112:115]
	v_mfma_f32_16x16x32_bf16 v[100:103], v[148:151], v[172:175], v[100:103]
	v_mfma_f32_16x16x32_bf16 v[96:99], v[156:159], v[172:175], v[96:99]
	v_mfma_f32_16x16x32_bf16 v[84:87], v[148:151], v[192:195], v[84:87]
	v_mfma_f32_16x16x32_bf16 v[80:83], v[156:159], v[192:195], v[80:83]
	v_mfma_f32_16x16x32_bf16 v[68:71], v[148:151], v[214:217], v[68:71]
	v_mfma_f32_16x16x32_bf16 v[64:67], v[156:159], v[214:217], v[64:67]
	s_barrier
; #define PG8_STAGE(bufoff, gbase, voff) do { _Pragma("unroll") for (int _i = 0; _i < 2; ++_i) \
;         __builtin_amdgcn_global_load_lds((const unsigned*)((const char*)(gbase) + (voff)[_i]), (LAS unsigned*)(lds + (bufoff) + ldsw + _i * 8192), 16, 0, 0); } while (0)
; #define PG8_LDA(dst, b, h) do { _Pragma("unroll") for (int m = 0; m < 4; ++m) _Pragma("unroll") for (int k = 0; k < 2; ++k) dst[m][k] = *(const LAS bf16x8*)(lds + PG8_SA(b, h) + aoff + m * 2048 + k * 1024); } while (0)
; #define PG8_MMA(ai, bj, At, Bt) do { __builtin_amdgcn_s_setprio(1); _Pragma("unroll") for (int m = 0; m < 4; ++m) _Pragma("unroll") for (int n = 0; n < 2; ++n) _Pragma("unroll") for (int k = 0; k < 2; ++k) \
;         acc[ai][bj][m][n] = __builtin_amdgcn_mfma_f32_16x16x32_bf16(Bt[n][k], At[m][k], acc[ai][bj][m][n], 0, 0, 0); __builtin_amdgcn_s_setprio(0); } while (0)
; #define PG8_WAIT_V(n) asm volatile("s_waitcnt vmcnt(" #n ")" ::: "memory")
; #define PG8_WAIT_L(n) asm volatile("s_waitcnt lgkmcnt(" #n ")" ::: "memory")
; #define PG8_BAR __builtin_amdgcn_s_barrier()
; #define PG8_SCHED __builtin_amdgcn_sched_barrier(0)
; template <class Epi, class Sched, bool ALIGN_EPI = true>
; __device__ __forceinline__ void gemm_phase(LAS unsigned char* lds, const Gemm g, const Sched& S, const Epi& E) {
;     ...
;             PG8_LDA(At, 1, 1); PG8_STAGE(PG8_SB(1, 0), b3, voffB); PG8_STAGE(PG8_SB(1, 1), b3 + hstep, voffB); PG8_STAGE(PG8_SA(1, 0), a3, voffA);
;             PG8_WAIT_V(8); PG8_WAIT_L(0); PG8_BAR; PG8_MMA(1, 0, At, B0); PG8_MMA(1, 1, At, B1); PG8_BAR; PG8_SCHED;
;         }
	s_add_i32 s38, s46, s41
	v_lshl_add_u64 v[200:201], v[200:201], 0, s[26:27]
	s_mov_b32 m0, s38
	ds_read_b128 v[160:163], v210 offset:49152
	ds_read_b128 v[164:167], v210 offset:50176
	ds_read_b128 v[168:171], v210 offset:51200
	ds_read_b128 v[172:175], v210 offset:52224
	ds_read_b128 v[188:191], v210 offset:53248
	ds_read_b128 v[192:195], v210 offset:54272
	ds_read_b128 v[196:199], v210 offset:55296
	ds_read_b128 v[214:217], v210 offset:56320
	global_load_lds_dwordx4 v[200:201], off
	s_add_i32 m0, s38, 0x2000
	s_add_u32 s36, s36, 0x80080
	v_lshl_add_u64 v[200:201], v[218:219], 0, s[26:27]
	s_addc_u32 s37, s37, 0
	s_add_i32 s38, s47, s41
	global_load_lds_dwordx4 v[200:201], off
	s_mov_b32 m0, s38
	v_lshl_add_u64 v[200:201], s[36:37], 0, v[178:179]
	global_load_lds_dwordx4 v[200:201], off
	s_add_i32 m0, s38, 0x2000
	v_lshl_add_u64 v[200:201], s[36:37], 0, v[182:183]
	global_load_lds_dwordx4 v[200:201], off
	s_mov_b32 m0, s48
	v_lshl_add_u64 v[200:201], v[220:221], 0, s[26:27]
	global_load_lds_dwordx4 v[200:201], off
	s_mov_b32 m0, s49
	v_lshl_add_u64 v[200:201], v[222:223], 0, s[26:27]
	global_load_lds_dwordx4 v[200:201], off
	s_waitcnt vmcnt(8)
	s_waitcnt lgkmcnt(0)
	s_barrier
	v_mfma_f32_16x16x32_bf16 v[60:63], v[120:123], v[160:163], v[60:63]
	v_mfma_f32_16x16x32_bf16 v[56:59], v[132:135], v[160:163], v[56:59]
	v_mfma_f32_16x16x32_bf16 v[44:47], v[120:123], v[168:171], v[44:47]
	v_mfma_f32_16x16x32_bf16 v[40:43], v[132:135], v[168:171], v[40:43]
	v_mfma_f32_16x16x32_bf16 v[28:31], v[120:123], v[188:191], v[28:31]
	v_mfma_f32_16x16x32_bf16 v[24:27], v[132:135], v[188:191], v[24:27]
	v_mfma_f32_16x16x32_bf16 v[12:15], v[120:123], v[196:199], v[12:15]
	v_mfma_f32_16x16x32_bf16 v[8:11], v[132:135], v[196:199], v[8:11]
	v_mfma_f32_16x16x32_bf16 v[60:63], v[124:127], v[164:167], v[60:63]
	v_mfma_f32_16x16x32_bf16 v[56:59], v[136:139], v[164:167], v[56:59]
	v_mfma_f32_16x16x32_bf16 v[44:47], v[124:127], v[172:175], v[44:47]
	v_mfma_f32_16x16x32_bf16 v[40:43], v[136:139], v[172:175], v[40:43]
	v_mfma_f32_16x16x32_bf16 v[28:31], v[124:127], v[192:195], v[28:31]
	v_mfma_f32_16x16x32_bf16 v[24:27], v[136:139], v[192:195], v[24:27]
	v_mfma_f32_16x16x32_bf16 v[12:15], v[124:127], v[214:217], v[12:15]
	v_mfma_f32_16x16x32_bf16 v[8:11], v[136:139], v[214:217], v[8:11]
	v_mfma_f32_16x16x32_bf16 v[52:55], v[144:147], v[160:163], v[52:55]
	v_mfma_f32_16x16x32_bf16 v[48:51], v[152:155], v[160:163], v[48:51]
	v_mfma_f32_16x16x32_bf16 v[36:39], v[144:147], v[168:171], v[36:39]
	v_mfma_f32_16x16x32_bf16 v[32:35], v[152:155], v[168:171], v[32:35]
	v_mfma_f32_16x16x32_bf16 v[20:23], v[144:147], v[188:191], v[20:23]
	v_mfma_f32_16x16x32_bf16 v[16:19], v[152:155], v[188:191], v[16:19]
	v_mfma_f32_16x16x32_bf16 v[4:7], v[144:147], v[196:199], v[4:7]
	v_mfma_f32_16x16x32_bf16 v[0:3], v[152:155], v[196:199], v[0:3]
	v_mfma_f32_16x16x32_bf16 v[52:55], v[148:151], v[164:167], v[52:55]
	v_mfma_f32_16x16x32_bf16 v[48:51], v[156:159], v[164:167], v[48:51]
	v_mfma_f32_16x16x32_bf16 v[36:39], v[148:151], v[172:175], v[36:39]
	v_mfma_f32_16x16x32_bf16 v[32:35], v[156:159], v[172:175], v[32:35]
	v_mfma_f32_16x16x32_bf16 v[20:23], v[148:151], v[192:195], v[20:23]
	v_mfma_f32_16x16x32_bf16 v[16:19], v[156:159], v[192:195], v[16:19]
	v_mfma_f32_16x16x32_bf16 v[4:7], v[148:151], v[214:217], v[4:7]
	v_mfma_f32_16x16x32_bf16 v[0:3], v[156:159], v[214:217], v[0:3]
	s_barrier
	s_add_i32 s60, s60, 2
	s_add_u32 s34, s34, 0x100
	s_addc_u32 s35, s35, 0
	s_add_u32 s58, s58, 0x100
	s_addc_u32 s59, s59, 0
	s_cmp_gt_u32 s60, 29
	s_cbranch_scc0 .LBB0_837
	s_and_b64 vcc, exec, s[28:29]
	s_cbranch_vccz .LBB0_840
	s_barrier
